# swiglu offset barrier moved after next-unit header+acc zeroing; LDS-DMA loads in 9 GEMM loops use saddr form (drops 64-bit VALU address adds)
# speedup vs baseline: 1.0166x; 1.0024x over previous
.LBB7_327:
	ds_read_b128 v[128:131], v177
	ds_read_b128 v[132:135], v177 offset:1024
	ds_read_b128 v[136:139], v177 offset:2048
	ds_read_b128 v[140:143], v177 offset:3072
	ds_read_b128 v[160:163], v178
	ds_read_b128 v[164:167], v178 offset:1024
	ds_read_b128 v[168:171], v178 offset:2048
	ds_read_b128 v[180:183], v178 offset:3072
	s_add_i32 s87, s40, 2
	s_add_u32 s41, s38, 0xfffc0080
	s_addc_u32 s42, s39, -1
	s_cmp_eq_u32 s57, s40
	s_cselect_b32 s40, s84, s85
	s_cselect_b32 s43, s81, s42
	s_cselect_b32 s42, s82, s41
	s_cselect_b32 s41, s83, s86
	s_add_i32 m0, s48, 0xc000
	ds_read_b128 v[184:187], v179
	ds_read_b128 v[188:191], v179 offset:1024
	ds_read_b128 v[192:195], v179 offset:2048
	ds_read_b128 v[196:199], v179 offset:3072
	ds_read_b128 v[202:205], v179 offset:4096
	ds_read_b128 v[206:209], v179 offset:5120
	ds_read_b128 v[210:213], v179 offset:6144
	ds_read_b128 v[214:217], v179 offset:7168
	global_load_lds_dwordx4 v152, s[38:39]
	s_add_i32 m0, s48, 0xe000
	s_nop 0
	global_load_lds_dwordx4 v154, s[38:39]
	s_waitcnt vmcnt(8)
	s_waitcnt lgkmcnt(0)
	s_setprio 1
	s_barrier
	v_mfma_f32_16x16x32_bf16 v[124:127], v[128:131], v[184:187], v[124:127]
	v_mfma_f32_16x16x32_bf16 v[120:123], v[136:139], v[184:187], v[120:123]
	v_mfma_f32_16x16x32_bf16 v[108:111], v[128:131], v[192:195], v[108:111]
	v_mfma_f32_16x16x32_bf16 v[104:107], v[136:139], v[192:195], v[104:107]
	v_mfma_f32_16x16x32_bf16 v[92:95], v[128:131], v[202:205], v[92:95]
	v_mfma_f32_16x16x32_bf16 v[88:91], v[136:139], v[202:205], v[88:91]
	v_mfma_f32_16x16x32_bf16 v[76:79], v[128:131], v[210:213], v[76:79]
	v_mfma_f32_16x16x32_bf16 v[72:75], v[136:139], v[210:213], v[72:75]
	v_mfma_f32_16x16x32_bf16 v[124:127], v[132:135], v[188:191], v[124:127]
	v_mfma_f32_16x16x32_bf16 v[120:123], v[140:143], v[188:191], v[120:123]
	v_mfma_f32_16x16x32_bf16 v[108:111], v[132:135], v[196:199], v[108:111]
	v_mfma_f32_16x16x32_bf16 v[104:107], v[140:143], v[196:199], v[104:107]
	v_mfma_f32_16x16x32_bf16 v[92:95], v[132:135], v[206:209], v[92:95]
	v_mfma_f32_16x16x32_bf16 v[88:91], v[140:143], v[206:209], v[88:91]
	v_mfma_f32_16x16x32_bf16 v[76:79], v[132:135], v[214:217], v[76:79]
	v_mfma_f32_16x16x32_bf16 v[72:75], v[140:143], v[214:217], v[72:75]
	v_mfma_f32_16x16x32_bf16 v[116:119], v[160:163], v[184:187], v[116:119]
	v_mfma_f32_16x16x32_bf16 v[112:115], v[168:171], v[184:187], v[112:115]
	v_mfma_f32_16x16x32_bf16 v[100:103], v[160:163], v[192:195], v[100:103]
	v_mfma_f32_16x16x32_bf16 v[96:99], v[168:171], v[192:195], v[96:99]
	v_mfma_f32_16x16x32_bf16 v[84:87], v[160:163], v[202:205], v[84:87]
	v_mfma_f32_16x16x32_bf16 v[80:83], v[168:171], v[202:205], v[80:83]
	v_mfma_f32_16x16x32_bf16 v[68:71], v[160:163], v[210:213], v[68:71]
	v_mfma_f32_16x16x32_bf16 v[64:67], v[168:171], v[210:213], v[64:67]
	v_mfma_f32_16x16x32_bf16 v[116:119], v[164:167], v[188:191], v[116:119]
	v_mfma_f32_16x16x32_bf16 v[112:115], v[180:183], v[188:191], v[112:115]
	v_mfma_f32_16x16x32_bf16 v[100:103], v[164:167], v[196:199], v[100:103]
	v_mfma_f32_16x16x32_bf16 v[96:99], v[180:183], v[196:199], v[96:99]
	v_mfma_f32_16x16x32_bf16 v[84:87], v[164:167], v[206:209], v[84:87]
	v_mfma_f32_16x16x32_bf16 v[80:83], v[180:183], v[206:209], v[80:83]
	v_mfma_f32_16x16x32_bf16 v[68:71], v[164:167], v[214:217], v[68:71]
	v_mfma_f32_16x16x32_bf16 v[64:67], v[180:183], v[214:217], v[64:67]
	s_barrier
	s_setprio 0
	s_add_i32 s88, s58, s33
	v_lshl_add_u64 v[172:173], s[40:41], 0, v[148:149]
	s_mov_b32 m0, s88
	ds_read_b128 v[184:187], v179 offset:16384
	ds_read_b128 v[188:191], v179 offset:17408
	ds_read_b128 v[192:195], v179 offset:18432
	ds_read_b128 v[196:199], v179 offset:19456
	ds_read_b128 v[202:205], v179 offset:20480
	ds_read_b128 v[206:209], v179 offset:21504
	ds_read_b128 v[210:213], v179 offset:22528
	ds_read_b128 v[214:217], v179 offset:23552
	global_load_lds_dwordx4 v[172:173], off
	s_add_i32 m0, s88, 0x2000
	s_add_u32 s88, s40, 0x40000
	v_lshl_add_u64 v[218:219], s[40:41], 0, v[144:145]
	s_addc_u32 s89, s41, 0
	s_add_i32 s90, s64, s33
	global_load_lds_dwordx4 v[218:219], off
	s_mov_b32 m0, s90
	v_lshl_add_u64 v[222:223], s[42:43], 0, v[146:147]
	global_load_lds_dwordx4 v148, s[88:89]
	s_add_i32 m0, s90, 0x2000
	s_nop 0
	global_load_lds_dwordx4 v144, s[88:89]
	v_lshl_add_u64 v[220:221], s[42:43], 0, v[150:151]
	s_mov_b32 m0, s48
	s_nop 0
	global_load_lds_dwordx4 v[220:221], off
	s_mov_b32 m0, s49
	s_nop 0
	global_load_lds_dwordx4 v[222:223], off
	s_waitcnt vmcnt(8)
	s_waitcnt lgkmcnt(0)
	s_setprio 1
	s_barrier
	v_mfma_f32_16x16x32_bf16 v[60:63], v[128:131], v[184:187], v[60:63]
	v_mfma_f32_16x16x32_bf16 v[56:59], v[136:139], v[184:187], v[56:59]
	v_mfma_f32_16x16x32_bf16 v[44:47], v[128:131], v[192:195], v[44:47]
	v_mfma_f32_16x16x32_bf16 v[40:43], v[136:139], v[192:195], v[40:43]
	v_mfma_f32_16x16x32_bf16 v[28:31], v[128:131], v[202:205], v[28:31]
	v_mfma_f32_16x16x32_bf16 v[24:27], v[136:139], v[202:205], v[24:27]
	v_mfma_f32_16x16x32_bf16 v[12:15], v[128:131], v[210:213], v[12:15]
	v_mfma_f32_16x16x32_bf16 v[8:11], v[136:139], v[210:213], v[8:11]
	v_mfma_f32_16x16x32_bf16 v[60:63], v[132:135], v[188:191], v[60:63]
	v_mfma_f32_16x16x32_bf16 v[56:59], v[140:143], v[188:191], v[56:59]
	v_mfma_f32_16x16x32_bf16 v[44:47], v[132:135], v[196:199], v[44:47]
	v_mfma_f32_16x16x32_bf16 v[40:43], v[140:143], v[196:199], v[40:43]
	v_mfma_f32_16x16x32_bf16 v[28:31], v[132:135], v[206:209], v[28:31]
	v_mfma_f32_16x16x32_bf16 v[24:27], v[140:143], v[206:209], v[24:27]
	v_mfma_f32_16x16x32_bf16 v[12:15], v[132:135], v[214:217], v[12:15]
	v_mfma_f32_16x16x32_bf16 v[8:11], v[140:143], v[214:217], v[8:11]
	v_mfma_f32_16x16x32_bf16 v[52:55], v[160:163], v[184:187], v[52:55]
	v_mfma_f32_16x16x32_bf16 v[48:51], v[168:171], v[184:187], v[48:51]
	v_mfma_f32_16x16x32_bf16 v[36:39], v[160:163], v[192:195], v[36:39]
	v_mfma_f32_16x16x32_bf16 v[32:35], v[168:171], v[192:195], v[32:35]
	v_mfma_f32_16x16x32_bf16 v[20:23], v[160:163], v[202:205], v[20:23]
	v_mfma_f32_16x16x32_bf16 v[16:19], v[168:171], v[202:205], v[16:19]
	v_mfma_f32_16x16x32_bf16 v[4:7], v[160:163], v[210:213], v[4:7]
	v_mfma_f32_16x16x32_bf16 v[0:3], v[168:171], v[210:213], v[0:3]
	v_mfma_f32_16x16x32_bf16 v[52:55], v[164:167], v[188:191], v[52:55]
	v_mfma_f32_16x16x32_bf16 v[48:51], v[180:183], v[188:191], v[48:51]
	v_mfma_f32_16x16x32_bf16 v[36:39], v[164:167], v[196:199], v[36:39]
	v_mfma_f32_16x16x32_bf16 v[32:35], v[180:183], v[196:199], v[32:35]
	v_mfma_f32_16x16x32_bf16 v[20:23], v[164:167], v[206:209], v[20:23]
	v_mfma_f32_16x16x32_bf16 v[16:19], v[180:183], v[206:209], v[16:19]
	v_mfma_f32_16x16x32_bf16 v[4:7], v[164:167], v[214:217], v[4:7]
	v_mfma_f32_16x16x32_bf16 v[0:3], v[180:183], v[214:217], v[0:3]
	s_barrier
	s_setprio 0
	s_add_i32 s88, 0, 0x18000
	s_add_i32 s89, 0, 0x1c000
	v_add_u32_e32 v140, s88, v175
	v_add_u32_e32 v180, s89, v175
	ds_read_b128 v[128:131], v140
	ds_read_b128 v[132:135], v140 offset:1024
	ds_read_b128 v[136:139], v140 offset:2048
	ds_read_b128 v[140:143], v140 offset:3072
	ds_read_b128 v[160:163], v180
	ds_read_b128 v[164:167], v180 offset:1024
	ds_read_b128 v[168:171], v180 offset:2048
	ds_read_b128 v[180:183], v180 offset:3072
	s_add_u32 s42, s42, 0x40000
	s_addc_u32 s43, s43, 0
	s_mov_b32 m0, s50
	ds_read_b128 v[184:187], v179 offset:32768
	ds_read_b128 v[188:191], v179 offset:33792
	ds_read_b128 v[192:195], v179 offset:34816
	ds_read_b128 v[196:199], v179 offset:35840
	ds_read_b128 v[202:205], v179 offset:36864
	ds_read_b128 v[206:209], v179 offset:37888
	ds_read_b128 v[210:213], v179 offset:38912
	ds_read_b128 v[214:217], v179 offset:39936
	global_load_lds_dwordx4 v150, s[42:43]
	s_mov_b32 m0, s51
	s_nop 0
	global_load_lds_dwordx4 v146, s[42:43]
	s_waitcnt vmcnt(8)
	s_waitcnt lgkmcnt(0)
	s_setprio 1
	s_barrier
	v_mfma_f32_16x16x32_bf16 v[124:127], v[128:131], v[184:187], v[124:127]
	v_mfma_f32_16x16x32_bf16 v[120:123], v[136:139], v[184:187], v[120:123]
	v_mfma_f32_16x16x32_bf16 v[108:111], v[128:131], v[192:195], v[108:111]
	v_mfma_f32_16x16x32_bf16 v[104:107], v[136:139], v[192:195], v[104:107]
	v_mfma_f32_16x16x32_bf16 v[92:95], v[128:131], v[202:205], v[92:95]
	v_mfma_f32_16x16x32_bf16 v[88:91], v[136:139], v[202:205], v[88:91]
	v_mfma_f32_16x16x32_bf16 v[76:79], v[128:131], v[210:213], v[76:79]
	v_mfma_f32_16x16x32_bf16 v[72:75], v[136:139], v[210:213], v[72:75]
	v_mfma_f32_16x16x32_bf16 v[124:127], v[132:135], v[188:191], v[124:127]
	v_mfma_f32_16x16x32_bf16 v[120:123], v[140:143], v[188:191], v[120:123]
	v_mfma_f32_16x16x32_bf16 v[108:111], v[132:135], v[196:199], v[108:111]
	v_mfma_f32_16x16x32_bf16 v[104:107], v[140:143], v[196:199], v[104:107]
	v_mfma_f32_16x16x32_bf16 v[92:95], v[132:135], v[206:209], v[92:95]
	v_mfma_f32_16x16x32_bf16 v[88:91], v[140:143], v[206:209], v[88:91]
	v_mfma_f32_16x16x32_bf16 v[76:79], v[132:135], v[214:217], v[76:79]
	v_mfma_f32_16x16x32_bf16 v[72:75], v[140:143], v[214:217], v[72:75]
	v_mfma_f32_16x16x32_bf16 v[116:119], v[160:163], v[184:187], v[116:119]
	v_mfma_f32_16x16x32_bf16 v[112:115], v[168:171], v[184:187], v[112:115]
	v_mfma_f32_16x16x32_bf16 v[100:103], v[160:163], v[192:195], v[100:103]
	v_mfma_f32_16x16x32_bf16 v[96:99], v[168:171], v[192:195], v[96:99]
	v_mfma_f32_16x16x32_bf16 v[84:87], v[160:163], v[202:205], v[84:87]
	v_mfma_f32_16x16x32_bf16 v[80:83], v[168:171], v[202:205], v[80:83]
	v_mfma_f32_16x16x32_bf16 v[68:71], v[160:163], v[210:213], v[68:71]
	v_mfma_f32_16x16x32_bf16 v[64:67], v[168:171], v[210:213], v[64:67]
	v_mfma_f32_16x16x32_bf16 v[116:119], v[164:167], v[188:191], v[116:119]
	v_mfma_f32_16x16x32_bf16 v[112:115], v[180:183], v[188:191], v[112:115]
	v_mfma_f32_16x16x32_bf16 v[100:103], v[164:167], v[196:199], v[100:103]
	v_mfma_f32_16x16x32_bf16 v[96:99], v[180:183], v[196:199], v[96:99]
	v_mfma_f32_16x16x32_bf16 v[84:87], v[164:167], v[206:209], v[84:87]
	v_mfma_f32_16x16x32_bf16 v[80:83], v[180:183], v[206:209], v[80:83]
	v_mfma_f32_16x16x32_bf16 v[68:71], v[164:167], v[214:217], v[68:71]
	v_mfma_f32_16x16x32_bf16 v[64:67], v[180:183], v[214:217], v[64:67]
	s_barrier
	s_setprio 0
	s_add_i32 s42, s88, s33
	v_lshl_add_u64 v[172:173], v[172:173], 0, s[10:11]
	s_mov_b32 m0, s42
	ds_read_b128 v[184:187], v179 offset:49152
	ds_read_b128 v[188:191], v179 offset:50176
	ds_read_b128 v[192:195], v179 offset:51200
	ds_read_b128 v[196:199], v179 offset:52224
	ds_read_b128 v[202:205], v179 offset:53248
	ds_read_b128 v[206:209], v179 offset:54272
	ds_read_b128 v[210:213], v179 offset:55296
	ds_read_b128 v[214:217], v179 offset:56320
	global_load_lds_dwordx4 v[172:173], off
	s_add_i32 m0, s42, 0x2000
	s_add_u32 s40, s40, 0x40080
	v_lshl_add_u64 v[172:173], v[218:219], 0, s[10:11]
	s_addc_u32 s41, s41, 0
	s_add_i32 s42, s89, s33
	global_load_lds_dwordx4 v[172:173], off
	s_mov_b32 m0, s42
	s_nop 0
	global_load_lds_dwordx4 v148, s[40:41]
	s_add_i32 m0, s42, 0x2000
	s_nop 0
	global_load_lds_dwordx4 v144, s[40:41]
	v_lshl_add_u64 v[172:173], v[220:221], 0, s[10:11]
	s_mov_b32 m0, s55
	s_nop 0
	global_load_lds_dwordx4 v[172:173], off
	v_lshl_add_u64 v[172:173], v[222:223], 0, s[10:11]
	s_mov_b32 m0, s56
	s_nop 0
	global_load_lds_dwordx4 v[172:173], off
	s_waitcnt vmcnt(8)
	s_waitcnt lgkmcnt(0)
	s_setprio 1
	s_barrier
	v_mfma_f32_16x16x32_bf16 v[60:63], v[128:131], v[184:187], v[60:63]
	v_mfma_f32_16x16x32_bf16 v[56:59], v[136:139], v[184:187], v[56:59]
	v_mfma_f32_16x16x32_bf16 v[44:47], v[128:131], v[192:195], v[44:47]
	v_mfma_f32_16x16x32_bf16 v[40:43], v[136:139], v[192:195], v[40:43]
	v_mfma_f32_16x16x32_bf16 v[28:31], v[128:131], v[202:205], v[28:31]
	v_mfma_f32_16x16x32_bf16 v[24:27], v[136:139], v[202:205], v[24:27]
	v_mfma_f32_16x16x32_bf16 v[12:15], v[128:131], v[210:213], v[12:15]
	v_mfma_f32_16x16x32_bf16 v[8:11], v[136:139], v[210:213], v[8:11]
	v_mfma_f32_16x16x32_bf16 v[60:63], v[132:135], v[188:191], v[60:63]
	v_mfma_f32_16x16x32_bf16 v[56:59], v[140:143], v[188:191], v[56:59]
	v_mfma_f32_16x16x32_bf16 v[44:47], v[132:135], v[196:199], v[44:47]
	v_mfma_f32_16x16x32_bf16 v[40:43], v[140:143], v[196:199], v[40:43]
	v_mfma_f32_16x16x32_bf16 v[28:31], v[132:135], v[206:209], v[28:31]
	v_mfma_f32_16x16x32_bf16 v[24:27], v[140:143], v[206:209], v[24:27]
	v_mfma_f32_16x16x32_bf16 v[12:15], v[132:135], v[214:217], v[12:15]
	v_mfma_f32_16x16x32_bf16 v[8:11], v[140:143], v[214:217], v[8:11]
	v_mfma_f32_16x16x32_bf16 v[52:55], v[160:163], v[184:187], v[52:55]
	v_mfma_f32_16x16x32_bf16 v[48:51], v[168:171], v[184:187], v[48:51]
	v_mfma_f32_16x16x32_bf16 v[36:39], v[160:163], v[192:195], v[36:39]
	v_mfma_f32_16x16x32_bf16 v[32:35], v[168:171], v[192:195], v[32:35]
	v_mfma_f32_16x16x32_bf16 v[20:23], v[160:163], v[202:205], v[20:23]
	v_mfma_f32_16x16x32_bf16 v[16:19], v[168:171], v[202:205], v[16:19]
	v_mfma_f32_16x16x32_bf16 v[4:7], v[160:163], v[210:213], v[4:7]
	v_mfma_f32_16x16x32_bf16 v[0:3], v[168:171], v[210:213], v[0:3]
	v_mfma_f32_16x16x32_bf16 v[52:55], v[164:167], v[188:191], v[52:55]
	v_mfma_f32_16x16x32_bf16 v[48:51], v[180:183], v[188:191], v[48:51]
	v_mfma_f32_16x16x32_bf16 v[36:39], v[164:167], v[196:199], v[36:39]
	v_mfma_f32_16x16x32_bf16 v[32:35], v[180:183], v[196:199], v[32:35]
	v_mfma_f32_16x16x32_bf16 v[20:23], v[164:167], v[206:209], v[20:23]
	v_mfma_f32_16x16x32_bf16 v[16:19], v[180:183], v[206:209], v[16:19]
	v_mfma_f32_16x16x32_bf16 v[4:7], v[164:167], v[214:217], v[4:7]
	v_mfma_f32_16x16x32_bf16 v[0:3], v[180:183], v[214:217], v[0:3]
	s_barrier
	s_setprio 0
	s_add_u32 s38, s38, 0x100
	s_addc_u32 s39, s39, 0
	s_add_u32 s85, s85, 0x100
	s_addc_u32 s86, s86, 0
	s_cmp_ge_i32 s87, s26
	s_mov_b32 s40, s87
	s_cbranch_scc0 .LBB7_327
	v_readlane_b32 s87, v251, 12
	v_readlane_b32 s89, v251, 13
	s_and_b64 vcc, exec, s[12:13]
	s_cbranch_vccz .LBB7_330

.LBB7_355:
	s_add_u32 s0, s68, s14
	s_addc_u32 s1, s69, s15
	s_add_u32 s6, s85, s18
	s_addc_u32 s7, s31, s19
	s_andn2_b64 vcc, exec, s[54:55]
	s_cbranch_vccnz .LBB7_363
	s_and_b64 s[28:29], s[40:41], exec
	s_cselect_b32 s9, s1, s17
	s_cselect_b32 s13, s0, s16
	s_cselect_b32 s28, s7, s43
	s_cselect_b32 s39, s6, s42
	s_add_u32 s16, s16, 0x40080
	s_addc_u32 s17, s17, 0
	s_add_u32 s56, s42, 0x100
	v_mov_b32_e32 v2, 0
	s_addc_u32 s57, s43, 0
	s_mov_b32 s42, 0
	v_mov_b32_e32 v3, v2
	v_mov_b32_e32 v4, v2
	v_mov_b32_e32 v5, v2
	v_mov_b32_e32 v10, v2
	v_mov_b32_e32 v11, v2
	v_mov_b32_e32 v12, v2
	v_mov_b32_e32 v13, v2
	v_mov_b32_e32 v18, v2
	v_mov_b32_e32 v19, v2
	v_mov_b32_e32 v20, v2
	v_mov_b32_e32 v21, v2
	v_mov_b32_e32 v26, v2
	v_mov_b32_e32 v27, v2
	v_mov_b32_e32 v28, v2
	v_mov_b32_e32 v29, v2
	v_mov_b32_e32 v34, v2
	v_mov_b32_e32 v35, v2
	v_mov_b32_e32 v36, v2
	v_mov_b32_e32 v37, v2
	v_mov_b32_e32 v42, v2
	v_mov_b32_e32 v43, v2
	v_mov_b32_e32 v44, v2
	v_mov_b32_e32 v45, v2
	v_mov_b32_e32 v50, v2
	v_mov_b32_e32 v51, v2
	v_mov_b32_e32 v52, v2
	v_mov_b32_e32 v53, v2
	v_mov_b32_e32 v58, v2
	v_mov_b32_e32 v59, v2
	v_mov_b32_e32 v60, v2
	v_mov_b32_e32 v61, v2
	v_mov_b32_e32 v6, v2
	v_mov_b32_e32 v7, v2
	v_mov_b32_e32 v8, v2
	v_mov_b32_e32 v9, v2
	v_mov_b32_e32 v14, v2
	v_mov_b32_e32 v15, v2
	v_mov_b32_e32 v16, v2
	v_mov_b32_e32 v17, v2
	v_mov_b32_e32 v22, v2
	v_mov_b32_e32 v23, v2
	v_mov_b32_e32 v24, v2
	v_mov_b32_e32 v25, v2
	v_mov_b32_e32 v30, v2
	v_mov_b32_e32 v31, v2
	v_mov_b32_e32 v32, v2
	v_mov_b32_e32 v33, v2
	v_mov_b32_e32 v38, v2
	v_mov_b32_e32 v39, v2
	v_mov_b32_e32 v40, v2
	v_mov_b32_e32 v41, v2
	v_mov_b32_e32 v46, v2
	v_mov_b32_e32 v47, v2
	v_mov_b32_e32 v48, v2
	v_mov_b32_e32 v49, v2
	v_mov_b32_e32 v54, v2
	v_mov_b32_e32 v55, v2
	v_mov_b32_e32 v56, v2
	v_mov_b32_e32 v57, v2
	v_mov_b32_e32 v62, v2
	v_mov_b32_e32 v63, v2
	v_mov_b32_e32 v64, v2
	v_mov_b32_e32 v65, v2
	v_mov_b32_e32 v66, v2
	v_mov_b32_e32 v67, v2
	v_mov_b32_e32 v68, v2
	v_mov_b32_e32 v69, v2
	v_mov_b32_e32 v74, v2
	v_mov_b32_e32 v75, v2
	v_mov_b32_e32 v76, v2
	v_mov_b32_e32 v77, v2
	v_mov_b32_e32 v82, v2
	v_mov_b32_e32 v83, v2
	v_mov_b32_e32 v84, v2
	v_mov_b32_e32 v85, v2
	v_mov_b32_e32 v90, v2
	v_mov_b32_e32 v91, v2
	v_mov_b32_e32 v92, v2
	v_mov_b32_e32 v93, v2
	v_mov_b32_e32 v98, v2
	v_mov_b32_e32 v99, v2
	v_mov_b32_e32 v100, v2
	v_mov_b32_e32 v101, v2
	v_mov_b32_e32 v106, v2
	v_mov_b32_e32 v107, v2
	v_mov_b32_e32 v108, v2
	v_mov_b32_e32 v109, v2
	v_mov_b32_e32 v114, v2
	v_mov_b32_e32 v115, v2
	v_mov_b32_e32 v116, v2
	v_mov_b32_e32 v117, v2
	v_mov_b32_e32 v122, v2
	v_mov_b32_e32 v123, v2
	v_mov_b32_e32 v124, v2
	v_mov_b32_e32 v125, v2
	v_mov_b32_e32 v70, v2
	v_mov_b32_e32 v71, v2
	v_mov_b32_e32 v72, v2
	v_mov_b32_e32 v73, v2
	v_mov_b32_e32 v78, v2
	v_mov_b32_e32 v79, v2
	v_mov_b32_e32 v80, v2
	v_mov_b32_e32 v81, v2
	v_mov_b32_e32 v86, v2
	v_mov_b32_e32 v87, v2
	v_mov_b32_e32 v88, v2
	v_mov_b32_e32 v89, v2
	v_mov_b32_e32 v94, v2
	v_mov_b32_e32 v95, v2
	v_mov_b32_e32 v96, v2
	v_mov_b32_e32 v97, v2
	v_mov_b32_e32 v102, v2
	v_mov_b32_e32 v103, v2
	v_mov_b32_e32 v104, v2
	v_mov_b32_e32 v105, v2
	v_mov_b32_e32 v110, v2
	v_mov_b32_e32 v111, v2
	v_mov_b32_e32 v112, v2
	v_mov_b32_e32 v113, v2
	v_mov_b32_e32 v118, v2
	v_mov_b32_e32 v119, v2
	v_mov_b32_e32 v120, v2
	v_mov_b32_e32 v121, v2
	v_mov_b32_e32 v126, v2
	v_mov_b32_e32 v127, v2
	v_mov_b32_e32 v128, v2
	v_mov_b32_e32 v129, v2
	s_cmp_lt_u32 s22, 2
	s_cbranch_scc1 .Lswi_nobar
	s_andn2_b64 vcc, exec, s[50:51]
	s_cbranch_vccnz .Lswi_nobar
	s_barrier
.Lswi_nobar:
.LBB7_357:
	s_add_i32 s86, s42, 2
	s_add_u32 s29, s16, 0xfffc0080
	s_addc_u32 s37, s17, -1
	s_add_i32 s74, 0, 0x10000
	s_cmp_eq_u32 s20, s42
	s_cselect_b32 s73, s9, s37
	s_cselect_b32 s72, s13, s29
	v_add_u32_e32 v170, s74, v179
	s_cselect_b32 s43, s28, s57
	s_cselect_b32 s42, s39, s56
	s_add_i32 s29, 0, 0x14000
	ds_read_b128 v[130:133], v170
	ds_read_b128 v[180:183], v170 offset:1024
	ds_read_b128 v[184:187], v170 offset:2048
	ds_read_b128 v[188:191], v170 offset:3072
	v_add_u32_e32 v170, s29, v179
	ds_read_b128 v[192:195], v170
	ds_read_b128 v[196:199], v170 offset:1024
	ds_read_b128 v[204:207], v170 offset:2048
	ds_read_b128 v[208:211], v170 offset:3072
	s_add_i32 m0, s4, 0xc000
	ds_read_b128 v[212:215], v143
	ds_read_b128 v[216:219], v143 offset:1024
	ds_read_b128 v[220:223], v143 offset:2048
	ds_read_b128 v[224:227], v143 offset:3072
	ds_read_b128 v[228:231], v143 offset:4096
	ds_read_b128 v[232:235], v143 offset:5120
	ds_read_b128 v[236:239], v143 offset:6144
	ds_read_b128 v[240:243], v143 offset:7168
	global_load_lds_dwordx4 v174, s[16:17]
	s_add_i32 m0, s4, 0xe000
	s_nop 0
	global_load_lds_dwordx4 v176, s[16:17]
	s_waitcnt vmcnt(8)
	s_waitcnt lgkmcnt(0)
	s_setprio 1
	s_barrier
	v_mfma_f32_16x16x32_bf16 v[126:129], v[130:133], v[212:215], v[126:129]
	v_mfma_f32_16x16x32_bf16 v[118:121], v[184:187], v[212:215], v[118:121]
	v_mfma_f32_16x16x32_bf16 v[110:113], v[130:133], v[220:223], v[110:113]
	v_mfma_f32_16x16x32_bf16 v[102:105], v[184:187], v[220:223], v[102:105]
	v_mfma_f32_16x16x32_bf16 v[94:97], v[130:133], v[228:231], v[94:97]
	v_mfma_f32_16x16x32_bf16 v[86:89], v[184:187], v[228:231], v[86:89]
	v_mfma_f32_16x16x32_bf16 v[78:81], v[130:133], v[236:239], v[78:81]
	v_mfma_f32_16x16x32_bf16 v[70:73], v[184:187], v[236:239], v[70:73]
	v_mfma_f32_16x16x32_bf16 v[126:129], v[180:183], v[216:219], v[126:129]
	v_mfma_f32_16x16x32_bf16 v[118:121], v[188:191], v[216:219], v[118:121]
	v_mfma_f32_16x16x32_bf16 v[110:113], v[180:183], v[224:227], v[110:113]
	v_mfma_f32_16x16x32_bf16 v[102:105], v[188:191], v[224:227], v[102:105]
	v_mfma_f32_16x16x32_bf16 v[94:97], v[180:183], v[232:235], v[94:97]
	v_mfma_f32_16x16x32_bf16 v[86:89], v[188:191], v[232:235], v[86:89]
	v_mfma_f32_16x16x32_bf16 v[78:81], v[180:183], v[240:243], v[78:81]
	v_mfma_f32_16x16x32_bf16 v[70:73], v[188:191], v[240:243], v[70:73]
	v_mfma_f32_16x16x32_bf16 v[122:125], v[192:195], v[212:215], v[122:125]
	v_mfma_f32_16x16x32_bf16 v[114:117], v[204:207], v[212:215], v[114:117]
	v_mfma_f32_16x16x32_bf16 v[106:109], v[192:195], v[220:223], v[106:109]
	v_mfma_f32_16x16x32_bf16 v[98:101], v[204:207], v[220:223], v[98:101]
	v_mfma_f32_16x16x32_bf16 v[90:93], v[192:195], v[228:231], v[90:93]
	v_mfma_f32_16x16x32_bf16 v[82:85], v[204:207], v[228:231], v[82:85]
	v_mfma_f32_16x16x32_bf16 v[74:77], v[192:195], v[236:239], v[74:77]
	v_mfma_f32_16x16x32_bf16 v[66:69], v[204:207], v[236:239], v[66:69]
	v_mfma_f32_16x16x32_bf16 v[122:125], v[196:199], v[216:219], v[122:125]
	v_mfma_f32_16x16x32_bf16 v[114:117], v[208:211], v[216:219], v[114:117]
	v_mfma_f32_16x16x32_bf16 v[106:109], v[196:199], v[224:227], v[106:109]
	v_mfma_f32_16x16x32_bf16 v[98:101], v[208:211], v[224:227], v[98:101]
	v_mfma_f32_16x16x32_bf16 v[90:93], v[196:199], v[232:235], v[90:93]
	v_mfma_f32_16x16x32_bf16 v[82:85], v[208:211], v[232:235], v[82:85]
	v_mfma_f32_16x16x32_bf16 v[74:77], v[196:199], v[240:243], v[74:77]
	v_mfma_f32_16x16x32_bf16 v[66:69], v[208:211], v[240:243], v[66:69]
	s_barrier
	s_setprio 0
	s_add_i32 s37, s74, s84
	v_lshl_add_u64 v[244:245], s[42:43], 0, v[138:139]
	s_mov_b32 m0, s37
	ds_read_b128 v[212:215], v143 offset:16384
	ds_read_b128 v[216:219], v143 offset:17408
	ds_read_b128 v[220:223], v143 offset:18432
	ds_read_b128 v[224:227], v143 offset:19456
	ds_read_b128 v[228:231], v143 offset:20480
	ds_read_b128 v[232:235], v143 offset:21504
	ds_read_b128 v[236:239], v143 offset:22528
	ds_read_b128 v[240:243], v143 offset:23552
	global_load_lds_dwordx4 v[244:245], off
	s_add_i32 m0, s37, 0x2000
	s_add_u32 s74, s42, 0x40000
	v_lshl_add_u64 v[246:247], s[42:43], 0, v[134:135]
	s_addc_u32 s75, s43, 0
	s_add_i32 s29, s29, s84
	global_load_lds_dwordx4 v[246:247], off
	s_mov_b32 m0, s29
	v_lshl_add_u64 v[170:171], s[72:73], 0, v[136:137]
	global_load_lds_dwordx4 v138, s[74:75]
	s_add_i32 m0, s29, 0x2000
	s_nop 0
	global_load_lds_dwordx4 v134, s[74:75]
	v_lshl_add_u64 v[248:249], s[72:73], 0, v[140:141]
	s_mov_b32 m0, s4
	s_nop 0
	global_load_lds_dwordx4 v[248:249], off
	s_mov_b32 m0, s5
	s_nop 0
	global_load_lds_dwordx4 v[170:171], off
	s_waitcnt vmcnt(8)
	s_waitcnt lgkmcnt(0)
	s_setprio 1
	s_barrier
	v_mfma_f32_16x16x32_bf16 v[62:65], v[130:133], v[212:215], v[62:65]
	v_mfma_f32_16x16x32_bf16 v[54:57], v[184:187], v[212:215], v[54:57]
	v_mfma_f32_16x16x32_bf16 v[46:49], v[130:133], v[220:223], v[46:49]
	v_mfma_f32_16x16x32_bf16 v[38:41], v[184:187], v[220:223], v[38:41]
	v_mfma_f32_16x16x32_bf16 v[30:33], v[130:133], v[228:231], v[30:33]
	v_mfma_f32_16x16x32_bf16 v[22:25], v[184:187], v[228:231], v[22:25]
	v_mfma_f32_16x16x32_bf16 v[14:17], v[130:133], v[236:239], v[14:17]
	v_mfma_f32_16x16x32_bf16 v[6:9], v[184:187], v[236:239], v[6:9]
	v_mfma_f32_16x16x32_bf16 v[62:65], v[180:183], v[216:219], v[62:65]
	v_mfma_f32_16x16x32_bf16 v[54:57], v[188:191], v[216:219], v[54:57]
	v_mfma_f32_16x16x32_bf16 v[46:49], v[180:183], v[224:227], v[46:49]
	v_mfma_f32_16x16x32_bf16 v[38:41], v[188:191], v[224:227], v[38:41]
	v_mfma_f32_16x16x32_bf16 v[30:33], v[180:183], v[232:235], v[30:33]
	v_mfma_f32_16x16x32_bf16 v[22:25], v[188:191], v[232:235], v[22:25]
	v_mfma_f32_16x16x32_bf16 v[14:17], v[180:183], v[240:243], v[14:17]
	v_mfma_f32_16x16x32_bf16 v[6:9], v[188:191], v[240:243], v[6:9]
	v_mfma_f32_16x16x32_bf16 v[58:61], v[192:195], v[212:215], v[58:61]
	v_mfma_f32_16x16x32_bf16 v[50:53], v[204:207], v[212:215], v[50:53]
	v_mfma_f32_16x16x32_bf16 v[42:45], v[192:195], v[220:223], v[42:45]
	v_mfma_f32_16x16x32_bf16 v[34:37], v[204:207], v[220:223], v[34:37]
	v_mfma_f32_16x16x32_bf16 v[26:29], v[192:195], v[228:231], v[26:29]
	v_mfma_f32_16x16x32_bf16 v[18:21], v[204:207], v[228:231], v[18:21]
	v_mfma_f32_16x16x32_bf16 v[10:13], v[192:195], v[236:239], v[10:13]
	v_mfma_f32_16x16x32_bf16 v[2:5], v[204:207], v[236:239], v[2:5]
	v_mfma_f32_16x16x32_bf16 v[58:61], v[196:199], v[216:219], v[58:61]
	v_mfma_f32_16x16x32_bf16 v[50:53], v[208:211], v[216:219], v[50:53]
	v_mfma_f32_16x16x32_bf16 v[42:45], v[196:199], v[224:227], v[42:45]
	v_mfma_f32_16x16x32_bf16 v[34:37], v[208:211], v[224:227], v[34:37]
	v_mfma_f32_16x16x32_bf16 v[26:29], v[196:199], v[232:235], v[26:29]
	v_mfma_f32_16x16x32_bf16 v[18:21], v[208:211], v[232:235], v[18:21]
	v_mfma_f32_16x16x32_bf16 v[10:13], v[196:199], v[240:243], v[10:13]
	v_mfma_f32_16x16x32_bf16 v[2:5], v[208:211], v[240:243], v[2:5]
	s_barrier
	s_setprio 0
	s_add_i32 s29, 0, 0x18000
	v_add_u32_e32 v172, s29, v179
	s_add_i32 s37, 0, 0x1c000
	ds_read_b128 v[130:133], v172
	ds_read_b128 v[180:183], v172 offset:1024
	ds_read_b128 v[184:187], v172 offset:2048
	ds_read_b128 v[188:191], v172 offset:3072
	v_add_u32_e32 v172, s37, v179
	ds_read_b128 v[192:195], v172
	ds_read_b128 v[196:199], v172 offset:1024
	ds_read_b128 v[204:207], v172 offset:2048
	ds_read_b128 v[208:211], v172 offset:3072
	s_add_u32 s72, s72, 0x40000
	s_addc_u32 s73, s73, 0
	s_mov_b32 m0, s93
	ds_read_b128 v[212:215], v143 offset:32768
	ds_read_b128 v[216:219], v143 offset:33792
	ds_read_b128 v[220:223], v143 offset:34816
	ds_read_b128 v[224:227], v143 offset:35840
	ds_read_b128 v[228:231], v143 offset:36864
	ds_read_b128 v[232:235], v143 offset:37888
	ds_read_b128 v[236:239], v143 offset:38912
	ds_read_b128 v[240:243], v143 offset:39936
	global_load_lds_dwordx4 v140, s[72:73]
	s_mov_b32 m0, s33
	s_nop 0
	global_load_lds_dwordx4 v136, s[72:73]
	s_waitcnt vmcnt(8)
	s_waitcnt lgkmcnt(0)
	s_setprio 1
	s_barrier
	v_mfma_f32_16x16x32_bf16 v[126:129], v[130:133], v[212:215], v[126:129]
	v_mfma_f32_16x16x32_bf16 v[118:121], v[184:187], v[212:215], v[118:121]
	v_mfma_f32_16x16x32_bf16 v[110:113], v[130:133], v[220:223], v[110:113]
	v_mfma_f32_16x16x32_bf16 v[102:105], v[184:187], v[220:223], v[102:105]
	v_mfma_f32_16x16x32_bf16 v[94:97], v[130:133], v[228:231], v[94:97]
	v_mfma_f32_16x16x32_bf16 v[86:89], v[184:187], v[228:231], v[86:89]
	v_mfma_f32_16x16x32_bf16 v[78:81], v[130:133], v[236:239], v[78:81]
	v_mfma_f32_16x16x32_bf16 v[70:73], v[184:187], v[236:239], v[70:73]
	v_mfma_f32_16x16x32_bf16 v[126:129], v[180:183], v[216:219], v[126:129]
	v_mfma_f32_16x16x32_bf16 v[118:121], v[188:191], v[216:219], v[118:121]
	v_mfma_f32_16x16x32_bf16 v[110:113], v[180:183], v[224:227], v[110:113]
	v_mfma_f32_16x16x32_bf16 v[102:105], v[188:191], v[224:227], v[102:105]
	v_mfma_f32_16x16x32_bf16 v[94:97], v[180:183], v[232:235], v[94:97]
	v_mfma_f32_16x16x32_bf16 v[86:89], v[188:191], v[232:235], v[86:89]
	v_mfma_f32_16x16x32_bf16 v[78:81], v[180:183], v[240:243], v[78:81]
	v_mfma_f32_16x16x32_bf16 v[70:73], v[188:191], v[240:243], v[70:73]
	v_mfma_f32_16x16x32_bf16 v[122:125], v[192:195], v[212:215], v[122:125]
	v_mfma_f32_16x16x32_bf16 v[114:117], v[204:207], v[212:215], v[114:117]
	v_mfma_f32_16x16x32_bf16 v[106:109], v[192:195], v[220:223], v[106:109]
	v_mfma_f32_16x16x32_bf16 v[98:101], v[204:207], v[220:223], v[98:101]
	v_mfma_f32_16x16x32_bf16 v[90:93], v[192:195], v[228:231], v[90:93]
	v_mfma_f32_16x16x32_bf16 v[82:85], v[204:207], v[228:231], v[82:85]
	v_mfma_f32_16x16x32_bf16 v[74:77], v[192:195], v[236:239], v[74:77]
	v_mfma_f32_16x16x32_bf16 v[66:69], v[204:207], v[236:239], v[66:69]
	v_mfma_f32_16x16x32_bf16 v[122:125], v[196:199], v[216:219], v[122:125]
	v_mfma_f32_16x16x32_bf16 v[114:117], v[208:211], v[216:219], v[114:117]
	v_mfma_f32_16x16x32_bf16 v[106:109], v[196:199], v[224:227], v[106:109]
	v_mfma_f32_16x16x32_bf16 v[98:101], v[208:211], v[224:227], v[98:101]
	v_mfma_f32_16x16x32_bf16 v[90:93], v[196:199], v[232:235], v[90:93]
	v_mfma_f32_16x16x32_bf16 v[82:85], v[208:211], v[232:235], v[82:85]
	v_mfma_f32_16x16x32_bf16 v[74:77], v[196:199], v[240:243], v[74:77]
	v_mfma_f32_16x16x32_bf16 v[66:69], v[208:211], v[240:243], v[66:69]
	s_barrier
	s_setprio 0
	s_add_i32 s29, s29, s84
	v_lshl_add_u64 v[172:173], v[244:245], 0, s[24:25]
	s_mov_b32 m0, s29
	ds_read_b128 v[212:215], v143 offset:49152
	ds_read_b128 v[216:219], v143 offset:50176
	ds_read_b128 v[220:223], v143 offset:51200
	ds_read_b128 v[224:227], v143 offset:52224
	ds_read_b128 v[228:231], v143 offset:53248
	ds_read_b128 v[232:235], v143 offset:54272
	ds_read_b128 v[236:239], v143 offset:55296
	ds_read_b128 v[240:243], v143 offset:56320
	global_load_lds_dwordx4 v[172:173], off
	s_add_i32 m0, s29, 0x2000
	s_add_u32 s42, s42, 0x40080
	v_lshl_add_u64 v[172:173], v[246:247], 0, s[24:25]
	s_addc_u32 s43, s43, 0
	s_add_i32 s29, s37, s84
	global_load_lds_dwordx4 v[172:173], off
	s_mov_b32 m0, s29
	v_lshl_add_u64 v[170:171], v[170:171], 0, s[24:25]
	global_load_lds_dwordx4 v138, s[42:43]
	s_add_i32 m0, s29, 0x2000
	s_nop 0
	global_load_lds_dwordx4 v134, s[42:43]
	v_lshl_add_u64 v[172:173], v[248:249], 0, s[24:25]
	s_mov_b32 m0, s97
	s_nop 0
	global_load_lds_dwordx4 v[172:173], off
	s_mov_b32 m0, s3
	s_nop 0
	global_load_lds_dwordx4 v[170:171], off
	s_waitcnt vmcnt(8)
	s_waitcnt lgkmcnt(0)
	s_setprio 1
	s_barrier
	v_mfma_f32_16x16x32_bf16 v[62:65], v[130:133], v[212:215], v[62:65]
	v_mfma_f32_16x16x32_bf16 v[54:57], v[184:187], v[212:215], v[54:57]
	v_mfma_f32_16x16x32_bf16 v[46:49], v[130:133], v[220:223], v[46:49]
	v_mfma_f32_16x16x32_bf16 v[38:41], v[184:187], v[220:223], v[38:41]
	v_mfma_f32_16x16x32_bf16 v[30:33], v[130:133], v[228:231], v[30:33]
	v_mfma_f32_16x16x32_bf16 v[22:25], v[184:187], v[228:231], v[22:25]
	v_mfma_f32_16x16x32_bf16 v[14:17], v[130:133], v[236:239], v[14:17]
	v_mfma_f32_16x16x32_bf16 v[6:9], v[184:187], v[236:239], v[6:9]
	v_mfma_f32_16x16x32_bf16 v[62:65], v[180:183], v[216:219], v[62:65]
	v_mfma_f32_16x16x32_bf16 v[54:57], v[188:191], v[216:219], v[54:57]
	v_mfma_f32_16x16x32_bf16 v[46:49], v[180:183], v[224:227], v[46:49]
	v_mfma_f32_16x16x32_bf16 v[38:41], v[188:191], v[224:227], v[38:41]
	v_mfma_f32_16x16x32_bf16 v[30:33], v[180:183], v[232:235], v[30:33]
	v_mfma_f32_16x16x32_bf16 v[22:25], v[188:191], v[232:235], v[22:25]
	v_mfma_f32_16x16x32_bf16 v[14:17], v[180:183], v[240:243], v[14:17]
	v_mfma_f32_16x16x32_bf16 v[6:9], v[188:191], v[240:243], v[6:9]
	v_mfma_f32_16x16x32_bf16 v[58:61], v[192:195], v[212:215], v[58:61]
	v_mfma_f32_16x16x32_bf16 v[50:53], v[204:207], v[212:215], v[50:53]
	v_mfma_f32_16x16x32_bf16 v[42:45], v[192:195], v[220:223], v[42:45]
	v_mfma_f32_16x16x32_bf16 v[34:37], v[204:207], v[220:223], v[34:37]
	v_mfma_f32_16x16x32_bf16 v[26:29], v[192:195], v[228:231], v[26:29]
	v_mfma_f32_16x16x32_bf16 v[18:21], v[204:207], v[228:231], v[18:21]
	v_mfma_f32_16x16x32_bf16 v[10:13], v[192:195], v[236:239], v[10:13]
	v_mfma_f32_16x16x32_bf16 v[2:5], v[204:207], v[236:239], v[2:5]
	v_mfma_f32_16x16x32_bf16 v[58:61], v[196:199], v[216:219], v[58:61]
	v_mfma_f32_16x16x32_bf16 v[50:53], v[208:211], v[216:219], v[50:53]
	v_mfma_f32_16x16x32_bf16 v[42:45], v[196:199], v[224:227], v[42:45]
	v_mfma_f32_16x16x32_bf16 v[34:37], v[208:211], v[224:227], v[34:37]
	v_mfma_f32_16x16x32_bf16 v[26:29], v[196:199], v[232:235], v[26:29]
	v_mfma_f32_16x16x32_bf16 v[18:21], v[208:211], v[232:235], v[18:21]
	v_mfma_f32_16x16x32_bf16 v[10:13], v[196:199], v[240:243], v[10:13]
	v_mfma_f32_16x16x32_bf16 v[2:5], v[208:211], v[240:243], v[2:5]
	s_barrier
	s_setprio 0
	s_add_u32 s16, s16, 0x100
	s_addc_u32 s17, s17, 0
	s_add_u32 s56, s56, 0x100
	s_addc_u32 s57, s57, 0
	s_cmp_ge_i32 s86, s23
	s_mov_b32 s42, s86
	s_cbranch_scc0 .LBB7_357
	s_mov_b32 s56, s61

.LBB7_360:
	v_and_b32_e32 v131, 64, v163
	v_xor_b32_e32 v130, 16, v163
	v_add_u32_e32 v131, 64, v131
	v_cmp_lt_i32_e32 vcc, v130, v131
	v_lshl_add_u32 v132, s38, 8, v142
	v_ashrrev_i32_e32 v133, 31, v132
	v_cndmask_b32_e32 v130, v163, v130, vcc
	v_lshlrev_b32_e32 v183, 2, v130
	v_xor_b32_e32 v130, 32, v163
	v_cmp_lt_i32_e32 vcc, v130, v131
	v_or_b32_e32 v172, 16, v132
	v_ashrrev_i32_e32 v173, 31, v172
	v_cndmask_b32_e32 v130, v163, v130, vcc
	v_lshlrev_b32_e32 v181, 2, v130
	v_lshlrev_b64 v[130:131], 6, v[132:133]
	v_lshl_add_u64 v[130:131], v[144:145], 0, v[130:131]
	v_lshlrev_b64 v[172:173], 6, v[172:173]
	v_lshl_add_u64 v[172:173], v[144:145], 0, v[172:173]
	s_lshl_b32 s9, s10, 7
	s_mov_b32 s10, 0x358637bd
	v_mov_b64_e32 v[190:191], s[10:11]
	s_movk_i32 s10, 0x2000
	s_or_b32 s9, s9, s96
	s_ashr_i32 s16, s9, 6
	s_ashr_i32 s17, s16, 31
	s_mul_i32 s13, s38, 0x160000
	s_lshl_b64 s[16:17], s[16:17], 15
	s_add_u32 s9, s70, s13
	s_waitcnt vmcnt(0)
	v_mov_b64_e32 v[184:185], v[204:205]
	v_mov_b64_e32 v[186:187], v[206:207]
	v_mov_b32_e32 v170, v185
	v_mov_b32_e32 v171, v186
	v_mov_b32_e32 v185, v187
	v_pk_add_f32 v[170:171], v[170:171], v[184:185]
	v_mov_b64_e32 v[184:185], v[208:209]
	v_mov_b64_e32 v[186:187], v[210:211]
	v_mov_b32_e32 v172, v185
	v_mov_b32_e32 v173, v186
	v_mov_b32_e32 v185, v187
	v_pk_add_f32 v[172:173], v[172:173], v[184:185]
	v_mov_b32_e32 v185, v170
	v_mov_b32_e32 v184, v172
	v_mov_b32_e32 v170, v173
	v_pk_add_f32 v[170:171], v[184:185], v[170:171]
	ds_bpermute_b32 v173, v183, v171
	ds_bpermute_b32 v172, v183, v170
	s_waitcnt lgkmcnt(0)
	v_pk_add_f32 v[170:171], v[170:171], v[172:173]
	ds_bpermute_b32 v173, v181, v171
	ds_bpermute_b32 v172, v181, v170
	s_waitcnt lgkmcnt(0)
	v_pk_add_f32 v[170:171], v[170:171], v[172:173]
	s_nop 0
	v_pk_fma_f32 v[170:171], v[170:171], s[26:27], v[190:191] op_sel_hi:[1,0,0]
	s_nop 0
	v_mul_f32_e32 v133, 0x4b800000, v171
	v_cmp_gt_f32_e64 s[42:43], s11, v171
	v_cmp_gt_f32_e32 vcc, s11, v170
	s_nop 0
	v_cndmask_b32_e64 v133, v171, v133, s[42:43]
	v_rsq_f32_e32 v133, v133
	s_nop 0
	v_mul_f32_e32 v171, 0x45800000, v133
	v_cndmask_b32_e64 v188, v133, v171, s[42:43]
	v_mul_f32_e32 v133, 0x4b800000, v170
	v_cndmask_b32_e32 v133, v170, v133, vcc
	v_rsq_f32_e32 v133, v133
	v_pk_mul_f32 v[126:127], v[126:127], v[188:189] op_sel_hi:[1,0]
	v_pk_mul_f32 v[122:123], v[122:123], v[188:189] op_sel_hi:[1,0]
	v_pk_mul_f32 v[124:125], v[124:125], v[188:189] op_sel_hi:[1,0]
	v_mul_f32_e32 v170, 0x45800000, v133
	v_cndmask_b32_e32 v186, v133, v170, vcc
	v_or_b32_e32 v170, 32, v132
	v_ashrrev_i32_e32 v171, 31, v170
	v_lshlrev_b64 v[170:171], 6, v[170:171]
	v_lshl_add_u64 v[170:171], v[144:145], 0, v[170:171]
	v_or_b32_e32 v132, 48, v132
	v_ashrrev_i32_e32 v133, 31, v132
	v_lshlrev_b64 v[132:133], 6, v[132:133]
	v_lshl_add_u64 v[132:133], v[144:145], 0, v[132:133]
	v_pk_mul_f32 v[122:123], v[126:127], v[122:123]
	v_pk_mul_f32 v[118:119], v[118:119], v[188:189] op_sel_hi:[1,0]
	v_pk_mul_f32 v[114:115], v[114:115], v[188:189] op_sel_hi:[1,0]
	v_pk_mul_f32 v[116:117], v[116:117], v[188:189] op_sel_hi:[1,0]
	v_pk_mul_f32 v[114:115], v[118:119], v[114:115]
	v_pk_mul_f32 v[110:111], v[110:111], v[186:187] op_sel_hi:[1,0]
	v_pk_mul_f32 v[106:107], v[106:107], v[186:187] op_sel_hi:[1,0]
	v_pk_mul_f32 v[108:109], v[108:109], v[186:187] op_sel_hi:[1,0]
	v_pk_mul_f32 v[106:107], v[110:111], v[106:107]
	v_pk_mul_f32 v[102:103], v[102:103], v[186:187] op_sel_hi:[1,0]
	v_pk_mul_f32 v[98:99], v[98:99], v[186:187] op_sel_hi:[1,0]
	v_pk_mul_f32 v[100:101], v[100:101], v[186:187] op_sel_hi:[1,0]
	v_pk_mul_f32 v[98:99], v[102:103], v[98:99]
	v_mov_b64_e32 v[192:193], v[212:213]
	v_mov_b64_e32 v[194:195], v[214:215]
	v_mov_b32_e32 v170, v193
	v_mov_b32_e32 v171, v194
	v_mov_b32_e32 v193, v195
	v_pk_add_f32 v[170:171], v[170:171], v[192:193]
	v_mov_b64_e32 v[192:193], v[216:217]
	v_mov_b64_e32 v[194:195], v[218:219]
	v_mov_b32_e32 v173, v170
	v_mov_b32_e32 v132, v193
	v_mov_b32_e32 v133, v194
	v_mov_b32_e32 v193, v195
	v_pk_add_f32 v[132:133], v[132:133], v[192:193]
	s_nop 0
	v_mov_b32_e32 v172, v132
	v_mov_b32_e32 v170, v133
	v_pk_add_f32 v[132:133], v[172:173], v[170:171]
	ds_bpermute_b32 v171, v183, v133
	ds_bpermute_b32 v170, v183, v132
	s_waitcnt lgkmcnt(0)
	v_pk_add_f32 v[132:133], v[132:133], v[170:171]
	ds_bpermute_b32 v171, v181, v133
	ds_bpermute_b32 v170, v181, v132
	s_waitcnt lgkmcnt(0)
	v_pk_add_f32 v[132:133], v[132:133], v[170:171]
	s_nop 0
	v_pk_fma_f32 v[132:133], v[132:133], s[26:27], v[190:191] op_sel_hi:[1,0,0]
	s_nop 0
	v_mul_f32_e32 v170, 0x4b800000, v133
	v_cmp_gt_f32_e64 s[42:43], s11, v133
	v_cmp_gt_f32_e32 vcc, s11, v132
	s_nop 0
	v_cndmask_b32_e64 v133, v133, v170, s[42:43]
	v_rsq_f32_e32 v133, v133
	s_nop 0
	v_mul_f32_e32 v170, 0x45800000, v133
	v_cndmask_b32_e64 v184, v133, v170, s[42:43]
	v_mul_f32_e32 v133, 0x4b800000, v132
	v_cndmask_b32_e32 v132, v132, v133, vcc
	v_rsq_f32_e32 v132, v132
	v_pk_mul_f32 v[94:95], v[94:95], v[184:185] op_sel_hi:[1,0]
	v_pk_mul_f32 v[90:91], v[90:91], v[184:185] op_sel_hi:[1,0]
	v_pk_mul_f32 v[92:93], v[92:93], v[184:185] op_sel_hi:[1,0]
	v_mul_f32_e32 v133, 0x45800000, v132
	v_cndmask_b32_e32 v182, v132, v133, vcc
	v_add_co_u32_e32 v170, vcc, s10, v130
	s_mul_hi_i32 s10, s38, 0x160000
	s_nop 0
	v_addc_co_u32_e32 v171, vcc, 0, v131, vcc
	s_addc_u32 s10, s71, s10
	s_add_u32 s16, s9, s16
	s_addc_u32 s17, s10, s17
	v_pk_mul_f32 v[90:91], v[94:95], v[90:91]
	v_pk_mul_f32 v[86:87], v[86:87], v[184:185] op_sel_hi:[1,0]
	v_pk_mul_f32 v[82:83], v[82:83], v[184:185] op_sel_hi:[1,0]
	v_pk_mul_f32 v[84:85], v[84:85], v[184:185] op_sel_hi:[1,0]
	v_pk_mul_f32 v[82:83], v[86:87], v[82:83]
	v_pk_mul_f32 v[78:79], v[78:79], v[182:183] op_sel_hi:[1,0]
	v_pk_mul_f32 v[74:75], v[74:75], v[182:183] op_sel_hi:[1,0]
	v_pk_mul_f32 v[76:77], v[76:77], v[182:183] op_sel_hi:[1,0]
	v_pk_mul_f32 v[74:75], v[78:79], v[74:75]
	v_pk_mul_f32 v[70:71], v[70:71], v[182:183] op_sel_hi:[1,0]
	v_pk_mul_f32 v[66:67], v[66:67], v[182:183] op_sel_hi:[1,0]
	v_pk_mul_f32 v[68:69], v[68:69], v[182:183] op_sel_hi:[1,0]
	v_pk_mul_f32 v[66:67], v[70:71], v[66:67]
	v_mov_b64_e32 v[130:131], v[220:221]
	v_mov_b64_e32 v[132:133], v[222:223]
	v_mov_b32_e32 v172, v131
	v_mov_b32_e32 v173, v132
	v_mov_b32_e32 v131, v133
	v_pk_add_f32 v[172:173], v[172:173], v[130:131]
	v_mov_b64_e32 v[130:131], v[224:225]
	v_mov_b64_e32 v[132:133], v[226:227]
	v_mov_b32_e32 v192, v131
	v_mov_b32_e32 v193, v132
	v_mov_b32_e32 v131, v133
	v_pk_add_f32 v[130:131], v[192:193], v[130:131]
	v_mov_b32_e32 v133, v172
	v_mov_b32_e32 v132, v130
	v_mov_b32_e32 v172, v131
	v_pk_add_f32 v[130:131], v[132:133], v[172:173]
	ds_bpermute_b32 v133, v183, v131
	ds_bpermute_b32 v132, v183, v130
	s_waitcnt lgkmcnt(0)
	v_pk_add_f32 v[130:131], v[130:131], v[132:133]
	ds_bpermute_b32 v133, v181, v131
	ds_bpermute_b32 v132, v181, v130
	s_waitcnt lgkmcnt(0)
	v_pk_add_f32 v[130:131], v[130:131], v[132:133]
	s_nop 0
	v_pk_fma_f32 v[130:131], v[130:131], s[26:27], v[190:191] op_sel_hi:[1,0,0]
	s_nop 0
	v_mul_f32_e32 v132, 0x4b800000, v131
	v_cmp_gt_f32_e64 s[42:43], s11, v131
	v_cmp_gt_f32_e32 vcc, s11, v130
	s_nop 0
	v_cndmask_b32_e64 v131, v131, v132, s[42:43]
	v_rsq_f32_e32 v131, v131
	s_nop 0
	v_mul_f32_e32 v132, 0x45800000, v131
	v_cndmask_b32_e64 v180, v131, v132, s[42:43]
	v_mul_f32_e32 v131, 0x4b800000, v130
	v_cndmask_b32_e32 v130, v130, v131, vcc
	v_rsq_f32_e32 v130, v130
	v_pk_mul_f32 v[62:63], v[62:63], v[180:181] op_sel_hi:[1,0]
	v_pk_mul_f32 v[58:59], v[58:59], v[180:181] op_sel_hi:[1,0]
	v_pk_mul_f32 v[60:61], v[60:61], v[180:181] op_sel_hi:[1,0]
	v_mul_f32_e32 v131, 0x45800000, v130
	v_cndmask_b32_e32 v178, v130, v131, vcc
	v_pk_mul_f32 v[58:59], v[62:63], v[58:59]
	v_pk_mul_f32 v[54:55], v[54:55], v[180:181] op_sel_hi:[1,0]
	v_pk_mul_f32 v[50:51], v[50:51], v[180:181] op_sel_hi:[1,0]
	v_pk_mul_f32 v[52:53], v[52:53], v[180:181] op_sel_hi:[1,0]
	v_pk_mul_f32 v[50:51], v[54:55], v[50:51]
	v_pk_mul_f32 v[46:47], v[46:47], v[178:179] op_sel_hi:[1,0]
	v_pk_mul_f32 v[42:43], v[42:43], v[178:179] op_sel_hi:[1,0]
	v_pk_mul_f32 v[44:45], v[44:45], v[178:179] op_sel_hi:[1,0]
	v_pk_mul_f32 v[42:43], v[46:47], v[42:43]
	v_pk_mul_f32 v[38:39], v[38:39], v[178:179] op_sel_hi:[1,0]
	v_pk_mul_f32 v[34:35], v[34:35], v[178:179] op_sel_hi:[1,0]
	v_pk_mul_f32 v[36:37], v[36:37], v[178:179] op_sel_hi:[1,0]
	v_pk_mul_f32 v[34:35], v[38:39], v[34:35]
	v_mov_b64_e32 v[130:131], v[228:229]
	v_mov_b64_e32 v[132:133], v[230:231]
	v_mov_b32_e32 v172, v131
	v_mov_b32_e32 v173, v132
	v_mov_b32_e32 v131, v133
	v_pk_add_f32 v[192:193], v[172:173], v[130:131]
	v_mov_b64_e32 v[130:131], v[232:233]
	v_mov_b64_e32 v[132:133], v[234:235]
	v_mov_b32_e32 v170, v131
	v_mov_b32_e32 v171, v132
	v_mov_b32_e32 v131, v133
	v_pk_add_f32 v[130:131], v[170:171], v[130:131]
	v_pk_mul_f32 v[170:171], v[126:127], s[30:31] op_sel_hi:[1,0]
	v_pk_mul_f32 v[126:127], v[128:129], v[188:189] op_sel_hi:[1,0]
	v_exp_f32_e32 v170, v170
	v_pk_mul_f32 v[128:129], v[126:127], s[30:31] op_sel_hi:[1,0]
	v_exp_f32_e32 v171, v171
	v_exp_f32_e32 v128, v128
	v_exp_f32_e32 v129, v129
	v_pk_mul_f32 v[124:125], v[126:127], v[124:125]
	v_pk_add_f32 v[170:171], v[170:171], 1.0 op_sel_hi:[1,0]
	v_mov_b32_e32 v132, v130
	v_pk_add_f32 v[128:129], v[128:129], 1.0 op_sel_hi:[1,0]
	v_rcp_f32_e32 v170, v170
	v_rcp_f32_e32 v171, v171
	v_rcp_f32_e32 v128, v128
	v_rcp_f32_e32 v129, v129
	v_mov_b32_e32 v133, v192
	v_pk_mul_f32 v[122:123], v[122:123], v[170:171]
	v_mov_b32_e32 v192, v131
	v_pk_mul_f32 v[124:125], v[124:125], v[128:129]
	v_cvt_pk_bf16_f32 v122, v122, v123
	v_pk_add_f32 v[130:131], v[132:133], v[192:193]
	v_cvt_pk_bf16_f32 v123, v124, v125
	v_pk_mul_f32 v[124:125], v[118:119], s[30:31] op_sel_hi:[1,0]
	ds_bpermute_b32 v133, v183, v131
	v_exp_f32_e32 v124, v124
	v_exp_f32_e32 v125, v125
	ds_bpermute_b32 v132, v183, v130
	v_pk_add_f32 v[124:125], v[124:125], 1.0 op_sel_hi:[1,0]
	s_nop 0
	v_rcp_f32_e32 v124, v124
	v_rcp_f32_e32 v125, v125
	s_waitcnt lgkmcnt(0)
	v_pk_add_f32 v[130:131], v[130:131], v[132:133]
	ds_bpermute_b32 v133, v181, v131
	ds_bpermute_b32 v132, v181, v130
	v_pk_mul_f32 v[114:115], v[114:115], v[124:125]
	s_waitcnt lgkmcnt(0)
	v_pk_add_f32 v[130:131], v[130:131], v[132:133]
	v_cvt_pk_bf16_f32 v124, v114, v115
	v_pk_mul_f32 v[114:115], v[120:121], v[188:189] op_sel_hi:[1,0]
	v_pk_fma_f32 v[130:131], v[130:131], s[26:27], v[190:191] op_sel_hi:[1,0,0]
	v_pk_mul_f32 v[118:119], v[114:115], s[30:31] op_sel_hi:[1,0]
	v_pk_mul_f32 v[114:115], v[114:115], v[116:117]
	v_exp_f32_e32 v118, v118
	v_exp_f32_e32 v119, v119
	v_mul_f32_e32 v132, 0x4b800000, v131
	v_cmp_gt_f32_e64 s[42:43], s11, v131
	v_cmp_gt_f32_e32 vcc, s11, v130
	v_pk_add_f32 v[118:119], v[118:119], 1.0 op_sel_hi:[1,0]
	v_cndmask_b32_e64 v131, v131, v132, s[42:43]
	v_rcp_f32_e32 v118, v118
	v_rcp_f32_e32 v119, v119
	v_rsq_f32_e32 v131, v131
	v_pk_mul_f32 v[114:115], v[114:115], v[118:119]
	s_nop 0
	v_cvt_pk_bf16_f32 v125, v114, v115
	v_lshl_add_u64 v[114:115], s[16:17], 0, v[146:147]
	v_lshl_add_u64 v[114:115], v[114:115], 0, v[0:1]
	global_store_dwordx4 v[114:115], v[122:125], off nt
	v_pk_mul_f32 v[114:115], v[110:111], s[30:31] op_sel_hi:[1,0]
	v_pk_mul_f32 v[110:111], v[112:113], v[186:187] op_sel_hi:[1,0]
	v_exp_f32_e32 v114, v114
	v_pk_mul_f32 v[112:113], v[110:111], s[30:31] op_sel_hi:[1,0]
	v_exp_f32_e32 v115, v115
	v_exp_f32_e32 v112, v112
	v_exp_f32_e32 v113, v113
	v_pk_mul_f32 v[108:109], v[110:111], v[108:109]
	v_pk_add_f32 v[114:115], v[114:115], 1.0 op_sel_hi:[1,0]
	v_pk_add_f32 v[112:113], v[112:113], 1.0 op_sel_hi:[1,0]
	v_rcp_f32_e32 v114, v114
	v_rcp_f32_e32 v115, v115
	v_rcp_f32_e32 v112, v112
	v_rcp_f32_e32 v113, v113
	v_mul_f32_e32 v132, 0x45800000, v131
	v_pk_mul_f32 v[106:107], v[106:107], v[114:115]
	v_cndmask_b32_e64 v132, v131, v132, s[42:43]
	v_pk_mul_f32 v[108:109], v[108:109], v[112:113]
	v_cvt_pk_bf16_f32 v106, v106, v107
	v_pk_mul_f32 v[30:31], v[30:31], v[132:133] op_sel_hi:[1,0]
	v_cvt_pk_bf16_f32 v107, v108, v109
	v_pk_mul_f32 v[108:109], v[102:103], s[30:31] op_sel_hi:[1,0]
	v_pk_mul_f32 v[26:27], v[26:27], v[132:133] op_sel_hi:[1,0]
	v_exp_f32_e32 v108, v108
	v_exp_f32_e32 v109, v109
	v_pk_mul_f32 v[26:27], v[30:31], v[26:27]
	v_pk_mul_f32 v[28:29], v[28:29], v[132:133] op_sel_hi:[1,0]
	v_pk_mul_f32 v[22:23], v[22:23], v[132:133] op_sel_hi:[1,0]
	v_pk_add_f32 v[108:109], v[108:109], 1.0 op_sel_hi:[1,0]
	v_pk_mul_f32 v[18:19], v[18:19], v[132:133] op_sel_hi:[1,0]
	v_rcp_f32_e32 v108, v108
	v_rcp_f32_e32 v109, v109
	v_pk_mul_f32 v[18:19], v[22:23], v[18:19]
	v_mul_f32_e32 v131, 0x4b800000, v130
	v_cndmask_b32_e32 v130, v130, v131, vcc
	v_pk_mul_f32 v[98:99], v[98:99], v[108:109]
	v_rsq_f32_e32 v130, v130
	v_cvt_pk_bf16_f32 v108, v98, v99
	v_pk_mul_f32 v[98:99], v[104:105], v[186:187] op_sel_hi:[1,0]
	v_pk_mul_f32 v[20:21], v[20:21], v[132:133] op_sel_hi:[1,0]
	v_pk_mul_f32 v[102:103], v[98:99], s[30:31] op_sel_hi:[1,0]
	v_pk_mul_f32 v[98:99], v[98:99], v[100:101]
	v_exp_f32_e32 v102, v102
	v_exp_f32_e32 v103, v103
	v_mul_f32_e32 v131, 0x45800000, v130
	v_cndmask_b32_e32 v130, v130, v131, vcc
	v_pk_mul_f32 v[14:15], v[14:15], v[130:131] op_sel_hi:[1,0]
	v_pk_add_f32 v[102:103], v[102:103], 1.0 op_sel_hi:[1,0]
	v_pk_mul_f32 v[10:11], v[10:11], v[130:131] op_sel_hi:[1,0]
	v_rcp_f32_e32 v102, v102
	v_rcp_f32_e32 v103, v103
	v_pk_mul_f32 v[10:11], v[14:15], v[10:11]
	v_pk_mul_f32 v[12:13], v[12:13], v[130:131] op_sel_hi:[1,0]
	v_pk_mul_f32 v[6:7], v[6:7], v[130:131] op_sel_hi:[1,0]
	v_pk_mul_f32 v[98:99], v[98:99], v[102:103]
	v_pk_mul_f32 v[2:3], v[2:3], v[130:131] op_sel_hi:[1,0]
	v_cvt_pk_bf16_f32 v109, v98, v99
	v_lshl_add_u64 v[98:99], s[16:17], 0, v[148:149]
	v_lshl_add_u64 v[98:99], v[98:99], 0, v[0:1]
	global_store_dwordx4 v[98:99], v[106:109], off nt
	v_pk_mul_f32 v[98:99], v[94:95], s[30:31] op_sel_hi:[1,0]
	v_pk_mul_f32 v[94:95], v[96:97], v[184:185] op_sel_hi:[1,0]
	v_exp_f32_e32 v98, v98
	v_pk_mul_f32 v[96:97], v[94:95], s[30:31] op_sel_hi:[1,0]
	v_exp_f32_e32 v99, v99
	v_exp_f32_e32 v96, v96
	v_exp_f32_e32 v97, v97
	v_pk_mul_f32 v[92:93], v[94:95], v[92:93]
	v_pk_add_f32 v[98:99], v[98:99], 1.0 op_sel_hi:[1,0]
	v_pk_add_f32 v[96:97], v[96:97], 1.0 op_sel_hi:[1,0]
	v_rcp_f32_e32 v98, v98
	v_rcp_f32_e32 v99, v99
	v_rcp_f32_e32 v96, v96
	v_rcp_f32_e32 v97, v97
	v_pk_mul_f32 v[2:3], v[6:7], v[2:3]
	v_pk_mul_f32 v[90:91], v[90:91], v[98:99]
	v_pk_mul_f32 v[4:5], v[4:5], v[130:131] op_sel_hi:[1,0]
	v_pk_mul_f32 v[92:93], v[92:93], v[96:97]
	v_cvt_pk_bf16_f32 v90, v90, v91
	s_andn2_b64 vcc, exec, s[40:41]
	v_cvt_pk_bf16_f32 v91, v92, v93
	v_pk_mul_f32 v[92:93], v[86:87], s[30:31] op_sel_hi:[1,0]
	s_nop 0
	v_exp_f32_e32 v92, v92
	v_exp_f32_e32 v93, v93
	s_nop 0
	v_pk_add_f32 v[92:93], v[92:93], 1.0 op_sel_hi:[1,0]
	s_nop 0
	v_rcp_f32_e32 v92, v92
	v_rcp_f32_e32 v93, v93
	s_nop 0
	v_pk_mul_f32 v[82:83], v[82:83], v[92:93]
	s_nop 0
	v_cvt_pk_bf16_f32 v92, v82, v83
	v_pk_mul_f32 v[82:83], v[88:89], v[184:185] op_sel_hi:[1,0]
	s_nop 0
	v_pk_mul_f32 v[86:87], v[82:83], s[30:31] op_sel_hi:[1,0]
	v_pk_mul_f32 v[82:83], v[82:83], v[84:85]
	v_exp_f32_e32 v86, v86
	v_exp_f32_e32 v87, v87
	s_nop 0
	v_pk_add_f32 v[86:87], v[86:87], 1.0 op_sel_hi:[1,0]
	s_nop 0
	v_rcp_f32_e32 v86, v86
	v_rcp_f32_e32 v87, v87
	s_nop 0
	v_pk_mul_f32 v[82:83], v[82:83], v[86:87]
	s_nop 0
	v_cvt_pk_bf16_f32 v93, v82, v83
	v_lshl_add_u64 v[82:83], s[16:17], 0, v[150:151]
	v_lshl_add_u64 v[82:83], v[82:83], 0, v[0:1]
	global_store_dwordx4 v[82:83], v[90:93], off nt
	v_pk_mul_f32 v[82:83], v[78:79], s[30:31] op_sel_hi:[1,0]
	v_pk_mul_f32 v[78:79], v[80:81], v[182:183] op_sel_hi:[1,0]
	v_exp_f32_e32 v82, v82
	v_pk_mul_f32 v[80:81], v[78:79], s[30:31] op_sel_hi:[1,0]
	v_exp_f32_e32 v83, v83
	v_exp_f32_e32 v80, v80
	v_exp_f32_e32 v81, v81
	v_pk_mul_f32 v[76:77], v[78:79], v[76:77]
	v_pk_add_f32 v[82:83], v[82:83], 1.0 op_sel_hi:[1,0]
	v_pk_add_f32 v[80:81], v[80:81], 1.0 op_sel_hi:[1,0]
	v_rcp_f32_e32 v82, v82
	v_rcp_f32_e32 v83, v83
	v_rcp_f32_e32 v80, v80
	v_rcp_f32_e32 v81, v81
	v_pk_mul_f32 v[74:75], v[74:75], v[82:83]
	s_nop 0
	v_cvt_pk_bf16_f32 v74, v74, v75
	v_pk_mul_f32 v[76:77], v[76:77], v[80:81]
	s_nop 0
	v_cvt_pk_bf16_f32 v75, v76, v77
	v_pk_mul_f32 v[76:77], v[70:71], s[30:31] op_sel_hi:[1,0]
	s_nop 0
	v_exp_f32_e32 v76, v76
	v_exp_f32_e32 v77, v77
	s_nop 0
	v_pk_add_f32 v[76:77], v[76:77], 1.0 op_sel_hi:[1,0]
	s_nop 0
	v_rcp_f32_e32 v76, v76
	v_rcp_f32_e32 v77, v77
	s_nop 0
	v_pk_mul_f32 v[66:67], v[66:67], v[76:77]
	s_nop 0
	v_cvt_pk_bf16_f32 v76, v66, v67
	v_pk_mul_f32 v[66:67], v[72:73], v[182:183] op_sel_hi:[1,0]
	s_nop 0
	v_pk_mul_f32 v[70:71], v[66:67], s[30:31] op_sel_hi:[1,0]
	v_pk_mul_f32 v[66:67], v[66:67], v[68:69]
	v_exp_f32_e32 v70, v70
	v_exp_f32_e32 v71, v71
	s_nop 0
	v_pk_add_f32 v[70:71], v[70:71], 1.0 op_sel_hi:[1,0]
	s_nop 0
	v_rcp_f32_e32 v70, v70
	v_rcp_f32_e32 v71, v71
	s_nop 0
	v_pk_mul_f32 v[66:67], v[66:67], v[70:71]
	s_nop 0
	v_cvt_pk_bf16_f32 v77, v66, v67
	v_lshl_add_u64 v[66:67], s[16:17], 0, v[152:153]
	v_lshl_add_u64 v[66:67], v[66:67], 0, v[0:1]
	global_store_dwordx4 v[66:67], v[74:77], off nt
	v_pk_mul_f32 v[66:67], v[62:63], s[30:31] op_sel_hi:[1,0]
	v_pk_mul_f32 v[62:63], v[64:65], v[180:181] op_sel_hi:[1,0]
	v_exp_f32_e32 v66, v66
	v_pk_mul_f32 v[64:65], v[62:63], s[30:31] op_sel_hi:[1,0]
	v_exp_f32_e32 v67, v67
	v_exp_f32_e32 v64, v64
	v_exp_f32_e32 v65, v65
	v_pk_mul_f32 v[60:61], v[62:63], v[60:61]
	v_pk_add_f32 v[66:67], v[66:67], 1.0 op_sel_hi:[1,0]
	v_pk_add_f32 v[64:65], v[64:65], 1.0 op_sel_hi:[1,0]
	v_rcp_f32_e32 v66, v66
	v_rcp_f32_e32 v67, v67
	v_rcp_f32_e32 v64, v64
	v_rcp_f32_e32 v65, v65
	v_pk_mul_f32 v[58:59], v[58:59], v[66:67]
	s_nop 0
	v_cvt_pk_bf16_f32 v58, v58, v59
	v_pk_mul_f32 v[60:61], v[60:61], v[64:65]
	s_nop 0
	v_cvt_pk_bf16_f32 v59, v60, v61
	v_pk_mul_f32 v[60:61], v[54:55], s[30:31] op_sel_hi:[1,0]
	s_nop 0
	v_exp_f32_e32 v60, v60
	v_exp_f32_e32 v61, v61
	s_nop 0
	v_pk_add_f32 v[60:61], v[60:61], 1.0 op_sel_hi:[1,0]
	s_nop 0
	v_rcp_f32_e32 v60, v60
	v_rcp_f32_e32 v61, v61
	s_nop 0
	v_pk_mul_f32 v[50:51], v[50:51], v[60:61]
	s_nop 0
	v_cvt_pk_bf16_f32 v60, v50, v51
	v_pk_mul_f32 v[50:51], v[56:57], v[180:181] op_sel_hi:[1,0]
	s_nop 0
	v_pk_mul_f32 v[54:55], v[50:51], s[30:31] op_sel_hi:[1,0]
	v_pk_mul_f32 v[50:51], v[50:51], v[52:53]
	v_exp_f32_e32 v54, v54
	v_exp_f32_e32 v55, v55
	s_nop 0
	v_pk_add_f32 v[54:55], v[54:55], 1.0 op_sel_hi:[1,0]
	s_nop 0
	v_rcp_f32_e32 v54, v54
	v_rcp_f32_e32 v55, v55
	s_nop 0
	v_pk_mul_f32 v[50:51], v[50:51], v[54:55]
	s_nop 0
	v_cvt_pk_bf16_f32 v61, v50, v51
	v_lshl_add_u64 v[50:51], s[16:17], 0, v[154:155]
	v_lshl_add_u64 v[50:51], v[50:51], 0, v[0:1]
	global_store_dwordx4 v[50:51], v[58:61], off nt
	v_pk_mul_f32 v[50:51], v[46:47], s[30:31] op_sel_hi:[1,0]
	v_pk_mul_f32 v[46:47], v[48:49], v[178:179] op_sel_hi:[1,0]
	v_exp_f32_e32 v50, v50
	v_pk_mul_f32 v[48:49], v[46:47], s[30:31] op_sel_hi:[1,0]
	v_exp_f32_e32 v51, v51
	v_exp_f32_e32 v48, v48
	v_exp_f32_e32 v49, v49
	v_pk_mul_f32 v[44:45], v[46:47], v[44:45]
	v_pk_add_f32 v[50:51], v[50:51], 1.0 op_sel_hi:[1,0]
	v_pk_add_f32 v[48:49], v[48:49], 1.0 op_sel_hi:[1,0]
	v_rcp_f32_e32 v50, v50
	v_rcp_f32_e32 v51, v51
	v_rcp_f32_e32 v48, v48
	v_rcp_f32_e32 v49, v49
	v_pk_mul_f32 v[42:43], v[42:43], v[50:51]
	s_nop 0
	v_cvt_pk_bf16_f32 v42, v42, v43
	v_pk_mul_f32 v[44:45], v[44:45], v[48:49]
	s_nop 0
	v_cvt_pk_bf16_f32 v43, v44, v45
	v_pk_mul_f32 v[44:45], v[38:39], s[30:31] op_sel_hi:[1,0]
	s_nop 0
	v_exp_f32_e32 v44, v44
	v_exp_f32_e32 v45, v45
	s_nop 0
	v_pk_add_f32 v[44:45], v[44:45], 1.0 op_sel_hi:[1,0]
	s_nop 0
	v_rcp_f32_e32 v44, v44
	v_rcp_f32_e32 v45, v45
	s_nop 0
	v_pk_mul_f32 v[34:35], v[34:35], v[44:45]
	s_nop 0
	v_cvt_pk_bf16_f32 v44, v34, v35
	v_pk_mul_f32 v[34:35], v[40:41], v[178:179] op_sel_hi:[1,0]
	s_nop 0
	v_pk_mul_f32 v[38:39], v[34:35], s[30:31] op_sel_hi:[1,0]
	v_pk_mul_f32 v[34:35], v[34:35], v[36:37]
	v_exp_f32_e32 v38, v38
	v_exp_f32_e32 v39, v39
	s_nop 0
	v_pk_add_f32 v[38:39], v[38:39], 1.0 op_sel_hi:[1,0]
	s_nop 0
	v_rcp_f32_e32 v38, v38
	v_rcp_f32_e32 v39, v39
	s_nop 0
	v_pk_mul_f32 v[34:35], v[34:35], v[38:39]
	s_nop 0
	v_cvt_pk_bf16_f32 v45, v34, v35
	v_lshl_add_u64 v[34:35], s[16:17], 0, v[156:157]
	v_lshl_add_u64 v[34:35], v[34:35], 0, v[0:1]
	global_store_dwordx4 v[34:35], v[42:45], off nt
	v_pk_mul_f32 v[34:35], v[30:31], s[30:31] op_sel_hi:[1,0]
	v_pk_mul_f32 v[30:31], v[32:33], v[132:133] op_sel_hi:[1,0]
	v_exp_f32_e32 v34, v34
	v_pk_mul_f32 v[32:33], v[30:31], s[30:31] op_sel_hi:[1,0]
	v_exp_f32_e32 v35, v35
	v_exp_f32_e32 v32, v32
	v_exp_f32_e32 v33, v33
	v_pk_mul_f32 v[28:29], v[30:31], v[28:29]
	v_pk_add_f32 v[34:35], v[34:35], 1.0 op_sel_hi:[1,0]
	v_pk_add_f32 v[32:33], v[32:33], 1.0 op_sel_hi:[1,0]
	v_rcp_f32_e32 v34, v34
	v_rcp_f32_e32 v35, v35
	v_rcp_f32_e32 v32, v32
	v_rcp_f32_e32 v33, v33
	v_pk_mul_f32 v[26:27], v[26:27], v[34:35]
	s_nop 0
	v_cvt_pk_bf16_f32 v26, v26, v27
	v_pk_mul_f32 v[28:29], v[28:29], v[32:33]
	s_nop 0
	v_cvt_pk_bf16_f32 v27, v28, v29
	v_pk_mul_f32 v[28:29], v[22:23], s[30:31] op_sel_hi:[1,0]
	s_nop 0
	v_exp_f32_e32 v28, v28
	v_exp_f32_e32 v29, v29
	s_nop 0
	v_pk_add_f32 v[28:29], v[28:29], 1.0 op_sel_hi:[1,0]
	s_nop 0
	v_rcp_f32_e32 v28, v28
	v_rcp_f32_e32 v29, v29
	s_nop 0
	v_pk_mul_f32 v[18:19], v[18:19], v[28:29]
	s_nop 0
	v_cvt_pk_bf16_f32 v28, v18, v19
	v_pk_mul_f32 v[18:19], v[24:25], v[132:133] op_sel_hi:[1,0]
	s_nop 0
	v_pk_mul_f32 v[22:23], v[18:19], s[30:31] op_sel_hi:[1,0]
	v_pk_mul_f32 v[18:19], v[18:19], v[20:21]
	v_exp_f32_e32 v22, v22
	v_exp_f32_e32 v23, v23
	s_nop 0
	v_pk_add_f32 v[22:23], v[22:23], 1.0 op_sel_hi:[1,0]
	s_nop 0
	v_rcp_f32_e32 v22, v22
	v_rcp_f32_e32 v23, v23
	s_nop 0
	v_pk_mul_f32 v[18:19], v[18:19], v[22:23]
	s_nop 0
	v_cvt_pk_bf16_f32 v29, v18, v19
	v_lshl_add_u64 v[18:19], s[16:17], 0, v[158:159]
	v_lshl_add_u64 v[18:19], v[18:19], 0, v[0:1]
	global_store_dwordx4 v[18:19], v[26:29], off nt
	v_pk_mul_f32 v[18:19], v[14:15], s[30:31] op_sel_hi:[1,0]
	v_pk_mul_f32 v[14:15], v[16:17], v[130:131] op_sel_hi:[1,0]
	v_exp_f32_e32 v18, v18
	v_pk_mul_f32 v[16:17], v[14:15], s[30:31] op_sel_hi:[1,0]
	v_exp_f32_e32 v19, v19
	v_exp_f32_e32 v16, v16
	v_exp_f32_e32 v17, v17
	v_pk_mul_f32 v[12:13], v[14:15], v[12:13]
	v_pk_add_f32 v[18:19], v[18:19], 1.0 op_sel_hi:[1,0]
	v_pk_add_f32 v[16:17], v[16:17], 1.0 op_sel_hi:[1,0]
	v_rcp_f32_e32 v18, v18
	v_rcp_f32_e32 v19, v19
	v_rcp_f32_e32 v16, v16
	v_rcp_f32_e32 v17, v17
	v_pk_mul_f32 v[10:11], v[10:11], v[18:19]
	s_nop 0
	v_cvt_pk_bf16_f32 v10, v10, v11
	v_pk_mul_f32 v[12:13], v[12:13], v[16:17]
	s_nop 0
	v_cvt_pk_bf16_f32 v11, v12, v13
	v_pk_mul_f32 v[12:13], v[6:7], s[30:31] op_sel_hi:[1,0]
	s_nop 0
	v_exp_f32_e32 v12, v12
	v_exp_f32_e32 v13, v13
	s_nop 0
	v_pk_add_f32 v[12:13], v[12:13], 1.0 op_sel_hi:[1,0]
	s_nop 0
	v_rcp_f32_e32 v12, v12
	v_rcp_f32_e32 v13, v13
	s_nop 0
	v_pk_mul_f32 v[2:3], v[2:3], v[12:13]
	s_nop 0
	v_cvt_pk_bf16_f32 v12, v2, v3
	v_pk_mul_f32 v[2:3], v[8:9], v[130:131] op_sel_hi:[1,0]
	s_nop 0
	v_pk_mul_f32 v[6:7], v[2:3], s[30:31] op_sel_hi:[1,0]
	v_pk_mul_f32 v[2:3], v[2:3], v[4:5]
	v_exp_f32_e32 v6, v6
	v_exp_f32_e32 v7, v7
	s_nop 0
	v_pk_add_f32 v[6:7], v[6:7], 1.0 op_sel_hi:[1,0]
	s_nop 0
	v_rcp_f32_e32 v6, v6
	v_rcp_f32_e32 v7, v7
	s_nop 0
	v_pk_mul_f32 v[2:3], v[2:3], v[6:7]
	s_nop 0
	v_cvt_pk_bf16_f32 v13, v2, v3
	v_lshl_add_u64 v[2:3], s[16:17], 0, v[160:161]
	v_lshl_add_u64 v[2:3], v[2:3], 0, v[0:1]
	global_store_dwordx4 v[2:3], v[10:13], off nt
	s_mov_b64 s[16:17], -1
	s_cbranch_vccnz .LBB7_352
	s_andn2_b64 vcc, exec, s[50:51]
	s_cbranch_vccnz .LBB7_351
	s_branch .LBB7_351

.LBB7_434:
	s_add_i32 s75, s72, 2
	s_add_u32 s76, s16, 0x4000
	s_addc_u32 s73, s17, 0
	s_cmp_eq_u32 s3, s72
	s_cselect_b32 s72, s86, s76
	s_cselect_b32 s73, s20, s73
	s_cselect_b32 s84, s37, s29
	s_cselect_b32 s85, s87, s74
	s_add_u32 vcc_lo, s72, 0x8000
	s_addc_u32 vcc_hi, s73, 0
	s_add_i32 s76, 0, 0x10000
	v_add_u32_e32 v0, s76, v205
	s_add_i32 s91, 0, 0x14000
	ds_read_b128 v[132:135], v0
	ds_read_b128 v[136:139], v0 offset:1024
	ds_read_b128 v[140:143], v0 offset:2048
	ds_read_b128 v[144:147], v0 offset:3072
	v_add_u32_e32 v0, s91, v205
	ds_read_b128 v[148:151], v0
	ds_read_b128 v[152:155], v0 offset:1024
	ds_read_b128 v[156:159], v0 offset:2048
	ds_read_b128 v[184:187], v0 offset:3072
	s_waitcnt lgkmcnt(0)
	s_add_i32 m0, s23, 0xc000
	ds_read_b128 v[188:191], v207
	ds_read_b128 v[192:195], v207 offset:1024
	ds_read_b128 v[196:199], v207 offset:2048
	ds_read_b128 v[208:211], v207 offset:3072
	ds_read_b128 v[212:215], v207 offset:4096
	ds_read_b128 v[216:219], v207 offset:5120
	ds_read_b128 v[220:223], v207 offset:6144
	ds_read_b128 v[224:227], v207 offset:7168
	global_load_lds_dwordx4 v180, s[16:17]
	s_add_i32 m0, s23, 0xe000
	s_nop 0
	global_load_lds_dwordx4 v182, s[16:17]
	s_waitcnt vmcnt(8)
	s_waitcnt lgkmcnt(0)
	s_setprio 1
	s_barrier
	v_mfma_f32_16x16x32_bf16 v[128:131], v[132:135], v[188:191], v[128:131]
	v_mfma_f32_16x16x32_bf16 v[124:127], v[140:143], v[188:191], v[124:127]
	v_mfma_f32_16x16x32_bf16 v[120:123], v[132:135], v[196:199], v[120:123]
	v_mfma_f32_16x16x32_bf16 v[116:119], v[140:143], v[196:199], v[116:119]
	v_mfma_f32_16x16x32_bf16 v[112:115], v[132:135], v[212:215], v[112:115]
	v_mfma_f32_16x16x32_bf16 v[108:111], v[140:143], v[212:215], v[108:111]
	v_mfma_f32_16x16x32_bf16 v[104:107], v[132:135], v[220:223], v[104:107]
	v_mfma_f32_16x16x32_bf16 v[100:103], v[140:143], v[220:223], v[100:103]
	v_mfma_f32_16x16x32_bf16 v[128:131], v[136:139], v[192:195], v[128:131]
	v_mfma_f32_16x16x32_bf16 v[124:127], v[144:147], v[192:195], v[124:127]
	v_mfma_f32_16x16x32_bf16 v[120:123], v[136:139], v[208:211], v[120:123]
	v_mfma_f32_16x16x32_bf16 v[116:119], v[144:147], v[208:211], v[116:119]
	v_mfma_f32_16x16x32_bf16 v[112:115], v[136:139], v[216:219], v[112:115]
	v_mfma_f32_16x16x32_bf16 v[108:111], v[144:147], v[216:219], v[108:111]
	v_mfma_f32_16x16x32_bf16 v[104:107], v[136:139], v[224:227], v[104:107]
	v_mfma_f32_16x16x32_bf16 v[100:103], v[144:147], v[224:227], v[100:103]
	v_mfma_f32_16x16x32_bf16 v[96:99], v[148:151], v[188:191], v[96:99]
	v_mfma_f32_16x16x32_bf16 v[92:95], v[156:159], v[188:191], v[92:95]
	v_mfma_f32_16x16x32_bf16 v[88:91], v[148:151], v[196:199], v[88:91]
	v_mfma_f32_16x16x32_bf16 v[84:87], v[156:159], v[196:199], v[84:87]
	v_mfma_f32_16x16x32_bf16 v[80:83], v[148:151], v[212:215], v[80:83]
	v_mfma_f32_16x16x32_bf16 v[76:79], v[156:159], v[212:215], v[76:79]
	v_mfma_f32_16x16x32_bf16 v[72:75], v[148:151], v[220:223], v[72:75]
	v_mfma_f32_16x16x32_bf16 v[64:67], v[156:159], v[220:223], v[64:67]
	v_mfma_f32_16x16x32_bf16 v[96:99], v[152:155], v[192:195], v[96:99]
	v_mfma_f32_16x16x32_bf16 v[92:95], v[184:187], v[192:195], v[92:95]
	v_mfma_f32_16x16x32_bf16 v[88:91], v[152:155], v[208:211], v[88:91]
	v_mfma_f32_16x16x32_bf16 v[84:87], v[184:187], v[208:211], v[84:87]
	v_mfma_f32_16x16x32_bf16 v[80:83], v[152:155], v[216:219], v[80:83]
	v_mfma_f32_16x16x32_bf16 v[76:79], v[184:187], v[216:219], v[76:79]
	v_mfma_f32_16x16x32_bf16 v[72:75], v[152:155], v[224:227], v[72:75]
	v_mfma_f32_16x16x32_bf16 v[64:67], v[184:187], v[224:227], v[64:67]
	s_barrier
	s_setprio 0
	s_add_i32 s76, s76, s4
	s_mov_b32 m0, s76
	ds_read_b128 v[188:191], v207 offset:16384
	ds_read_b128 v[192:195], v207 offset:17408
	ds_read_b128 v[196:199], v207 offset:18432
	ds_read_b128 v[208:211], v207 offset:19456
	ds_read_b128 v[212:215], v207 offset:20480
	ds_read_b128 v[216:219], v207 offset:21504
	ds_read_b128 v[220:223], v207 offset:22528
	ds_read_b128 v[224:227], v207 offset:23552
	global_load_lds_dwordx4 v176, s[84:85]
	s_add_i32 m0, s76, 0x2000
	s_add_u32 s76, s84, 0x4000
	s_addc_u32 s77, s85, 0
	s_add_i32 s91, s91, s4
	global_load_lds_dwordx4 v160, s[84:85]
	s_mov_b32 m0, s91
	s_nop 0
	global_load_lds_dwordx4 v176, s[76:77]
	s_add_i32 m0, s91, 0x2000
	s_nop 0
	global_load_lds_dwordx4 v160, s[76:77]
	s_mov_b32 m0, s23
	s_nop 0
	global_load_lds_dwordx4 v178, s[72:73]
	s_mov_b32 m0, s31
	s_nop 0
	global_load_lds_dwordx4 v174, s[72:73]
	s_waitcnt vmcnt(8)
	s_waitcnt lgkmcnt(0)
	s_setprio 1
	s_barrier
	v_mfma_f32_16x16x32_bf16 v[68:71], v[132:135], v[188:191], v[68:71]
	v_mfma_f32_16x16x32_bf16 v[60:63], v[140:143], v[188:191], v[60:63]
	v_mfma_f32_16x16x32_bf16 v[56:59], v[132:135], v[196:199], v[56:59]
	v_mfma_f32_16x16x32_bf16 v[52:55], v[140:143], v[196:199], v[52:55]
	v_mfma_f32_16x16x32_bf16 v[48:51], v[132:135], v[212:215], v[48:51]
	v_mfma_f32_16x16x32_bf16 v[44:47], v[140:143], v[212:215], v[44:47]
	v_mfma_f32_16x16x32_bf16 v[40:43], v[132:135], v[220:223], v[40:43]
	v_mfma_f32_16x16x32_bf16 v[36:39], v[140:143], v[220:223], v[36:39]
	v_mfma_f32_16x16x32_bf16 v[68:71], v[136:139], v[192:195], v[68:71]
	v_mfma_f32_16x16x32_bf16 v[60:63], v[144:147], v[192:195], v[60:63]
	v_mfma_f32_16x16x32_bf16 v[56:59], v[136:139], v[208:211], v[56:59]
	v_mfma_f32_16x16x32_bf16 v[52:55], v[144:147], v[208:211], v[52:55]
	v_mfma_f32_16x16x32_bf16 v[48:51], v[136:139], v[216:219], v[48:51]
	v_mfma_f32_16x16x32_bf16 v[44:47], v[144:147], v[216:219], v[44:47]
	v_mfma_f32_16x16x32_bf16 v[40:43], v[136:139], v[224:227], v[40:43]
	v_mfma_f32_16x16x32_bf16 v[36:39], v[144:147], v[224:227], v[36:39]
	v_mfma_f32_16x16x32_bf16 v[32:35], v[148:151], v[188:191], v[32:35]
	v_mfma_f32_16x16x32_bf16 v[28:31], v[156:159], v[188:191], v[28:31]
	v_mfma_f32_16x16x32_bf16 v[24:27], v[148:151], v[196:199], v[24:27]
	v_mfma_f32_16x16x32_bf16 v[20:23], v[156:159], v[196:199], v[20:23]
	v_mfma_f32_16x16x32_bf16 v[16:19], v[148:151], v[212:215], v[16:19]
	v_mfma_f32_16x16x32_bf16 v[12:15], v[156:159], v[212:215], v[12:15]
	v_mfma_f32_16x16x32_bf16 v[8:11], v[148:151], v[220:223], v[8:11]
	v_mfma_f32_16x16x32_bf16 v[2:5], v[156:159], v[220:223], v[4:7]
	v_mfma_f32_16x16x32_bf16 v[32:35], v[152:155], v[192:195], v[32:35]
	v_mfma_f32_16x16x32_bf16 v[28:31], v[184:187], v[192:195], v[28:31]
	v_mfma_f32_16x16x32_bf16 v[24:27], v[152:155], v[208:211], v[24:27]
	v_mfma_f32_16x16x32_bf16 v[20:23], v[184:187], v[208:211], v[20:23]
	v_mfma_f32_16x16x32_bf16 v[16:19], v[152:155], v[216:219], v[16:19]
	v_mfma_f32_16x16x32_bf16 v[12:15], v[184:187], v[216:219], v[12:15]
	v_mfma_f32_16x16x32_bf16 v[8:11], v[152:155], v[224:227], v[8:11]
	v_mfma_f32_16x16x32_bf16 v[2:5], v[184:187], v[224:227], v[2:5]
	s_barrier
	s_setprio 0
	s_add_i32 s76, 0, 0x18000
	v_add_u32_e32 v0, s76, v205
	s_add_i32 s77, 0, 0x1c000
	ds_read_b128 v[132:135], v0
	ds_read_b128 v[136:139], v0 offset:1024
	ds_read_b128 v[140:143], v0 offset:2048
	ds_read_b128 v[144:147], v0 offset:3072
	v_add_u32_e32 v0, s77, v205
	ds_read_b128 v[148:151], v0
	ds_read_b128 v[152:155], v0 offset:1024
	ds_read_b128 v[156:159], v0 offset:2048
	ds_read_b128 v[184:187], v0 offset:3072
	s_add_u32 s72, s72, 0x4000
	s_addc_u32 s73, s73, 0
	s_mov_b32 m0, s33
	ds_read_b128 v[188:191], v207 offset:32768
	ds_read_b128 v[192:195], v207 offset:33792
	ds_read_b128 v[196:199], v207 offset:34816
	ds_read_b128 v[208:211], v207 offset:35840
	ds_read_b128 v[212:215], v207 offset:36864
	ds_read_b128 v[216:219], v207 offset:37888
	ds_read_b128 v[220:223], v207 offset:38912
	ds_read_b128 v[224:227], v207 offset:39936
	global_load_lds_dwordx4 v178, s[72:73]
	s_mov_b32 m0, s93
	s_nop 0
	global_load_lds_dwordx4 v174, s[72:73]
	s_waitcnt vmcnt(8)
	s_waitcnt lgkmcnt(0)
	s_setprio 1
	s_barrier
	v_mfma_f32_16x16x32_bf16 v[128:131], v[132:135], v[188:191], v[128:131]
	v_mfma_f32_16x16x32_bf16 v[124:127], v[140:143], v[188:191], v[124:127]
	v_mfma_f32_16x16x32_bf16 v[120:123], v[132:135], v[196:199], v[120:123]
	v_mfma_f32_16x16x32_bf16 v[116:119], v[140:143], v[196:199], v[116:119]
	v_mfma_f32_16x16x32_bf16 v[112:115], v[132:135], v[212:215], v[112:115]
	v_mfma_f32_16x16x32_bf16 v[108:111], v[140:143], v[212:215], v[108:111]
	v_mfma_f32_16x16x32_bf16 v[104:107], v[132:135], v[220:223], v[104:107]
	v_mfma_f32_16x16x32_bf16 v[100:103], v[140:143], v[220:223], v[100:103]
	v_mfma_f32_16x16x32_bf16 v[128:131], v[136:139], v[192:195], v[128:131]
	v_mfma_f32_16x16x32_bf16 v[124:127], v[144:147], v[192:195], v[124:127]
	v_mfma_f32_16x16x32_bf16 v[120:123], v[136:139], v[208:211], v[120:123]
	v_mfma_f32_16x16x32_bf16 v[116:119], v[144:147], v[208:211], v[116:119]
	v_mfma_f32_16x16x32_bf16 v[112:115], v[136:139], v[216:219], v[112:115]
	v_mfma_f32_16x16x32_bf16 v[108:111], v[144:147], v[216:219], v[108:111]
	v_mfma_f32_16x16x32_bf16 v[104:107], v[136:139], v[224:227], v[104:107]
	v_mfma_f32_16x16x32_bf16 v[100:103], v[144:147], v[224:227], v[100:103]
	v_mfma_f32_16x16x32_bf16 v[96:99], v[148:151], v[188:191], v[96:99]
	v_mfma_f32_16x16x32_bf16 v[92:95], v[156:159], v[188:191], v[92:95]
	v_mfma_f32_16x16x32_bf16 v[88:91], v[148:151], v[196:199], v[88:91]
	v_mfma_f32_16x16x32_bf16 v[84:87], v[156:159], v[196:199], v[84:87]
	v_mfma_f32_16x16x32_bf16 v[80:83], v[148:151], v[212:215], v[80:83]
	v_mfma_f32_16x16x32_bf16 v[76:79], v[156:159], v[212:215], v[76:79]
	v_mfma_f32_16x16x32_bf16 v[72:75], v[148:151], v[220:223], v[72:75]
	v_mfma_f32_16x16x32_bf16 v[64:67], v[156:159], v[220:223], v[64:67]
	v_mfma_f32_16x16x32_bf16 v[96:99], v[152:155], v[192:195], v[96:99]
	v_mfma_f32_16x16x32_bf16 v[92:95], v[184:187], v[192:195], v[92:95]
	v_mfma_f32_16x16x32_bf16 v[88:91], v[152:155], v[208:211], v[88:91]
	v_mfma_f32_16x16x32_bf16 v[84:87], v[184:187], v[208:211], v[84:87]
	v_mfma_f32_16x16x32_bf16 v[80:83], v[152:155], v[216:219], v[80:83]
	v_mfma_f32_16x16x32_bf16 v[76:79], v[184:187], v[216:219], v[76:79]
	v_mfma_f32_16x16x32_bf16 v[72:75], v[152:155], v[224:227], v[72:75]
	v_mfma_f32_16x16x32_bf16 v[64:67], v[184:187], v[224:227], v[64:67]
	s_barrier
	s_setprio 0
	s_add_u32 s72, s84, 0x8000
	s_addc_u32 s73, s85, 0
	s_add_i32 s76, s76, s4
	s_mov_b32 m0, s76
	ds_read_b128 v[188:191], v207 offset:49152
	ds_read_b128 v[192:195], v207 offset:50176
	ds_read_b128 v[196:199], v207 offset:51200
	ds_read_b128 v[208:211], v207 offset:52224
	ds_read_b128 v[212:215], v207 offset:53248
	ds_read_b128 v[216:219], v207 offset:54272
	ds_read_b128 v[220:223], v207 offset:55296
	ds_read_b128 v[224:227], v207 offset:56320
	global_load_lds_dwordx4 v176, s[72:73]
	s_add_i32 m0, s76, 0x2000
	v_lshl_add_u64 v[6:7], s[72:73], 0, v[160:161]
	s_add_u32 s72, s84, 0xc000
	s_addc_u32 s73, s85, 0
	s_add_i32 s76, s77, s4
	global_load_lds_dwordx4 v[6:7], off
	s_mov_b32 m0, s76
	s_nop 0
	global_load_lds_dwordx4 v176, s[72:73]
	s_add_i32 m0, s76, 0x2000
	s_nop 0
	global_load_lds_dwordx4 v160, s[72:73]
	s_mov_b32 m0, s97
	s_nop 0
	global_load_lds_dwordx4 v178, vcc
	s_mov_b32 m0, s38
	s_nop 0
	global_load_lds_dwordx4 v174, vcc
	s_waitcnt vmcnt(8)
	s_waitcnt lgkmcnt(0)
	s_setprio 1
	s_barrier
	v_mfma_f32_16x16x32_bf16 v[68:71], v[132:135], v[188:191], v[68:71]
	v_mfma_f32_16x16x32_bf16 v[60:63], v[140:143], v[188:191], v[60:63]
	v_mfma_f32_16x16x32_bf16 v[56:59], v[132:135], v[196:199], v[56:59]
	v_mfma_f32_16x16x32_bf16 v[52:55], v[140:143], v[196:199], v[52:55]
	v_mfma_f32_16x16x32_bf16 v[48:51], v[132:135], v[212:215], v[48:51]
	v_mfma_f32_16x16x32_bf16 v[44:47], v[140:143], v[212:215], v[44:47]
	v_mfma_f32_16x16x32_bf16 v[40:43], v[132:135], v[220:223], v[40:43]
	v_mfma_f32_16x16x32_bf16 v[36:39], v[140:143], v[220:223], v[36:39]
	v_mfma_f32_16x16x32_bf16 v[68:71], v[136:139], v[192:195], v[68:71]
	v_mfma_f32_16x16x32_bf16 v[60:63], v[144:147], v[192:195], v[60:63]
	v_mfma_f32_16x16x32_bf16 v[56:59], v[136:139], v[208:211], v[56:59]
	v_mfma_f32_16x16x32_bf16 v[52:55], v[144:147], v[208:211], v[52:55]
	v_mfma_f32_16x16x32_bf16 v[48:51], v[136:139], v[216:219], v[48:51]
	v_mfma_f32_16x16x32_bf16 v[44:47], v[144:147], v[216:219], v[44:47]
	v_mfma_f32_16x16x32_bf16 v[40:43], v[136:139], v[224:227], v[40:43]
	v_mfma_f32_16x16x32_bf16 v[36:39], v[144:147], v[224:227], v[36:39]
	v_mfma_f32_16x16x32_bf16 v[32:35], v[148:151], v[188:191], v[32:35]
	v_mfma_f32_16x16x32_bf16 v[28:31], v[156:159], v[188:191], v[28:31]
	v_mfma_f32_16x16x32_bf16 v[24:27], v[148:151], v[196:199], v[24:27]
	v_mfma_f32_16x16x32_bf16 v[20:23], v[156:159], v[196:199], v[20:23]
	v_mfma_f32_16x16x32_bf16 v[16:19], v[148:151], v[212:215], v[16:19]
	v_mfma_f32_16x16x32_bf16 v[12:15], v[156:159], v[212:215], v[12:15]
	v_mfma_f32_16x16x32_bf16 v[6:9], v[148:151], v[220:223], v[8:11]
	v_mfma_f32_16x16x32_bf16 v[2:5], v[156:159], v[220:223], v[2:5]
	v_mfma_f32_16x16x32_bf16 v[32:35], v[152:155], v[192:195], v[32:35]
	v_mfma_f32_16x16x32_bf16 v[28:31], v[184:187], v[192:195], v[28:31]
	v_mfma_f32_16x16x32_bf16 v[24:27], v[152:155], v[208:211], v[24:27]
	v_mfma_f32_16x16x32_bf16 v[20:23], v[184:187], v[208:211], v[20:23]
	v_mfma_f32_16x16x32_bf16 v[16:19], v[152:155], v[216:219], v[16:19]
	v_mfma_f32_16x16x32_bf16 v[12:15], v[184:187], v[216:219], v[12:15]
	v_mfma_f32_16x16x32_bf16 v[8:11], v[152:155], v[224:227], v[6:9]
	v_mfma_f32_16x16x32_bf16 v[4:7], v[184:187], v[224:227], v[2:5]
	s_barrier
	s_setprio 0
	s_add_u32 s29, s29, 0x10000
	s_addc_u32 s74, s74, 0
	s_add_u32 s16, s16, 0x10000
	s_addc_u32 s17, s17, 0
	s_cmp_ge_i32 s75, s39
	s_mov_b32 s72, s75
	s_cbranch_scc0 .LBB7_434

.LBB7_523:
	s_add_i32 s56, s42, 2
	s_add_u32 s29, s16, 0xfffc0080
	s_addc_u32 s37, s17, -1
	s_add_i32 s57, 0, 0x10000
	s_cmp_eq_u32 s84, s42
	s_cselect_b32 s45, s13, s37
	s_cselect_b32 s44, s15, s29
	v_add_u32_e32 v0, s57, v195
	s_cselect_b32 s43, s38, s49
	s_cselect_b32 s42, s39, s48
	s_add_i32 s29, 0, 0x14000
	ds_read_b128 v[130:133], v0
	ds_read_b128 v[150:153], v0 offset:1024
	ds_read_b128 v[154:157], v0 offset:2048
	ds_read_b128 v[158:161], v0 offset:3072
	v_add_u32_e32 v0, s29, v195
	ds_read_b128 v[174:177], v0
	ds_read_b128 v[178:181], v0 offset:1024
	ds_read_b128 v[182:185], v0 offset:2048
	ds_read_b128 v[186:189], v0 offset:3072
	s_add_i32 m0, s5, 0xc000
	ds_read_b128 v[190:193], v196
	ds_read_b128 v[204:207], v196 offset:1024
	ds_read_b128 v[208:211], v196 offset:2048
	ds_read_b128 v[212:215], v196 offset:3072
	ds_read_b128 v[216:219], v196 offset:4096
	ds_read_b128 v[220:223], v196 offset:5120
	ds_read_b128 v[224:227], v196 offset:6144
	ds_read_b128 v[228:231], v196 offset:7168
	global_load_lds_dwordx4 v146, s[16:17]
	s_add_i32 m0, s5, 0xe000
	s_nop 0
	global_load_lds_dwordx4 v148, s[16:17]
	s_waitcnt vmcnt(8)
	s_waitcnt lgkmcnt(0)
	s_setprio 1
	s_barrier
	v_mfma_f32_16x16x32_bf16 v[126:129], v[130:133], v[190:193], v[126:129]
	v_mfma_f32_16x16x32_bf16 v[122:125], v[154:157], v[190:193], v[122:125]
	v_mfma_f32_16x16x32_bf16 v[110:113], v[130:133], v[208:211], v[110:113]
	v_mfma_f32_16x16x32_bf16 v[106:109], v[154:157], v[208:211], v[106:109]
	v_mfma_f32_16x16x32_bf16 v[94:97], v[130:133], v[216:219], v[94:97]
	v_mfma_f32_16x16x32_bf16 v[90:93], v[154:157], v[216:219], v[90:93]
	v_mfma_f32_16x16x32_bf16 v[78:81], v[130:133], v[224:227], v[78:81]
	v_mfma_f32_16x16x32_bf16 v[74:77], v[154:157], v[224:227], v[74:77]
	v_mfma_f32_16x16x32_bf16 v[126:129], v[150:153], v[204:207], v[126:129]
	v_mfma_f32_16x16x32_bf16 v[122:125], v[158:161], v[204:207], v[122:125]
	v_mfma_f32_16x16x32_bf16 v[110:113], v[150:153], v[212:215], v[110:113]
	v_mfma_f32_16x16x32_bf16 v[106:109], v[158:161], v[212:215], v[106:109]
	v_mfma_f32_16x16x32_bf16 v[94:97], v[150:153], v[220:223], v[94:97]
	v_mfma_f32_16x16x32_bf16 v[90:93], v[158:161], v[220:223], v[90:93]
	v_mfma_f32_16x16x32_bf16 v[78:81], v[150:153], v[228:231], v[78:81]
	v_mfma_f32_16x16x32_bf16 v[74:77], v[158:161], v[228:231], v[74:77]
	v_mfma_f32_16x16x32_bf16 v[118:121], v[174:177], v[190:193], v[118:121]
	v_mfma_f32_16x16x32_bf16 v[114:117], v[182:185], v[190:193], v[114:117]
	v_mfma_f32_16x16x32_bf16 v[102:105], v[174:177], v[208:211], v[102:105]
	v_mfma_f32_16x16x32_bf16 v[98:101], v[182:185], v[208:211], v[98:101]
	v_mfma_f32_16x16x32_bf16 v[86:89], v[174:177], v[216:219], v[86:89]
	v_mfma_f32_16x16x32_bf16 v[82:85], v[182:185], v[216:219], v[82:85]
	v_mfma_f32_16x16x32_bf16 v[70:73], v[174:177], v[224:227], v[70:73]
	v_mfma_f32_16x16x32_bf16 v[66:69], v[182:185], v[224:227], v[66:69]
	v_mfma_f32_16x16x32_bf16 v[118:121], v[178:181], v[204:207], v[118:121]
	v_mfma_f32_16x16x32_bf16 v[114:117], v[186:189], v[204:207], v[114:117]
	v_mfma_f32_16x16x32_bf16 v[102:105], v[178:181], v[212:215], v[102:105]
	v_mfma_f32_16x16x32_bf16 v[98:101], v[186:189], v[212:215], v[98:101]
	v_mfma_f32_16x16x32_bf16 v[86:89], v[178:181], v[220:223], v[86:89]
	v_mfma_f32_16x16x32_bf16 v[82:85], v[186:189], v[220:223], v[82:85]
	v_mfma_f32_16x16x32_bf16 v[70:73], v[178:181], v[228:231], v[70:73]
	v_mfma_f32_16x16x32_bf16 v[66:69], v[186:189], v[228:231], v[66:69]
	s_barrier
	s_setprio 0
	s_add_i32 s37, s57, s4
	v_lshl_add_u64 v[170:171], s[42:43], 0, v[138:139]
	s_mov_b32 m0, s37
	ds_read_b128 v[190:193], v196 offset:16384
	ds_read_b128 v[204:207], v196 offset:17408
	ds_read_b128 v[208:211], v196 offset:18432
	ds_read_b128 v[212:215], v196 offset:19456
	ds_read_b128 v[216:219], v196 offset:20480
	ds_read_b128 v[220:223], v196 offset:21504
	ds_read_b128 v[224:227], v196 offset:22528
	ds_read_b128 v[228:231], v196 offset:23552
	global_load_lds_dwordx4 v[170:171], off
	s_add_i32 m0, s37, 0x2000
	s_add_u32 s74, s42, 0x40000
	v_lshl_add_u64 v[172:173], s[42:43], 0, v[134:135]
	s_addc_u32 s75, s43, 0
	s_add_i32 s29, s29, s4
	global_load_lds_dwordx4 v[172:173], off
	s_mov_b32 m0, s29
	v_lshl_add_u64 v[232:233], s[44:45], 0, v[136:137]
	global_load_lds_dwordx4 v138, s[74:75]
	s_add_i32 m0, s29, 0x2000
	s_nop 0
	global_load_lds_dwordx4 v134, s[74:75]
	v_lshl_add_u64 v[198:199], s[44:45], 0, v[140:141]
	s_mov_b32 m0, s5
	s_nop 0
	global_load_lds_dwordx4 v[198:199], off
	s_mov_b32 m0, s20
	s_nop 0
	global_load_lds_dwordx4 v[232:233], off
	s_waitcnt vmcnt(8)
	s_waitcnt lgkmcnt(0)
	s_setprio 1
	s_barrier
	v_mfma_f32_16x16x32_bf16 v[62:65], v[130:133], v[190:193], v[62:65]
	v_mfma_f32_16x16x32_bf16 v[58:61], v[154:157], v[190:193], v[58:61]
	v_mfma_f32_16x16x32_bf16 v[46:49], v[130:133], v[208:211], v[46:49]
	v_mfma_f32_16x16x32_bf16 v[42:45], v[154:157], v[208:211], v[42:45]
	v_mfma_f32_16x16x32_bf16 v[30:33], v[130:133], v[216:219], v[30:33]
	v_mfma_f32_16x16x32_bf16 v[26:29], v[154:157], v[216:219], v[26:29]
	v_mfma_f32_16x16x32_bf16 v[14:17], v[130:133], v[224:227], v[14:17]
	v_mfma_f32_16x16x32_bf16 v[10:13], v[154:157], v[224:227], v[10:13]
	v_mfma_f32_16x16x32_bf16 v[62:65], v[150:153], v[204:207], v[62:65]
	v_mfma_f32_16x16x32_bf16 v[58:61], v[158:161], v[204:207], v[58:61]
	v_mfma_f32_16x16x32_bf16 v[46:49], v[150:153], v[212:215], v[46:49]
	v_mfma_f32_16x16x32_bf16 v[42:45], v[158:161], v[212:215], v[42:45]
	v_mfma_f32_16x16x32_bf16 v[30:33], v[150:153], v[220:223], v[30:33]
	v_mfma_f32_16x16x32_bf16 v[26:29], v[158:161], v[220:223], v[26:29]
	v_mfma_f32_16x16x32_bf16 v[14:17], v[150:153], v[228:231], v[14:17]
	v_mfma_f32_16x16x32_bf16 v[10:13], v[158:161], v[228:231], v[10:13]
	v_mfma_f32_16x16x32_bf16 v[54:57], v[174:177], v[190:193], v[54:57]
	v_mfma_f32_16x16x32_bf16 v[50:53], v[182:185], v[190:193], v[50:53]
	v_mfma_f32_16x16x32_bf16 v[38:41], v[174:177], v[208:211], v[38:41]
	v_mfma_f32_16x16x32_bf16 v[34:37], v[182:185], v[208:211], v[34:37]
	v_mfma_f32_16x16x32_bf16 v[22:25], v[174:177], v[216:219], v[22:25]
	v_mfma_f32_16x16x32_bf16 v[18:21], v[182:185], v[216:219], v[18:21]
	v_mfma_f32_16x16x32_bf16 v[6:9], v[174:177], v[224:227], v[6:9]
	v_mfma_f32_16x16x32_bf16 v[2:5], v[182:185], v[224:227], v[2:5]
	v_mfma_f32_16x16x32_bf16 v[54:57], v[178:181], v[204:207], v[54:57]
	v_mfma_f32_16x16x32_bf16 v[50:53], v[186:189], v[204:207], v[50:53]
	v_mfma_f32_16x16x32_bf16 v[38:41], v[178:181], v[212:215], v[38:41]
	v_mfma_f32_16x16x32_bf16 v[34:37], v[186:189], v[212:215], v[34:37]
	v_mfma_f32_16x16x32_bf16 v[22:25], v[178:181], v[220:223], v[22:25]
	v_mfma_f32_16x16x32_bf16 v[18:21], v[186:189], v[220:223], v[18:21]
	v_mfma_f32_16x16x32_bf16 v[6:9], v[178:181], v[228:231], v[6:9]
	v_mfma_f32_16x16x32_bf16 v[2:5], v[186:189], v[228:231], v[2:5]
	s_barrier
	s_setprio 0
	s_add_i32 s29, 0, 0x18000
	v_add_u32_e32 v0, s29, v195
	s_add_i32 s37, 0, 0x1c000
	ds_read_b128 v[130:133], v0
	ds_read_b128 v[150:153], v0 offset:1024
	ds_read_b128 v[154:157], v0 offset:2048
	ds_read_b128 v[158:161], v0 offset:3072
	v_add_u32_e32 v0, s37, v195
	ds_read_b128 v[174:177], v0
	ds_read_b128 v[178:181], v0 offset:1024
	ds_read_b128 v[182:185], v0 offset:2048
	ds_read_b128 v[186:189], v0 offset:3072
	s_add_u32 s44, s44, 0x40000
	s_addc_u32 s45, s45, 0
	s_mov_b32 m0, s22
	ds_read_b128 v[190:193], v196 offset:32768
	ds_read_b128 v[204:207], v196 offset:33792
	ds_read_b128 v[208:211], v196 offset:34816
	ds_read_b128 v[212:215], v196 offset:35840
	ds_read_b128 v[216:219], v196 offset:36864
	ds_read_b128 v[220:223], v196 offset:37888
	ds_read_b128 v[224:227], v196 offset:38912
	ds_read_b128 v[228:231], v196 offset:39936
	global_load_lds_dwordx4 v140, s[44:45]
	s_mov_b32 m0, s23
	s_nop 0
	global_load_lds_dwordx4 v136, s[44:45]
	s_waitcnt vmcnt(8)
	s_waitcnt lgkmcnt(0)
	s_setprio 1
	s_barrier
	v_mfma_f32_16x16x32_bf16 v[126:129], v[130:133], v[190:193], v[126:129]
	v_mfma_f32_16x16x32_bf16 v[122:125], v[154:157], v[190:193], v[122:125]
	v_mfma_f32_16x16x32_bf16 v[110:113], v[130:133], v[208:211], v[110:113]
	v_mfma_f32_16x16x32_bf16 v[106:109], v[154:157], v[208:211], v[106:109]
	v_mfma_f32_16x16x32_bf16 v[94:97], v[130:133], v[216:219], v[94:97]
	v_mfma_f32_16x16x32_bf16 v[90:93], v[154:157], v[216:219], v[90:93]
	v_mfma_f32_16x16x32_bf16 v[78:81], v[130:133], v[224:227], v[78:81]
	v_mfma_f32_16x16x32_bf16 v[74:77], v[154:157], v[224:227], v[74:77]
	v_mfma_f32_16x16x32_bf16 v[126:129], v[150:153], v[204:207], v[126:129]
	v_mfma_f32_16x16x32_bf16 v[122:125], v[158:161], v[204:207], v[122:125]
	v_mfma_f32_16x16x32_bf16 v[110:113], v[150:153], v[212:215], v[110:113]
	v_mfma_f32_16x16x32_bf16 v[106:109], v[158:161], v[212:215], v[106:109]
	v_mfma_f32_16x16x32_bf16 v[94:97], v[150:153], v[220:223], v[94:97]
	v_mfma_f32_16x16x32_bf16 v[90:93], v[158:161], v[220:223], v[90:93]
	v_mfma_f32_16x16x32_bf16 v[78:81], v[150:153], v[228:231], v[78:81]
	v_mfma_f32_16x16x32_bf16 v[74:77], v[158:161], v[228:231], v[74:77]
	v_mfma_f32_16x16x32_bf16 v[118:121], v[174:177], v[190:193], v[118:121]
	v_mfma_f32_16x16x32_bf16 v[114:117], v[182:185], v[190:193], v[114:117]
	v_mfma_f32_16x16x32_bf16 v[102:105], v[174:177], v[208:211], v[102:105]
	v_mfma_f32_16x16x32_bf16 v[98:101], v[182:185], v[208:211], v[98:101]
	v_mfma_f32_16x16x32_bf16 v[86:89], v[174:177], v[216:219], v[86:89]
	v_mfma_f32_16x16x32_bf16 v[82:85], v[182:185], v[216:219], v[82:85]
	v_mfma_f32_16x16x32_bf16 v[70:73], v[174:177], v[224:227], v[70:73]
	v_mfma_f32_16x16x32_bf16 v[66:69], v[182:185], v[224:227], v[66:69]
	v_mfma_f32_16x16x32_bf16 v[118:121], v[178:181], v[204:207], v[118:121]
	v_mfma_f32_16x16x32_bf16 v[114:117], v[186:189], v[204:207], v[114:117]
	v_mfma_f32_16x16x32_bf16 v[102:105], v[178:181], v[212:215], v[102:105]
	v_mfma_f32_16x16x32_bf16 v[98:101], v[186:189], v[212:215], v[98:101]
	v_mfma_f32_16x16x32_bf16 v[86:89], v[178:181], v[220:223], v[86:89]
	v_mfma_f32_16x16x32_bf16 v[82:85], v[186:189], v[220:223], v[82:85]
	v_mfma_f32_16x16x32_bf16 v[70:73], v[178:181], v[228:231], v[70:73]
	v_mfma_f32_16x16x32_bf16 v[66:69], v[186:189], v[228:231], v[66:69]
	s_barrier
	s_setprio 0
	s_add_i32 s29, s29, s4
	v_lshl_add_u64 v[170:171], v[170:171], 0, s[24:25]
	s_mov_b32 m0, s29
	ds_read_b128 v[190:193], v196 offset:49152
	ds_read_b128 v[204:207], v196 offset:50176
	ds_read_b128 v[208:211], v196 offset:51200
	ds_read_b128 v[212:215], v196 offset:52224
	ds_read_b128 v[216:219], v196 offset:53248
	ds_read_b128 v[220:223], v196 offset:54272
	ds_read_b128 v[224:227], v196 offset:55296
	ds_read_b128 v[228:231], v196 offset:56320
	global_load_lds_dwordx4 v[170:171], off
	s_add_i32 m0, s29, 0x2000
	s_add_u32 s42, s42, 0x40080
	v_lshl_add_u64 v[170:171], v[172:173], 0, s[24:25]
	s_addc_u32 s43, s43, 0
	s_add_i32 s29, s37, s4
	global_load_lds_dwordx4 v[170:171], off
	s_mov_b32 m0, s29
	s_nop 0
	global_load_lds_dwordx4 v138, s[42:43]
	s_add_i32 m0, s29, 0x2000
	s_nop 0
	global_load_lds_dwordx4 v134, s[42:43]
	v_lshl_add_u64 v[170:171], v[198:199], 0, s[24:25]
	s_mov_b32 m0, s33
	s_nop 0
	global_load_lds_dwordx4 v[170:171], off
	v_lshl_add_u64 v[170:171], v[232:233], 0, s[24:25]
	s_mov_b32 m0, s72
	s_nop 0
	global_load_lds_dwordx4 v[170:171], off
	s_waitcnt vmcnt(8)
	s_waitcnt lgkmcnt(0)
	s_setprio 1
	s_barrier
	v_mfma_f32_16x16x32_bf16 v[62:65], v[130:133], v[190:193], v[62:65]
	v_mfma_f32_16x16x32_bf16 v[58:61], v[154:157], v[190:193], v[58:61]
	v_mfma_f32_16x16x32_bf16 v[46:49], v[130:133], v[208:211], v[46:49]
	v_mfma_f32_16x16x32_bf16 v[42:45], v[154:157], v[208:211], v[42:45]
	v_mfma_f32_16x16x32_bf16 v[30:33], v[130:133], v[216:219], v[30:33]
	v_mfma_f32_16x16x32_bf16 v[26:29], v[154:157], v[216:219], v[26:29]
	v_mfma_f32_16x16x32_bf16 v[14:17], v[130:133], v[224:227], v[14:17]
	v_mfma_f32_16x16x32_bf16 v[10:13], v[154:157], v[224:227], v[10:13]
	v_mfma_f32_16x16x32_bf16 v[62:65], v[150:153], v[204:207], v[62:65]
	v_mfma_f32_16x16x32_bf16 v[58:61], v[158:161], v[204:207], v[58:61]
	v_mfma_f32_16x16x32_bf16 v[46:49], v[150:153], v[212:215], v[46:49]
	v_mfma_f32_16x16x32_bf16 v[42:45], v[158:161], v[212:215], v[42:45]
	v_mfma_f32_16x16x32_bf16 v[30:33], v[150:153], v[220:223], v[30:33]
	v_mfma_f32_16x16x32_bf16 v[26:29], v[158:161], v[220:223], v[26:29]
	v_mfma_f32_16x16x32_bf16 v[14:17], v[150:153], v[228:231], v[14:17]
	v_mfma_f32_16x16x32_bf16 v[10:13], v[158:161], v[228:231], v[10:13]
	v_mfma_f32_16x16x32_bf16 v[54:57], v[174:177], v[190:193], v[54:57]
	v_mfma_f32_16x16x32_bf16 v[50:53], v[182:185], v[190:193], v[50:53]
	v_mfma_f32_16x16x32_bf16 v[38:41], v[174:177], v[208:211], v[38:41]
	v_mfma_f32_16x16x32_bf16 v[34:37], v[182:185], v[208:211], v[34:37]
	v_mfma_f32_16x16x32_bf16 v[22:25], v[174:177], v[216:219], v[22:25]
	v_mfma_f32_16x16x32_bf16 v[18:21], v[182:185], v[216:219], v[18:21]
	v_mfma_f32_16x16x32_bf16 v[6:9], v[174:177], v[224:227], v[6:9]
	v_mfma_f32_16x16x32_bf16 v[2:5], v[182:185], v[224:227], v[2:5]
	v_mfma_f32_16x16x32_bf16 v[54:57], v[178:181], v[204:207], v[54:57]
	v_mfma_f32_16x16x32_bf16 v[50:53], v[186:189], v[204:207], v[50:53]
	v_mfma_f32_16x16x32_bf16 v[38:41], v[178:181], v[212:215], v[38:41]
	v_mfma_f32_16x16x32_bf16 v[34:37], v[186:189], v[212:215], v[34:37]
	v_mfma_f32_16x16x32_bf16 v[22:25], v[178:181], v[220:223], v[22:25]
	v_mfma_f32_16x16x32_bf16 v[18:21], v[186:189], v[220:223], v[18:21]
	v_mfma_f32_16x16x32_bf16 v[6:9], v[178:181], v[228:231], v[6:9]
	v_mfma_f32_16x16x32_bf16 v[2:5], v[186:189], v[228:231], v[2:5]
	s_barrier
	s_setprio 0
	s_add_u32 s16, s16, 0x100
	s_addc_u32 s17, s17, 0
	s_add_u32 s48, s48, 0x100
	s_addc_u32 s49, s49, 0
	s_cmp_ge_i32 s56, s3
	s_mov_b32 s42, s56
	s_cbranch_scc0 .LBB7_523
	s_mov_b32 s56, s61
	s_and_b64 vcc, exec, s[6:7]
	s_cbranch_vccz .LBB7_526

.LBB7_1104:
	s_add_i32 s74, s72, 2
	s_add_u32 s75, vcc_lo, 0xfffc0080
	s_addc_u32 s73, vcc_hi, -1
	s_add_i32 s76, 0, 0x10000
	s_cmp_eq_u32 s39, s72
	s_cselect_b32 s73, s19, s73
	s_cselect_b32 s72, s20, s75
	v_add_u32_e32 v0, s76, v205
	s_cselect_b32 s85, s28, s49
	s_cselect_b32 s84, s29, s37
	s_add_i32 s75, 0, 0x14000
	ds_read_b128 v[132:135], v0
	ds_read_b128 v[136:139], v0 offset:1024
	ds_read_b128 v[140:143], v0 offset:2048
	ds_read_b128 v[144:147], v0 offset:3072
	v_add_u32_e32 v0, s75, v205
	ds_read_b128 v[148:151], v0
	ds_read_b128 v[152:155], v0 offset:1024
	ds_read_b128 v[156:159], v0 offset:2048
	ds_read_b128 v[184:187], v0 offset:3072
	s_waitcnt lgkmcnt(0)
	s_add_i32 m0, s5, 0xc000
	ds_read_b128 v[188:191], v207
	ds_read_b128 v[192:195], v207 offset:1024
	ds_read_b128 v[196:199], v207 offset:2048
	ds_read_b128 v[208:211], v207 offset:3072
	ds_read_b128 v[212:215], v207 offset:4096
	ds_read_b128 v[216:219], v207 offset:5120
	ds_read_b128 v[220:223], v207 offset:6144
	ds_read_b128 v[224:227], v207 offset:7168
	global_load_lds_dwordx4 v180, vcc
	s_add_i32 m0, s5, 0xe000
	s_nop 0
	global_load_lds_dwordx4 v182, vcc
	s_waitcnt vmcnt(8)
	s_waitcnt lgkmcnt(0)
	s_setprio 1
	s_barrier
	v_mfma_f32_16x16x32_bf16 v[128:131], v[132:135], v[188:191], v[128:131]
	v_mfma_f32_16x16x32_bf16 v[124:127], v[140:143], v[188:191], v[124:127]
	v_mfma_f32_16x16x32_bf16 v[120:123], v[132:135], v[196:199], v[120:123]
	v_mfma_f32_16x16x32_bf16 v[116:119], v[140:143], v[196:199], v[116:119]
	v_mfma_f32_16x16x32_bf16 v[112:115], v[132:135], v[212:215], v[112:115]
	v_mfma_f32_16x16x32_bf16 v[108:111], v[140:143], v[212:215], v[108:111]
	v_mfma_f32_16x16x32_bf16 v[104:107], v[132:135], v[220:223], v[104:107]
	v_mfma_f32_16x16x32_bf16 v[100:103], v[140:143], v[220:223], v[100:103]
	v_mfma_f32_16x16x32_bf16 v[128:131], v[136:139], v[192:195], v[128:131]
	v_mfma_f32_16x16x32_bf16 v[124:127], v[144:147], v[192:195], v[124:127]
	v_mfma_f32_16x16x32_bf16 v[120:123], v[136:139], v[208:211], v[120:123]
	v_mfma_f32_16x16x32_bf16 v[116:119], v[144:147], v[208:211], v[116:119]
	v_mfma_f32_16x16x32_bf16 v[112:115], v[136:139], v[216:219], v[112:115]
	v_mfma_f32_16x16x32_bf16 v[108:111], v[144:147], v[216:219], v[108:111]
	v_mfma_f32_16x16x32_bf16 v[104:107], v[136:139], v[224:227], v[104:107]
	v_mfma_f32_16x16x32_bf16 v[100:103], v[144:147], v[224:227], v[100:103]
	v_mfma_f32_16x16x32_bf16 v[96:99], v[148:151], v[188:191], v[96:99]
	v_mfma_f32_16x16x32_bf16 v[92:95], v[156:159], v[188:191], v[92:95]
	v_mfma_f32_16x16x32_bf16 v[88:91], v[148:151], v[196:199], v[88:91]
	v_mfma_f32_16x16x32_bf16 v[84:87], v[156:159], v[196:199], v[84:87]
	v_mfma_f32_16x16x32_bf16 v[80:83], v[148:151], v[212:215], v[80:83]
	v_mfma_f32_16x16x32_bf16 v[76:79], v[156:159], v[212:215], v[76:79]
	v_mfma_f32_16x16x32_bf16 v[72:75], v[148:151], v[220:223], v[72:75]
	v_mfma_f32_16x16x32_bf16 v[68:71], v[156:159], v[220:223], v[68:71]
	v_mfma_f32_16x16x32_bf16 v[96:99], v[152:155], v[192:195], v[96:99]
	v_mfma_f32_16x16x32_bf16 v[92:95], v[184:187], v[192:195], v[92:95]
	v_mfma_f32_16x16x32_bf16 v[88:91], v[152:155], v[208:211], v[88:91]
	v_mfma_f32_16x16x32_bf16 v[84:87], v[184:187], v[208:211], v[84:87]
	v_mfma_f32_16x16x32_bf16 v[80:83], v[152:155], v[216:219], v[80:83]
	v_mfma_f32_16x16x32_bf16 v[76:79], v[184:187], v[216:219], v[76:79]
	v_mfma_f32_16x16x32_bf16 v[72:75], v[152:155], v[224:227], v[72:75]
	v_mfma_f32_16x16x32_bf16 v[68:71], v[184:187], v[224:227], v[68:71]
	s_barrier
	s_setprio 0
	s_add_i32 s76, s76, s4
	v_lshl_add_u64 v[170:171], s[84:85], 0, v[176:177]
	s_mov_b32 m0, s76
	ds_read_b128 v[188:191], v207 offset:16384
	ds_read_b128 v[192:195], v207 offset:17408
	ds_read_b128 v[196:199], v207 offset:18432
	ds_read_b128 v[208:211], v207 offset:19456
	ds_read_b128 v[212:215], v207 offset:20480
	ds_read_b128 v[216:219], v207 offset:21504
	ds_read_b128 v[220:223], v207 offset:22528
	ds_read_b128 v[224:227], v207 offset:23552
	global_load_lds_dwordx4 v[170:171], off
	s_add_i32 m0, s76, 0x2000
	s_add_u32 s76, s84, 0x40000
	v_lshl_add_u64 v[172:173], s[84:85], 0, v[160:161]
	s_addc_u32 s77, s85, 0
	s_add_i32 s75, s75, s4
	global_load_lds_dwordx4 v[172:173], off
	s_mov_b32 m0, s75
	v_lshl_add_u64 v[228:229], s[72:73], 0, v[178:179]
	global_load_lds_dwordx4 v176, s[76:77]
	s_add_i32 m0, s75, 0x2000
	v_lshl_add_u64 v[230:231], s[72:73], 0, v[174:175]
	global_load_lds_dwordx4 v160, s[76:77]
	s_mov_b32 m0, s5
	s_nop 0
	global_load_lds_dwordx4 v[228:229], off
	s_mov_b32 m0, s22
	s_nop 0
	global_load_lds_dwordx4 v[230:231], off
	s_waitcnt vmcnt(8)
	s_waitcnt lgkmcnt(0)
	s_setprio 1
	s_barrier
	v_mfma_f32_16x16x32_bf16 v[64:67], v[132:135], v[188:191], v[64:67]
	v_mfma_f32_16x16x32_bf16 v[60:63], v[140:143], v[188:191], v[60:63]
	v_mfma_f32_16x16x32_bf16 v[56:59], v[132:135], v[196:199], v[56:59]
	v_mfma_f32_16x16x32_bf16 v[52:55], v[140:143], v[196:199], v[52:55]
	v_mfma_f32_16x16x32_bf16 v[48:51], v[132:135], v[212:215], v[48:51]
	v_mfma_f32_16x16x32_bf16 v[44:47], v[140:143], v[212:215], v[44:47]
	v_mfma_f32_16x16x32_bf16 v[40:43], v[132:135], v[220:223], v[40:43]
	v_mfma_f32_16x16x32_bf16 v[36:39], v[140:143], v[220:223], v[36:39]
	v_mfma_f32_16x16x32_bf16 v[64:67], v[136:139], v[192:195], v[64:67]
	v_mfma_f32_16x16x32_bf16 v[60:63], v[144:147], v[192:195], v[60:63]
	v_mfma_f32_16x16x32_bf16 v[56:59], v[136:139], v[208:211], v[56:59]
	v_mfma_f32_16x16x32_bf16 v[52:55], v[144:147], v[208:211], v[52:55]
	v_mfma_f32_16x16x32_bf16 v[48:51], v[136:139], v[216:219], v[48:51]
	v_mfma_f32_16x16x32_bf16 v[44:47], v[144:147], v[216:219], v[44:47]
	v_mfma_f32_16x16x32_bf16 v[40:43], v[136:139], v[224:227], v[40:43]
	v_mfma_f32_16x16x32_bf16 v[36:39], v[144:147], v[224:227], v[36:39]
	v_mfma_f32_16x16x32_bf16 v[32:35], v[148:151], v[188:191], v[32:35]
	v_mfma_f32_16x16x32_bf16 v[28:31], v[156:159], v[188:191], v[28:31]
	v_mfma_f32_16x16x32_bf16 v[24:27], v[148:151], v[196:199], v[24:27]
	v_mfma_f32_16x16x32_bf16 v[20:23], v[156:159], v[196:199], v[20:23]
	v_mfma_f32_16x16x32_bf16 v[16:19], v[148:151], v[212:215], v[16:19]
	v_mfma_f32_16x16x32_bf16 v[12:15], v[156:159], v[212:215], v[12:15]
	v_mfma_f32_16x16x32_bf16 v[8:11], v[148:151], v[220:223], v[8:11]
	v_mfma_f32_16x16x32_bf16 v[2:5], v[156:159], v[220:223], v[4:7]
	v_mfma_f32_16x16x32_bf16 v[32:35], v[152:155], v[192:195], v[32:35]
	v_mfma_f32_16x16x32_bf16 v[28:31], v[184:187], v[192:195], v[28:31]
	v_mfma_f32_16x16x32_bf16 v[24:27], v[152:155], v[208:211], v[24:27]
	v_mfma_f32_16x16x32_bf16 v[20:23], v[184:187], v[208:211], v[20:23]
	v_mfma_f32_16x16x32_bf16 v[16:19], v[152:155], v[216:219], v[16:19]
	v_mfma_f32_16x16x32_bf16 v[12:15], v[184:187], v[216:219], v[12:15]
	v_mfma_f32_16x16x32_bf16 v[8:11], v[152:155], v[224:227], v[8:11]
	v_mfma_f32_16x16x32_bf16 v[2:5], v[184:187], v[224:227], v[2:5]
	s_barrier
	s_setprio 0
	s_add_i32 s75, 0, 0x18000
	v_add_u32_e32 v0, s75, v205
	s_add_i32 s76, 0, 0x1c000
	ds_read_b128 v[132:135], v0
	ds_read_b128 v[136:139], v0 offset:1024
	ds_read_b128 v[140:143], v0 offset:2048
	ds_read_b128 v[144:147], v0 offset:3072
	v_add_u32_e32 v0, s76, v205
	ds_read_b128 v[148:151], v0
	ds_read_b128 v[152:155], v0 offset:1024
	ds_read_b128 v[156:159], v0 offset:2048
	ds_read_b128 v[184:187], v0 offset:3072
	s_add_u32 s72, s72, 0x40000
	s_addc_u32 s73, s73, 0
	s_mov_b32 m0, s23
	ds_read_b128 v[188:191], v207 offset:32768
	ds_read_b128 v[192:195], v207 offset:33792
	ds_read_b128 v[196:199], v207 offset:34816
	ds_read_b128 v[208:211], v207 offset:35840
	ds_read_b128 v[212:215], v207 offset:36864
	ds_read_b128 v[216:219], v207 offset:37888
	ds_read_b128 v[220:223], v207 offset:38912
	ds_read_b128 v[224:227], v207 offset:39936
	global_load_lds_dwordx4 v178, s[72:73]
	s_mov_b32 m0, s31
	s_nop 0
	global_load_lds_dwordx4 v174, s[72:73]
	s_waitcnt vmcnt(8)
	s_waitcnt lgkmcnt(0)
	s_setprio 1
	s_barrier
	v_mfma_f32_16x16x32_bf16 v[128:131], v[132:135], v[188:191], v[128:131]
	v_mfma_f32_16x16x32_bf16 v[124:127], v[140:143], v[188:191], v[124:127]
	v_mfma_f32_16x16x32_bf16 v[120:123], v[132:135], v[196:199], v[120:123]
	v_mfma_f32_16x16x32_bf16 v[116:119], v[140:143], v[196:199], v[116:119]
	v_mfma_f32_16x16x32_bf16 v[112:115], v[132:135], v[212:215], v[112:115]
	v_mfma_f32_16x16x32_bf16 v[108:111], v[140:143], v[212:215], v[108:111]
	v_mfma_f32_16x16x32_bf16 v[104:107], v[132:135], v[220:223], v[104:107]
	v_mfma_f32_16x16x32_bf16 v[100:103], v[140:143], v[220:223], v[100:103]
	v_mfma_f32_16x16x32_bf16 v[128:131], v[136:139], v[192:195], v[128:131]
	v_mfma_f32_16x16x32_bf16 v[124:127], v[144:147], v[192:195], v[124:127]
	v_mfma_f32_16x16x32_bf16 v[120:123], v[136:139], v[208:211], v[120:123]
	v_mfma_f32_16x16x32_bf16 v[116:119], v[144:147], v[208:211], v[116:119]
	v_mfma_f32_16x16x32_bf16 v[112:115], v[136:139], v[216:219], v[112:115]
	v_mfma_f32_16x16x32_bf16 v[108:111], v[144:147], v[216:219], v[108:111]
	v_mfma_f32_16x16x32_bf16 v[104:107], v[136:139], v[224:227], v[104:107]
	v_mfma_f32_16x16x32_bf16 v[100:103], v[144:147], v[224:227], v[100:103]
	v_mfma_f32_16x16x32_bf16 v[96:99], v[148:151], v[188:191], v[96:99]
	v_mfma_f32_16x16x32_bf16 v[92:95], v[156:159], v[188:191], v[92:95]
	v_mfma_f32_16x16x32_bf16 v[88:91], v[148:151], v[196:199], v[88:91]
	v_mfma_f32_16x16x32_bf16 v[84:87], v[156:159], v[196:199], v[84:87]
	v_mfma_f32_16x16x32_bf16 v[80:83], v[148:151], v[212:215], v[80:83]
	v_mfma_f32_16x16x32_bf16 v[76:79], v[156:159], v[212:215], v[76:79]
	v_mfma_f32_16x16x32_bf16 v[72:75], v[148:151], v[220:223], v[72:75]
	v_mfma_f32_16x16x32_bf16 v[68:71], v[156:159], v[220:223], v[68:71]
	v_mfma_f32_16x16x32_bf16 v[96:99], v[152:155], v[192:195], v[96:99]
	v_mfma_f32_16x16x32_bf16 v[92:95], v[184:187], v[192:195], v[92:95]
	v_mfma_f32_16x16x32_bf16 v[88:91], v[152:155], v[208:211], v[88:91]
	v_mfma_f32_16x16x32_bf16 v[84:87], v[184:187], v[208:211], v[84:87]
	v_mfma_f32_16x16x32_bf16 v[80:83], v[152:155], v[216:219], v[80:83]
	v_mfma_f32_16x16x32_bf16 v[76:79], v[184:187], v[216:219], v[76:79]
	v_mfma_f32_16x16x32_bf16 v[72:75], v[152:155], v[224:227], v[72:75]
	v_mfma_f32_16x16x32_bf16 v[68:71], v[184:187], v[224:227], v[68:71]
	s_barrier
	s_setprio 0
	s_add_i32 s72, s75, s4
	v_lshl_add_u64 v[6:7], v[170:171], 0, s[24:25]
	s_mov_b32 m0, s72
	ds_read_b128 v[188:191], v207 offset:49152
	ds_read_b128 v[192:195], v207 offset:50176
	ds_read_b128 v[196:199], v207 offset:51200
	ds_read_b128 v[208:211], v207 offset:52224
	ds_read_b128 v[212:215], v207 offset:53248
	ds_read_b128 v[216:219], v207 offset:54272
	ds_read_b128 v[220:223], v207 offset:55296
	ds_read_b128 v[224:227], v207 offset:56320
	global_load_lds_dwordx4 v[6:7], off
	s_add_i32 m0, s72, 0x2000
	s_add_u32 s72, s84, 0x40080
	v_lshl_add_u64 v[6:7], v[172:173], 0, s[24:25]
	s_addc_u32 s73, s85, 0
	s_add_i32 s75, s76, s4
	global_load_lds_dwordx4 v[6:7], off
	s_mov_b32 m0, s75
	s_nop 0
	global_load_lds_dwordx4 v176, s[72:73]
	s_add_i32 m0, s75, 0x2000
	s_nop 0
	global_load_lds_dwordx4 v160, s[72:73]
	v_lshl_add_u64 v[6:7], v[228:229], 0, s[24:25]
	s_mov_b32 m0, s33
	s_nop 0
	global_load_lds_dwordx4 v[6:7], off
	v_lshl_add_u64 v[6:7], v[230:231], 0, s[24:25]
	s_mov_b32 m0, s38
	s_nop 0
	global_load_lds_dwordx4 v[6:7], off
	s_waitcnt vmcnt(8)
	s_waitcnt lgkmcnt(0)
	s_setprio 1
	s_barrier
	v_mfma_f32_16x16x32_bf16 v[64:67], v[132:135], v[188:191], v[64:67]
	v_mfma_f32_16x16x32_bf16 v[60:63], v[140:143], v[188:191], v[60:63]
	v_mfma_f32_16x16x32_bf16 v[56:59], v[132:135], v[196:199], v[56:59]
	v_mfma_f32_16x16x32_bf16 v[52:55], v[140:143], v[196:199], v[52:55]
	v_mfma_f32_16x16x32_bf16 v[48:51], v[132:135], v[212:215], v[48:51]
	v_mfma_f32_16x16x32_bf16 v[44:47], v[140:143], v[212:215], v[44:47]
	v_mfma_f32_16x16x32_bf16 v[40:43], v[132:135], v[220:223], v[40:43]
	v_mfma_f32_16x16x32_bf16 v[36:39], v[140:143], v[220:223], v[36:39]
	v_mfma_f32_16x16x32_bf16 v[64:67], v[136:139], v[192:195], v[64:67]
	v_mfma_f32_16x16x32_bf16 v[60:63], v[144:147], v[192:195], v[60:63]
	v_mfma_f32_16x16x32_bf16 v[56:59], v[136:139], v[208:211], v[56:59]
	v_mfma_f32_16x16x32_bf16 v[52:55], v[144:147], v[208:211], v[52:55]
	v_mfma_f32_16x16x32_bf16 v[48:51], v[136:139], v[216:219], v[48:51]
	v_mfma_f32_16x16x32_bf16 v[44:47], v[144:147], v[216:219], v[44:47]
	v_mfma_f32_16x16x32_bf16 v[40:43], v[136:139], v[224:227], v[40:43]
	v_mfma_f32_16x16x32_bf16 v[36:39], v[144:147], v[224:227], v[36:39]
	v_mfma_f32_16x16x32_bf16 v[32:35], v[148:151], v[188:191], v[32:35]
	v_mfma_f32_16x16x32_bf16 v[28:31], v[156:159], v[188:191], v[28:31]
	v_mfma_f32_16x16x32_bf16 v[24:27], v[148:151], v[196:199], v[24:27]
	v_mfma_f32_16x16x32_bf16 v[20:23], v[156:159], v[196:199], v[20:23]
	v_mfma_f32_16x16x32_bf16 v[16:19], v[148:151], v[212:215], v[16:19]
	v_mfma_f32_16x16x32_bf16 v[12:15], v[156:159], v[212:215], v[12:15]
	v_mfma_f32_16x16x32_bf16 v[6:9], v[148:151], v[220:223], v[8:11]
	v_mfma_f32_16x16x32_bf16 v[2:5], v[156:159], v[220:223], v[2:5]
	v_mfma_f32_16x16x32_bf16 v[32:35], v[152:155], v[192:195], v[32:35]
	v_mfma_f32_16x16x32_bf16 v[28:31], v[184:187], v[192:195], v[28:31]
	v_mfma_f32_16x16x32_bf16 v[24:27], v[152:155], v[208:211], v[24:27]
	v_mfma_f32_16x16x32_bf16 v[20:23], v[184:187], v[208:211], v[20:23]
	v_mfma_f32_16x16x32_bf16 v[16:19], v[152:155], v[216:219], v[16:19]
	v_mfma_f32_16x16x32_bf16 v[12:15], v[184:187], v[216:219], v[12:15]
	v_mfma_f32_16x16x32_bf16 v[8:11], v[152:155], v[224:227], v[6:9]
	v_mfma_f32_16x16x32_bf16 v[4:7], v[184:187], v[224:227], v[2:5]
	s_barrier
	s_setprio 0
	s_add_u32 s37, s37, 0x100
	s_addc_u32 s49, s49, 0
	s_add_u32 vcc_lo, vcc_lo, 0x100
	s_addc_u32 vcc_hi, vcc_hi, 0
	s_cmp_ge_i32 s74, s3
	s_mov_b32 s72, s74
	s_cbranch_scc0 .LBB7_1104

.LBB7_1196:
	s_add_i32 s72, s42, 2
	s_add_u32 s29, s16, 0xfffc0080
	s_addc_u32 s37, s17, -1
	s_add_i32 s73, 0, 0x10000
	s_cmp_eq_u32 s55, s42
	s_cselect_b32 s53, s13, s37
	s_cselect_b32 s52, s15, s29
	v_add_u32_e32 v146, s73, v153
	s_cselect_b32 s43, s28, s57
	s_cselect_b32 s42, s39, s56
	s_add_i32 s29, 0, 0x14000
	ds_read_b128 v[130:133], v146
	ds_read_b128 v[156:159], v146 offset:1024
	ds_read_b128 v[174:177], v146 offset:2048
	ds_read_b128 v[178:181], v146 offset:3072
	v_add_u32_e32 v146, s29, v153
	ds_read_b128 v[182:185], v146
	ds_read_b128 v[186:189], v146 offset:1024
	ds_read_b128 v[190:193], v146 offset:2048
	ds_read_b128 v[194:197], v146 offset:3072
	s_add_i32 m0, s5, 0xc000
	ds_read_b128 v[204:207], v161
	ds_read_b128 v[208:211], v161 offset:1024
	ds_read_b128 v[212:215], v161 offset:2048
	ds_read_b128 v[216:219], v161 offset:3072
	ds_read_b128 v[220:223], v161 offset:4096
	ds_read_b128 v[224:227], v161 offset:5120
	ds_read_b128 v[228:231], v161 offset:6144
	ds_read_b128 v[232:235], v161 offset:7168
	global_load_lds_dwordx4 v142, s[16:17]
	s_add_i32 m0, s5, 0xe000
	s_nop 0
	global_load_lds_dwordx4 v144, s[16:17]
	s_waitcnt vmcnt(8)
	s_waitcnt lgkmcnt(0)
	s_setprio 1
	s_barrier
	v_mfma_f32_16x16x32_bf16 v[126:129], v[130:133], v[204:207], v[126:129]
	v_mfma_f32_16x16x32_bf16 v[122:125], v[174:177], v[204:207], v[122:125]
	v_mfma_f32_16x16x32_bf16 v[110:113], v[130:133], v[212:215], v[110:113]
	v_mfma_f32_16x16x32_bf16 v[106:109], v[174:177], v[212:215], v[106:109]
	v_mfma_f32_16x16x32_bf16 v[94:97], v[130:133], v[220:223], v[94:97]
	v_mfma_f32_16x16x32_bf16 v[90:93], v[174:177], v[220:223], v[90:93]
	v_mfma_f32_16x16x32_bf16 v[78:81], v[130:133], v[228:231], v[78:81]
	v_mfma_f32_16x16x32_bf16 v[74:77], v[174:177], v[228:231], v[74:77]
	v_mfma_f32_16x16x32_bf16 v[126:129], v[156:159], v[208:211], v[126:129]
	v_mfma_f32_16x16x32_bf16 v[122:125], v[178:181], v[208:211], v[122:125]
	v_mfma_f32_16x16x32_bf16 v[110:113], v[156:159], v[216:219], v[110:113]
	v_mfma_f32_16x16x32_bf16 v[106:109], v[178:181], v[216:219], v[106:109]
	v_mfma_f32_16x16x32_bf16 v[94:97], v[156:159], v[224:227], v[94:97]
	v_mfma_f32_16x16x32_bf16 v[90:93], v[178:181], v[224:227], v[90:93]
	v_mfma_f32_16x16x32_bf16 v[78:81], v[156:159], v[232:235], v[78:81]
	v_mfma_f32_16x16x32_bf16 v[74:77], v[178:181], v[232:235], v[74:77]
	v_mfma_f32_16x16x32_bf16 v[118:121], v[182:185], v[204:207], v[118:121]
	v_mfma_f32_16x16x32_bf16 v[114:117], v[190:193], v[204:207], v[114:117]
	v_mfma_f32_16x16x32_bf16 v[102:105], v[182:185], v[212:215], v[102:105]
	v_mfma_f32_16x16x32_bf16 v[98:101], v[190:193], v[212:215], v[98:101]
	v_mfma_f32_16x16x32_bf16 v[86:89], v[182:185], v[220:223], v[86:89]
	v_mfma_f32_16x16x32_bf16 v[82:85], v[190:193], v[220:223], v[82:85]
	v_mfma_f32_16x16x32_bf16 v[70:73], v[182:185], v[228:231], v[70:73]
	v_mfma_f32_16x16x32_bf16 v[66:69], v[190:193], v[228:231], v[66:69]
	v_mfma_f32_16x16x32_bf16 v[118:121], v[186:189], v[208:211], v[118:121]
	v_mfma_f32_16x16x32_bf16 v[114:117], v[194:197], v[208:211], v[114:117]
	v_mfma_f32_16x16x32_bf16 v[102:105], v[186:189], v[216:219], v[102:105]
	v_mfma_f32_16x16x32_bf16 v[98:101], v[194:197], v[216:219], v[98:101]
	v_mfma_f32_16x16x32_bf16 v[86:89], v[186:189], v[224:227], v[86:89]
	v_mfma_f32_16x16x32_bf16 v[82:85], v[194:197], v[224:227], v[82:85]
	v_mfma_f32_16x16x32_bf16 v[70:73], v[186:189], v[232:235], v[70:73]
	v_mfma_f32_16x16x32_bf16 v[66:69], v[194:197], v[232:235], v[66:69]
	s_barrier
	s_setprio 0
	s_add_i32 s37, s73, s4
	v_lshl_add_u64 v[146:147], s[42:43], 0, v[0:1]
	s_mov_b32 m0, s37
	ds_read_b128 v[204:207], v161 offset:16384
	ds_read_b128 v[208:211], v161 offset:17408
	ds_read_b128 v[212:215], v161 offset:18432
	ds_read_b128 v[216:219], v161 offset:19456
	ds_read_b128 v[220:223], v161 offset:20480
	ds_read_b128 v[224:227], v161 offset:21504
	ds_read_b128 v[228:231], v161 offset:22528
	ds_read_b128 v[232:235], v161 offset:23552
	global_load_lds_dwordx4 v[146:147], off
	s_add_i32 m0, s37, 0x2000
	s_add_u32 s74, s42, 0x40000
	v_lshl_add_u64 v[150:151], s[42:43], 0, v[134:135]
	s_addc_u32 s75, s43, 0
	s_add_i32 s29, s29, s4
	global_load_lds_dwordx4 v[150:151], off
	s_mov_b32 m0, s29
	v_lshl_add_u64 v[172:173], s[52:53], 0, v[136:137]
	global_load_lds_dwordx4 v0, s[74:75]
	s_add_i32 m0, s29, 0x2000
	s_nop 0
	global_load_lds_dwordx4 v134, s[74:75]
	v_lshl_add_u64 v[170:171], s[52:53], 0, v[138:139]
	s_mov_b32 m0, s5
	s_nop 0
	global_load_lds_dwordx4 v[170:171], off
	s_mov_b32 m0, s20
	s_nop 0
	global_load_lds_dwordx4 v[172:173], off
	s_waitcnt vmcnt(8)
	s_waitcnt lgkmcnt(0)
	s_setprio 1
	s_barrier
	v_mfma_f32_16x16x32_bf16 v[62:65], v[130:133], v[204:207], v[62:65]
	v_mfma_f32_16x16x32_bf16 v[58:61], v[174:177], v[204:207], v[58:61]
	v_mfma_f32_16x16x32_bf16 v[46:49], v[130:133], v[212:215], v[46:49]
	v_mfma_f32_16x16x32_bf16 v[42:45], v[174:177], v[212:215], v[42:45]
	v_mfma_f32_16x16x32_bf16 v[30:33], v[130:133], v[220:223], v[30:33]
	v_mfma_f32_16x16x32_bf16 v[26:29], v[174:177], v[220:223], v[26:29]
	v_mfma_f32_16x16x32_bf16 v[14:17], v[130:133], v[228:231], v[14:17]
	v_mfma_f32_16x16x32_bf16 v[10:13], v[174:177], v[228:231], v[10:13]
	v_mfma_f32_16x16x32_bf16 v[62:65], v[156:159], v[208:211], v[62:65]
	v_mfma_f32_16x16x32_bf16 v[58:61], v[178:181], v[208:211], v[58:61]
	v_mfma_f32_16x16x32_bf16 v[46:49], v[156:159], v[216:219], v[46:49]
	v_mfma_f32_16x16x32_bf16 v[42:45], v[178:181], v[216:219], v[42:45]
	v_mfma_f32_16x16x32_bf16 v[30:33], v[156:159], v[224:227], v[30:33]
	v_mfma_f32_16x16x32_bf16 v[26:29], v[178:181], v[224:227], v[26:29]
	v_mfma_f32_16x16x32_bf16 v[14:17], v[156:159], v[232:235], v[14:17]
	v_mfma_f32_16x16x32_bf16 v[10:13], v[178:181], v[232:235], v[10:13]
	v_mfma_f32_16x16x32_bf16 v[54:57], v[182:185], v[204:207], v[54:57]
	v_mfma_f32_16x16x32_bf16 v[50:53], v[190:193], v[204:207], v[50:53]
	v_mfma_f32_16x16x32_bf16 v[38:41], v[182:185], v[212:215], v[38:41]
	v_mfma_f32_16x16x32_bf16 v[34:37], v[190:193], v[212:215], v[34:37]
	v_mfma_f32_16x16x32_bf16 v[22:25], v[182:185], v[220:223], v[22:25]
	v_mfma_f32_16x16x32_bf16 v[18:21], v[190:193], v[220:223], v[18:21]
	v_mfma_f32_16x16x32_bf16 v[6:9], v[182:185], v[228:231], v[6:9]
	v_mfma_f32_16x16x32_bf16 v[2:5], v[190:193], v[228:231], v[2:5]
	v_mfma_f32_16x16x32_bf16 v[54:57], v[186:189], v[208:211], v[54:57]
	v_mfma_f32_16x16x32_bf16 v[50:53], v[194:197], v[208:211], v[50:53]
	v_mfma_f32_16x16x32_bf16 v[38:41], v[186:189], v[216:219], v[38:41]
	v_mfma_f32_16x16x32_bf16 v[34:37], v[194:197], v[216:219], v[34:37]
	v_mfma_f32_16x16x32_bf16 v[22:25], v[186:189], v[224:227], v[22:25]
	v_mfma_f32_16x16x32_bf16 v[18:21], v[194:197], v[224:227], v[18:21]
	v_mfma_f32_16x16x32_bf16 v[6:9], v[186:189], v[232:235], v[6:9]
	v_mfma_f32_16x16x32_bf16 v[2:5], v[194:197], v[232:235], v[2:5]
	s_barrier
	s_setprio 0
	s_add_i32 s29, 0, 0x18000
	v_add_u32_e32 v148, s29, v153
	s_add_i32 s37, 0, 0x1c000
	ds_read_b128 v[130:133], v148
	ds_read_b128 v[156:159], v148 offset:1024
	ds_read_b128 v[174:177], v148 offset:2048
	ds_read_b128 v[178:181], v148 offset:3072
	v_add_u32_e32 v148, s37, v153
	ds_read_b128 v[182:185], v148
	ds_read_b128 v[186:189], v148 offset:1024
	ds_read_b128 v[190:193], v148 offset:2048
	ds_read_b128 v[194:197], v148 offset:3072
	s_add_u32 s52, s52, 0x40000
	s_addc_u32 s53, s53, 0
	s_mov_b32 m0, s22
	ds_read_b128 v[204:207], v161 offset:32768
	ds_read_b128 v[208:211], v161 offset:33792
	ds_read_b128 v[212:215], v161 offset:34816
	ds_read_b128 v[216:219], v161 offset:35840
	ds_read_b128 v[220:223], v161 offset:36864
	ds_read_b128 v[224:227], v161 offset:37888
	ds_read_b128 v[228:231], v161 offset:38912
	ds_read_b128 v[232:235], v161 offset:39936
	global_load_lds_dwordx4 v138, s[52:53]
	s_mov_b32 m0, s23
	s_nop 0
	global_load_lds_dwordx4 v136, s[52:53]
	s_waitcnt vmcnt(8)
	s_waitcnt lgkmcnt(0)
	s_setprio 1
	s_barrier
	v_mfma_f32_16x16x32_bf16 v[126:129], v[130:133], v[204:207], v[126:129]
	v_mfma_f32_16x16x32_bf16 v[122:125], v[174:177], v[204:207], v[122:125]
	v_mfma_f32_16x16x32_bf16 v[110:113], v[130:133], v[212:215], v[110:113]
	v_mfma_f32_16x16x32_bf16 v[106:109], v[174:177], v[212:215], v[106:109]
	v_mfma_f32_16x16x32_bf16 v[94:97], v[130:133], v[220:223], v[94:97]
	v_mfma_f32_16x16x32_bf16 v[90:93], v[174:177], v[220:223], v[90:93]
	v_mfma_f32_16x16x32_bf16 v[78:81], v[130:133], v[228:231], v[78:81]
	v_mfma_f32_16x16x32_bf16 v[74:77], v[174:177], v[228:231], v[74:77]
	v_mfma_f32_16x16x32_bf16 v[126:129], v[156:159], v[208:211], v[126:129]
	v_mfma_f32_16x16x32_bf16 v[122:125], v[178:181], v[208:211], v[122:125]
	v_mfma_f32_16x16x32_bf16 v[110:113], v[156:159], v[216:219], v[110:113]
	v_mfma_f32_16x16x32_bf16 v[106:109], v[178:181], v[216:219], v[106:109]
	v_mfma_f32_16x16x32_bf16 v[94:97], v[156:159], v[224:227], v[94:97]
	v_mfma_f32_16x16x32_bf16 v[90:93], v[178:181], v[224:227], v[90:93]
	v_mfma_f32_16x16x32_bf16 v[78:81], v[156:159], v[232:235], v[78:81]
	v_mfma_f32_16x16x32_bf16 v[74:77], v[178:181], v[232:235], v[74:77]
	v_mfma_f32_16x16x32_bf16 v[118:121], v[182:185], v[204:207], v[118:121]
	v_mfma_f32_16x16x32_bf16 v[114:117], v[190:193], v[204:207], v[114:117]
	v_mfma_f32_16x16x32_bf16 v[102:105], v[182:185], v[212:215], v[102:105]
	v_mfma_f32_16x16x32_bf16 v[98:101], v[190:193], v[212:215], v[98:101]
	v_mfma_f32_16x16x32_bf16 v[86:89], v[182:185], v[220:223], v[86:89]
	v_mfma_f32_16x16x32_bf16 v[82:85], v[190:193], v[220:223], v[82:85]
	v_mfma_f32_16x16x32_bf16 v[70:73], v[182:185], v[228:231], v[70:73]
	v_mfma_f32_16x16x32_bf16 v[66:69], v[190:193], v[228:231], v[66:69]
	v_mfma_f32_16x16x32_bf16 v[118:121], v[186:189], v[208:211], v[118:121]
	v_mfma_f32_16x16x32_bf16 v[114:117], v[194:197], v[208:211], v[114:117]
	v_mfma_f32_16x16x32_bf16 v[102:105], v[186:189], v[216:219], v[102:105]
	v_mfma_f32_16x16x32_bf16 v[98:101], v[194:197], v[216:219], v[98:101]
	v_mfma_f32_16x16x32_bf16 v[86:89], v[186:189], v[224:227], v[86:89]
	v_mfma_f32_16x16x32_bf16 v[82:85], v[194:197], v[224:227], v[82:85]
	v_mfma_f32_16x16x32_bf16 v[70:73], v[186:189], v[232:235], v[70:73]
	v_mfma_f32_16x16x32_bf16 v[66:69], v[194:197], v[232:235], v[66:69]
	s_barrier
	s_setprio 0
	s_add_i32 s29, s29, s4
	v_lshl_add_u64 v[146:147], v[146:147], 0, s[24:25]
	s_mov_b32 m0, s29
	ds_read_b128 v[204:207], v161 offset:49152
	ds_read_b128 v[208:211], v161 offset:50176
	ds_read_b128 v[212:215], v161 offset:51200
	ds_read_b128 v[216:219], v161 offset:52224
	ds_read_b128 v[220:223], v161 offset:53248
	ds_read_b128 v[224:227], v161 offset:54272
	ds_read_b128 v[228:231], v161 offset:55296
	ds_read_b128 v[232:235], v161 offset:56320
	global_load_lds_dwordx4 v[146:147], off
	s_add_i32 m0, s29, 0x2000
	s_add_u32 s42, s42, 0x40080
	v_lshl_add_u64 v[146:147], v[150:151], 0, s[24:25]
	s_addc_u32 s43, s43, 0
	s_add_i32 s29, s37, s4
	global_load_lds_dwordx4 v[146:147], off
	s_mov_b32 m0, s29
	s_nop 0
	global_load_lds_dwordx4 v0, s[42:43]
	s_add_i32 m0, s29, 0x2000
	s_nop 0
	global_load_lds_dwordx4 v134, s[42:43]
	v_lshl_add_u64 v[146:147], v[170:171], 0, s[24:25]
	s_mov_b32 m0, s31
	s_nop 0
	global_load_lds_dwordx4 v[146:147], off
	v_lshl_add_u64 v[146:147], v[172:173], 0, s[24:25]
	s_mov_b32 m0, s33
	s_nop 0
	global_load_lds_dwordx4 v[146:147], off
	s_waitcnt vmcnt(8)
	s_waitcnt lgkmcnt(0)
	s_setprio 1
	s_barrier
	v_mfma_f32_16x16x32_bf16 v[62:65], v[130:133], v[204:207], v[62:65]
	v_mfma_f32_16x16x32_bf16 v[58:61], v[174:177], v[204:207], v[58:61]
	v_mfma_f32_16x16x32_bf16 v[46:49], v[130:133], v[212:215], v[46:49]
	v_mfma_f32_16x16x32_bf16 v[42:45], v[174:177], v[212:215], v[42:45]
	v_mfma_f32_16x16x32_bf16 v[30:33], v[130:133], v[220:223], v[30:33]
	v_mfma_f32_16x16x32_bf16 v[26:29], v[174:177], v[220:223], v[26:29]
	v_mfma_f32_16x16x32_bf16 v[14:17], v[130:133], v[228:231], v[14:17]
	v_mfma_f32_16x16x32_bf16 v[10:13], v[174:177], v[228:231], v[10:13]
	v_mfma_f32_16x16x32_bf16 v[62:65], v[156:159], v[208:211], v[62:65]
	v_mfma_f32_16x16x32_bf16 v[58:61], v[178:181], v[208:211], v[58:61]
	v_mfma_f32_16x16x32_bf16 v[46:49], v[156:159], v[216:219], v[46:49]
	v_mfma_f32_16x16x32_bf16 v[42:45], v[178:181], v[216:219], v[42:45]
	v_mfma_f32_16x16x32_bf16 v[30:33], v[156:159], v[224:227], v[30:33]
	v_mfma_f32_16x16x32_bf16 v[26:29], v[178:181], v[224:227], v[26:29]
	v_mfma_f32_16x16x32_bf16 v[14:17], v[156:159], v[232:235], v[14:17]
	v_mfma_f32_16x16x32_bf16 v[10:13], v[178:181], v[232:235], v[10:13]
	v_mfma_f32_16x16x32_bf16 v[54:57], v[182:185], v[204:207], v[54:57]
	v_mfma_f32_16x16x32_bf16 v[50:53], v[190:193], v[204:207], v[50:53]
	v_mfma_f32_16x16x32_bf16 v[38:41], v[182:185], v[212:215], v[38:41]
	v_mfma_f32_16x16x32_bf16 v[34:37], v[190:193], v[212:215], v[34:37]
	v_mfma_f32_16x16x32_bf16 v[22:25], v[182:185], v[220:223], v[22:25]
	v_mfma_f32_16x16x32_bf16 v[18:21], v[190:193], v[220:223], v[18:21]
	v_mfma_f32_16x16x32_bf16 v[6:9], v[182:185], v[228:231], v[6:9]
	v_mfma_f32_16x16x32_bf16 v[2:5], v[190:193], v[228:231], v[2:5]
	v_mfma_f32_16x16x32_bf16 v[54:57], v[186:189], v[208:211], v[54:57]
	v_mfma_f32_16x16x32_bf16 v[50:53], v[194:197], v[208:211], v[50:53]
	v_mfma_f32_16x16x32_bf16 v[38:41], v[186:189], v[216:219], v[38:41]
	v_mfma_f32_16x16x32_bf16 v[34:37], v[194:197], v[216:219], v[34:37]
	v_mfma_f32_16x16x32_bf16 v[22:25], v[186:189], v[224:227], v[22:25]
	v_mfma_f32_16x16x32_bf16 v[18:21], v[194:197], v[224:227], v[18:21]
	v_mfma_f32_16x16x32_bf16 v[6:9], v[186:189], v[232:235], v[6:9]
	v_mfma_f32_16x16x32_bf16 v[2:5], v[194:197], v[232:235], v[2:5]
	s_barrier
	s_setprio 0
	s_add_u32 s16, s16, 0x100
	s_addc_u32 s17, s17, 0
	s_add_u32 s56, s56, 0x100
	s_addc_u32 s57, s57, 0
	s_cmp_ge_i32 s72, s3
	s_mov_b32 s42, s72
	s_cbranch_scc0 .LBB7_1196
	s_mov_b32 s56, s61
	s_and_b64 vcc, exec, s[6:7]
	s_cbranch_vccz .LBB7_1199

.LBB7_1219:
	s_add_i32 s56, s52, 2
	s_add_u32 s29, s16, 0xfffc0080
	s_addc_u32 s37, s17, -1
	s_add_i32 s57, 0, 0x10000
	s_cmp_eq_u32 s84, s52
	s_cselect_b32 s55, s10, s37
	s_cselect_b32 s54, s13, s29
	s_cselect_b32 s53, s15, s39
	s_cselect_b32 s52, s28, s38
	s_add_i32 s29, 0, 0x14000
	v_add_u32_e32 v152, s57, v157
	v_add_u32_e32 v170, s29, v157
	ds_read_b128 v[140:143], v152
	ds_read_b128 v[144:147], v152 offset:1024
	ds_read_b128 v[148:151], v152 offset:2048
	ds_read_b128 v[152:155], v152 offset:3072
	ds_read_b128 v[184:187], v170
	ds_read_b128 v[188:191], v170 offset:1024
	ds_read_b128 v[192:195], v170 offset:2048
	ds_read_b128 v[196:199], v170 offset:3072
	s_add_i32 m0, s5, 0xc000
	ds_read_b128 v[204:207], v181
	ds_read_b128 v[208:211], v181 offset:1024
	ds_read_b128 v[212:215], v181 offset:2048
	ds_read_b128 v[216:219], v181 offset:3072
	ds_read_b128 v[220:223], v181 offset:4096
	ds_read_b128 v[224:227], v181 offset:5120
	ds_read_b128 v[228:231], v181 offset:6144
	ds_read_b128 v[232:235], v181 offset:7168
	global_load_lds_dwordx4 v136, s[16:17]
	s_add_i32 m0, s5, 0xe000
	s_nop 0
	global_load_lds_dwordx4 v138, s[16:17]
	s_waitcnt vmcnt(8)
	s_waitcnt lgkmcnt(0)
	s_setprio 1
	s_barrier
	v_mfma_f32_16x16x32_bf16 v[126:129], v[140:143], v[204:207], v[126:129]
	v_mfma_f32_16x16x32_bf16 v[122:125], v[148:151], v[204:207], v[122:125]
	v_mfma_f32_16x16x32_bf16 v[118:121], v[140:143], v[212:215], v[118:121]
	v_mfma_f32_16x16x32_bf16 v[114:117], v[148:151], v[212:215], v[114:117]
	v_mfma_f32_16x16x32_bf16 v[106:109], v[140:143], v[220:223], v[106:109]
	v_mfma_f32_16x16x32_bf16 v[98:101], v[148:151], v[220:223], v[98:101]
	v_mfma_f32_16x16x32_bf16 v[90:93], v[140:143], v[228:231], v[90:93]
	v_mfma_f32_16x16x32_bf16 v[82:85], v[148:151], v[228:231], v[82:85]
	v_mfma_f32_16x16x32_bf16 v[126:129], v[144:147], v[208:211], v[126:129]
	v_mfma_f32_16x16x32_bf16 v[122:125], v[152:155], v[208:211], v[122:125]
	v_mfma_f32_16x16x32_bf16 v[118:121], v[144:147], v[216:219], v[118:121]
	v_mfma_f32_16x16x32_bf16 v[114:117], v[152:155], v[216:219], v[114:117]
	v_mfma_f32_16x16x32_bf16 v[106:109], v[144:147], v[224:227], v[106:109]
	v_mfma_f32_16x16x32_bf16 v[98:101], v[152:155], v[224:227], v[98:101]
	v_mfma_f32_16x16x32_bf16 v[90:93], v[144:147], v[232:235], v[90:93]
	v_mfma_f32_16x16x32_bf16 v[82:85], v[152:155], v[232:235], v[82:85]
	v_mfma_f32_16x16x32_bf16 v[110:113], v[184:187], v[204:207], v[110:113]
	v_mfma_f32_16x16x32_bf16 v[102:105], v[192:195], v[204:207], v[102:105]
	v_mfma_f32_16x16x32_bf16 v[94:97], v[184:187], v[212:215], v[94:97]
	v_mfma_f32_16x16x32_bf16 v[86:89], v[192:195], v[212:215], v[86:89]
	v_mfma_f32_16x16x32_bf16 v[78:81], v[184:187], v[220:223], v[78:81]
	v_mfma_f32_16x16x32_bf16 v[74:77], v[192:195], v[220:223], v[74:77]
	v_mfma_f32_16x16x32_bf16 v[70:73], v[184:187], v[228:231], v[70:73]
	v_mfma_f32_16x16x32_bf16 v[66:69], v[192:195], v[228:231], v[66:69]
	v_mfma_f32_16x16x32_bf16 v[110:113], v[188:191], v[208:211], v[110:113]
	v_mfma_f32_16x16x32_bf16 v[102:105], v[196:199], v[208:211], v[102:105]
	v_mfma_f32_16x16x32_bf16 v[94:97], v[188:191], v[216:219], v[94:97]
	v_mfma_f32_16x16x32_bf16 v[86:89], v[196:199], v[216:219], v[86:89]
	v_mfma_f32_16x16x32_bf16 v[78:81], v[188:191], v[224:227], v[78:81]
	v_mfma_f32_16x16x32_bf16 v[74:77], v[196:199], v[224:227], v[74:77]
	v_mfma_f32_16x16x32_bf16 v[70:73], v[188:191], v[232:235], v[70:73]
	v_mfma_f32_16x16x32_bf16 v[66:69], v[196:199], v[232:235], v[66:69]
	s_barrier
	s_setprio 0
	s_add_i32 s37, s57, s4
	v_lshl_add_u64 v[170:171], s[52:53], 0, v[0:1]
	s_mov_b32 m0, s37
	ds_read_b128 v[204:207], v181 offset:16384
	ds_read_b128 v[208:211], v181 offset:17408
	ds_read_b128 v[212:215], v181 offset:18432
	ds_read_b128 v[216:219], v181 offset:19456
	ds_read_b128 v[220:223], v181 offset:20480
	ds_read_b128 v[224:227], v181 offset:21504
	ds_read_b128 v[228:231], v181 offset:22528
	ds_read_b128 v[232:235], v181 offset:23552
	global_load_lds_dwordx4 v[170:171], off
	s_add_i32 m0, s37, 0x2000
	s_add_u32 s74, s52, 0x40000
	v_lshl_add_u64 v[172:173], s[52:53], 0, v[130:131]
	s_addc_u32 s75, s53, 0
	s_add_i32 s29, s29, s4
	global_load_lds_dwordx4 v[172:173], off
	s_mov_b32 m0, s29
	v_lshl_add_u64 v[238:239], s[54:55], 0, v[132:133]
	global_load_lds_dwordx4 v0, s[74:75]
	s_add_i32 m0, s29, 0x2000
	s_nop 0
	global_load_lds_dwordx4 v130, s[74:75]
	v_lshl_add_u64 v[236:237], s[54:55], 0, v[134:135]
	s_mov_b32 m0, s5
	s_nop 0
	global_load_lds_dwordx4 v[236:237], off
	s_mov_b32 m0, s20
	s_nop 0
	global_load_lds_dwordx4 v[238:239], off
	s_waitcnt vmcnt(8)
	s_waitcnt lgkmcnt(0)
	s_setprio 1
	s_barrier
	v_mfma_f32_16x16x32_bf16 v[62:65], v[140:143], v[204:207], v[62:65]
	v_mfma_f32_16x16x32_bf16 v[58:61], v[148:151], v[204:207], v[58:61]
	v_mfma_f32_16x16x32_bf16 v[54:57], v[140:143], v[212:215], v[54:57]
	v_mfma_f32_16x16x32_bf16 v[50:53], v[148:151], v[212:215], v[50:53]
	v_mfma_f32_16x16x32_bf16 v[42:45], v[140:143], v[220:223], v[42:45]
	v_mfma_f32_16x16x32_bf16 v[34:37], v[148:151], v[220:223], v[34:37]
	v_mfma_f32_16x16x32_bf16 v[26:29], v[140:143], v[228:231], v[26:29]
	v_mfma_f32_16x16x32_bf16 v[18:21], v[148:151], v[228:231], v[18:21]
	v_mfma_f32_16x16x32_bf16 v[62:65], v[144:147], v[208:211], v[62:65]
	v_mfma_f32_16x16x32_bf16 v[58:61], v[152:155], v[208:211], v[58:61]
	v_mfma_f32_16x16x32_bf16 v[54:57], v[144:147], v[216:219], v[54:57]
	v_mfma_f32_16x16x32_bf16 v[50:53], v[152:155], v[216:219], v[50:53]
	v_mfma_f32_16x16x32_bf16 v[42:45], v[144:147], v[224:227], v[42:45]
	v_mfma_f32_16x16x32_bf16 v[34:37], v[152:155], v[224:227], v[34:37]
	v_mfma_f32_16x16x32_bf16 v[26:29], v[144:147], v[232:235], v[26:29]
	v_mfma_f32_16x16x32_bf16 v[18:21], v[152:155], v[232:235], v[18:21]
	v_mfma_f32_16x16x32_bf16 v[46:49], v[184:187], v[204:207], v[46:49]
	v_mfma_f32_16x16x32_bf16 v[38:41], v[192:195], v[204:207], v[38:41]
	v_mfma_f32_16x16x32_bf16 v[30:33], v[184:187], v[212:215], v[30:33]
	v_mfma_f32_16x16x32_bf16 v[22:25], v[192:195], v[212:215], v[22:25]
	v_mfma_f32_16x16x32_bf16 v[14:17], v[184:187], v[220:223], v[14:17]
	v_mfma_f32_16x16x32_bf16 v[10:13], v[192:195], v[220:223], v[10:13]
	v_mfma_f32_16x16x32_bf16 v[6:9], v[184:187], v[228:231], v[6:9]
	v_mfma_f32_16x16x32_bf16 v[2:5], v[192:195], v[228:231], v[2:5]
	v_mfma_f32_16x16x32_bf16 v[46:49], v[188:191], v[208:211], v[46:49]
	v_mfma_f32_16x16x32_bf16 v[38:41], v[196:199], v[208:211], v[38:41]
	v_mfma_f32_16x16x32_bf16 v[30:33], v[188:191], v[216:219], v[30:33]
	v_mfma_f32_16x16x32_bf16 v[22:25], v[196:199], v[216:219], v[22:25]
	v_mfma_f32_16x16x32_bf16 v[14:17], v[188:191], v[224:227], v[14:17]
	v_mfma_f32_16x16x32_bf16 v[10:13], v[196:199], v[224:227], v[10:13]
	v_mfma_f32_16x16x32_bf16 v[6:9], v[188:191], v[232:235], v[6:9]
	v_mfma_f32_16x16x32_bf16 v[2:5], v[196:199], v[232:235], v[2:5]
	s_barrier
	s_setprio 0
	s_add_i32 s29, 0, 0x18000
	s_add_i32 s37, 0, 0x1c000
	v_add_u32_e32 v152, s29, v157
	v_add_u32_e32 v183, s37, v157
	ds_read_b128 v[140:143], v152
	ds_read_b128 v[144:147], v152 offset:1024
	ds_read_b128 v[148:151], v152 offset:2048
	ds_read_b128 v[152:155], v152 offset:3072
	ds_read_b128 v[184:187], v183
	ds_read_b128 v[188:191], v183 offset:1024
	ds_read_b128 v[192:195], v183 offset:2048
	ds_read_b128 v[196:199], v183 offset:3072
	s_add_u32 s54, s54, 0x40000
	s_addc_u32 s55, s55, 0
	s_mov_b32 m0, s22
	ds_read_b128 v[204:207], v181 offset:32768
	ds_read_b128 v[208:211], v181 offset:33792
	ds_read_b128 v[212:215], v181 offset:34816
	ds_read_b128 v[216:219], v181 offset:35840
	ds_read_b128 v[220:223], v181 offset:36864
	ds_read_b128 v[224:227], v181 offset:37888
	ds_read_b128 v[228:231], v181 offset:38912
	ds_read_b128 v[232:235], v181 offset:39936
	global_load_lds_dwordx4 v134, s[54:55]
	s_mov_b32 m0, s23
	s_nop 0
	global_load_lds_dwordx4 v132, s[54:55]
	s_waitcnt vmcnt(8)
	s_waitcnt lgkmcnt(0)
	s_setprio 1
	s_barrier
	v_mfma_f32_16x16x32_bf16 v[126:129], v[140:143], v[204:207], v[126:129]
	v_mfma_f32_16x16x32_bf16 v[122:125], v[148:151], v[204:207], v[122:125]
	v_mfma_f32_16x16x32_bf16 v[118:121], v[140:143], v[212:215], v[118:121]
	v_mfma_f32_16x16x32_bf16 v[114:117], v[148:151], v[212:215], v[114:117]
	v_mfma_f32_16x16x32_bf16 v[106:109], v[140:143], v[220:223], v[106:109]
	v_mfma_f32_16x16x32_bf16 v[98:101], v[148:151], v[220:223], v[98:101]
	v_mfma_f32_16x16x32_bf16 v[90:93], v[140:143], v[228:231], v[90:93]
	v_mfma_f32_16x16x32_bf16 v[82:85], v[148:151], v[228:231], v[82:85]
	v_mfma_f32_16x16x32_bf16 v[126:129], v[144:147], v[208:211], v[126:129]
	v_mfma_f32_16x16x32_bf16 v[122:125], v[152:155], v[208:211], v[122:125]
	v_mfma_f32_16x16x32_bf16 v[118:121], v[144:147], v[216:219], v[118:121]
	v_mfma_f32_16x16x32_bf16 v[114:117], v[152:155], v[216:219], v[114:117]
	v_mfma_f32_16x16x32_bf16 v[106:109], v[144:147], v[224:227], v[106:109]
	v_mfma_f32_16x16x32_bf16 v[98:101], v[152:155], v[224:227], v[98:101]
	v_mfma_f32_16x16x32_bf16 v[90:93], v[144:147], v[232:235], v[90:93]
	v_mfma_f32_16x16x32_bf16 v[82:85], v[152:155], v[232:235], v[82:85]
	v_mfma_f32_16x16x32_bf16 v[110:113], v[184:187], v[204:207], v[110:113]
	v_mfma_f32_16x16x32_bf16 v[102:105], v[192:195], v[204:207], v[102:105]
	v_mfma_f32_16x16x32_bf16 v[94:97], v[184:187], v[212:215], v[94:97]
	v_mfma_f32_16x16x32_bf16 v[86:89], v[192:195], v[212:215], v[86:89]
	v_mfma_f32_16x16x32_bf16 v[78:81], v[184:187], v[220:223], v[78:81]
	v_mfma_f32_16x16x32_bf16 v[74:77], v[192:195], v[220:223], v[74:77]
	v_mfma_f32_16x16x32_bf16 v[70:73], v[184:187], v[228:231], v[70:73]
	v_mfma_f32_16x16x32_bf16 v[66:69], v[192:195], v[228:231], v[66:69]
	v_mfma_f32_16x16x32_bf16 v[110:113], v[188:191], v[208:211], v[110:113]
	v_mfma_f32_16x16x32_bf16 v[102:105], v[196:199], v[208:211], v[102:105]
	v_mfma_f32_16x16x32_bf16 v[94:97], v[188:191], v[216:219], v[94:97]
	v_mfma_f32_16x16x32_bf16 v[86:89], v[196:199], v[216:219], v[86:89]
	v_mfma_f32_16x16x32_bf16 v[78:81], v[188:191], v[224:227], v[78:81]
	v_mfma_f32_16x16x32_bf16 v[74:77], v[196:199], v[224:227], v[74:77]
	v_mfma_f32_16x16x32_bf16 v[70:73], v[188:191], v[232:235], v[70:73]
	v_mfma_f32_16x16x32_bf16 v[66:69], v[196:199], v[232:235], v[66:69]
	s_barrier
	s_setprio 0
	s_add_i32 s29, s29, s4
	v_lshl_add_u64 v[170:171], v[170:171], 0, s[24:25]
	s_mov_b32 m0, s29
	ds_read_b128 v[204:207], v181 offset:49152
	ds_read_b128 v[208:211], v181 offset:50176
	ds_read_b128 v[212:215], v181 offset:51200
	ds_read_b128 v[216:219], v181 offset:52224
	ds_read_b128 v[220:223], v181 offset:53248
	ds_read_b128 v[224:227], v181 offset:54272
	ds_read_b128 v[228:231], v181 offset:55296
	ds_read_b128 v[232:235], v181 offset:56320
	global_load_lds_dwordx4 v[170:171], off
	s_add_i32 m0, s29, 0x2000
	s_add_u32 s52, s52, 0x40080
	v_lshl_add_u64 v[170:171], v[172:173], 0, s[24:25]
	s_addc_u32 s53, s53, 0
	s_add_i32 s29, s37, s4
	global_load_lds_dwordx4 v[170:171], off
	s_mov_b32 m0, s29
	s_nop 0
	global_load_lds_dwordx4 v0, s[52:53]
	s_add_i32 m0, s29, 0x2000
	s_nop 0
	global_load_lds_dwordx4 v130, s[52:53]
	v_lshl_add_u64 v[170:171], v[236:237], 0, s[24:25]
	s_mov_b32 m0, s31
	s_nop 0
	global_load_lds_dwordx4 v[170:171], off
	v_lshl_add_u64 v[170:171], v[238:239], 0, s[24:25]
	s_mov_b32 m0, s33
	s_nop 0
	global_load_lds_dwordx4 v[170:171], off
	s_waitcnt vmcnt(8)
	s_waitcnt lgkmcnt(0)
	s_setprio 1
	s_barrier
	v_mfma_f32_16x16x32_bf16 v[62:65], v[140:143], v[204:207], v[62:65]
	v_mfma_f32_16x16x32_bf16 v[58:61], v[148:151], v[204:207], v[58:61]
	v_mfma_f32_16x16x32_bf16 v[54:57], v[140:143], v[212:215], v[54:57]
	v_mfma_f32_16x16x32_bf16 v[50:53], v[148:151], v[212:215], v[50:53]
	v_mfma_f32_16x16x32_bf16 v[42:45], v[140:143], v[220:223], v[42:45]
	v_mfma_f32_16x16x32_bf16 v[34:37], v[148:151], v[220:223], v[34:37]
	v_mfma_f32_16x16x32_bf16 v[26:29], v[140:143], v[228:231], v[26:29]
	v_mfma_f32_16x16x32_bf16 v[18:21], v[148:151], v[228:231], v[18:21]
	v_mfma_f32_16x16x32_bf16 v[62:65], v[144:147], v[208:211], v[62:65]
	v_mfma_f32_16x16x32_bf16 v[58:61], v[152:155], v[208:211], v[58:61]
	v_mfma_f32_16x16x32_bf16 v[54:57], v[144:147], v[216:219], v[54:57]
	v_mfma_f32_16x16x32_bf16 v[50:53], v[152:155], v[216:219], v[50:53]
	v_mfma_f32_16x16x32_bf16 v[42:45], v[144:147], v[224:227], v[42:45]
	v_mfma_f32_16x16x32_bf16 v[34:37], v[152:155], v[224:227], v[34:37]
	v_mfma_f32_16x16x32_bf16 v[26:29], v[144:147], v[232:235], v[26:29]
	v_mfma_f32_16x16x32_bf16 v[18:21], v[152:155], v[232:235], v[18:21]
	v_mfma_f32_16x16x32_bf16 v[46:49], v[184:187], v[204:207], v[46:49]
	v_mfma_f32_16x16x32_bf16 v[38:41], v[192:195], v[204:207], v[38:41]
	v_mfma_f32_16x16x32_bf16 v[30:33], v[184:187], v[212:215], v[30:33]
	v_mfma_f32_16x16x32_bf16 v[22:25], v[192:195], v[212:215], v[22:25]
	v_mfma_f32_16x16x32_bf16 v[14:17], v[184:187], v[220:223], v[14:17]
	v_mfma_f32_16x16x32_bf16 v[10:13], v[192:195], v[220:223], v[10:13]
	v_mfma_f32_16x16x32_bf16 v[6:9], v[184:187], v[228:231], v[6:9]
	v_mfma_f32_16x16x32_bf16 v[2:5], v[192:195], v[228:231], v[2:5]
	v_mfma_f32_16x16x32_bf16 v[46:49], v[188:191], v[208:211], v[46:49]
	v_mfma_f32_16x16x32_bf16 v[38:41], v[196:199], v[208:211], v[38:41]
	v_mfma_f32_16x16x32_bf16 v[30:33], v[188:191], v[216:219], v[30:33]
	v_mfma_f32_16x16x32_bf16 v[22:25], v[196:199], v[216:219], v[22:25]
	v_mfma_f32_16x16x32_bf16 v[14:17], v[188:191], v[224:227], v[14:17]
	v_mfma_f32_16x16x32_bf16 v[10:13], v[196:199], v[224:227], v[10:13]
	v_mfma_f32_16x16x32_bf16 v[6:9], v[188:191], v[232:235], v[6:9]
	v_mfma_f32_16x16x32_bf16 v[2:5], v[196:199], v[232:235], v[2:5]
	s_barrier
	s_setprio 0
	s_add_u32 s16, s16, 0x100
	s_addc_u32 s17, s17, 0
	s_add_u32 s38, s38, 0x100
	s_addc_u32 s39, s39, 0
	s_cmp_ge_i32 s56, s3
	s_mov_b32 s52, s56
	s_cbranch_scc0 .LBB7_1219
	v_pk_mul_f32 v[128:129], v[128:129], s[36:37] op_sel_hi:[1,0]
	v_pk_mul_f32 v[144:145], v[126:127], s[36:37] op_sel_hi:[1,0]
	v_pk_mul_f32 v[126:127], v[124:125], s[36:37] op_sel_hi:[1,0]
	v_pk_mul_f32 v[140:141], v[122:123], s[36:37] op_sel_hi:[1,0]
	v_pk_mul_f32 v[146:147], v[112:113], s[36:37] op_sel_hi:[1,0]
	v_pk_mul_f32 v[150:151], v[110:111], s[36:37] op_sel_hi:[1,0]
	v_pk_mul_f32 v[142:143], v[104:105], s[36:37] op_sel_hi:[1,0]
	v_pk_mul_f32 v[148:149], v[102:103], s[36:37] op_sel_hi:[1,0]
	v_pk_mul_f32 v[120:121], v[120:121], s[36:37] op_sel_hi:[1,0]
	v_pk_mul_f32 v[118:119], v[118:119], s[36:37] op_sel_hi:[1,0]
	v_pk_mul_f32 v[110:111], v[116:117], s[36:37] op_sel_hi:[1,0]
	v_pk_mul_f32 v[112:113], v[114:115], s[36:37] op_sel_hi:[1,0]
	v_pk_mul_f32 v[116:117], v[96:97], s[36:37] op_sel_hi:[1,0]
	v_pk_mul_f32 v[124:125], v[94:95], s[36:37] op_sel_hi:[1,0]
	v_pk_mul_f32 v[114:115], v[88:89], s[36:37] op_sel_hi:[1,0]
	v_pk_mul_f32 v[122:123], v[86:87], s[36:37] op_sel_hi:[1,0]
	v_pk_mul_f32 v[102:103], v[108:109], s[36:37] op_sel_hi:[1,0]
	v_pk_mul_f32 v[104:105], v[106:107], s[36:37] op_sel_hi:[1,0]
	v_pk_mul_f32 v[94:95], v[100:101], s[36:37] op_sel_hi:[1,0]
	v_pk_mul_f32 v[96:97], v[98:99], s[36:37] op_sel_hi:[1,0]
	v_pk_mul_f32 v[100:101], v[80:81], s[36:37] op_sel_hi:[1,0]
	v_pk_mul_f32 v[108:109], v[78:79], s[36:37] op_sel_hi:[1,0]
	v_pk_mul_f32 v[98:99], v[76:77], s[36:37] op_sel_hi:[1,0]
	v_pk_mul_f32 v[106:107], v[74:75], s[36:37] op_sel_hi:[1,0]
	v_pk_mul_f32 v[86:87], v[92:93], s[36:37] op_sel_hi:[1,0]
	v_pk_mul_f32 v[88:89], v[90:91], s[36:37] op_sel_hi:[1,0]
	v_pk_mul_f32 v[76:77], v[84:85], s[36:37] op_sel_hi:[1,0]
	v_pk_mul_f32 v[80:81], v[82:83], s[36:37] op_sel_hi:[1,0]
	v_pk_mul_f32 v[84:85], v[72:73], s[36:37] op_sel_hi:[1,0]
	v_pk_mul_f32 v[92:93], v[70:71], s[36:37] op_sel_hi:[1,0]
	v_pk_mul_f32 v[82:83], v[68:69], s[36:37] op_sel_hi:[1,0]
	v_pk_mul_f32 v[90:91], v[66:67], s[36:37] op_sel_hi:[1,0]
	v_pk_mul_f32 v[66:67], v[64:65], s[36:37] op_sel_hi:[1,0]
	v_pk_mul_f32 v[72:73], v[62:63], s[36:37] op_sel_hi:[1,0]
	v_pk_mul_f32 v[62:63], v[60:61], s[36:37] op_sel_hi:[1,0]
	v_pk_mul_f32 v[64:65], v[58:59], s[36:37] op_sel_hi:[1,0]
	v_pk_mul_f32 v[70:71], v[48:49], s[36:37] op_sel_hi:[1,0]
	v_pk_mul_f32 v[78:79], v[46:47], s[36:37] op_sel_hi:[1,0]
	v_pk_mul_f32 v[68:69], v[40:41], s[36:37] op_sel_hi:[1,0]
	v_pk_mul_f32 v[74:75], v[38:39], s[36:37] op_sel_hi:[1,0]
	v_pk_mul_f32 v[56:57], v[56:57], s[36:37] op_sel_hi:[1,0]
	v_pk_mul_f32 v[54:55], v[54:55], s[36:37] op_sel_hi:[1,0]
	v_pk_mul_f32 v[46:47], v[52:53], s[36:37] op_sel_hi:[1,0]
	v_pk_mul_f32 v[48:49], v[50:51], s[36:37] op_sel_hi:[1,0]
	v_pk_mul_f32 v[52:53], v[32:33], s[36:37] op_sel_hi:[1,0]
	v_pk_mul_f32 v[60:61], v[30:31], s[36:37] op_sel_hi:[1,0]
	v_pk_mul_f32 v[50:51], v[24:25], s[36:37] op_sel_hi:[1,0]
	v_pk_mul_f32 v[58:59], v[22:23], s[36:37] op_sel_hi:[1,0]
	v_pk_mul_f32 v[30:31], v[44:45], s[36:37] op_sel_hi:[1,0]
	v_pk_mul_f32 v[38:39], v[42:43], s[36:37] op_sel_hi:[1,0]
	v_pk_mul_f32 v[22:23], v[36:37], s[36:37] op_sel_hi:[1,0]
	v_pk_mul_f32 v[24:25], v[34:35], s[36:37] op_sel_hi:[1,0]
	v_pk_mul_f32 v[34:35], v[16:17], s[36:37] op_sel_hi:[1,0]
	v_pk_mul_f32 v[40:41], v[14:15], s[36:37] op_sel_hi:[1,0]
	v_pk_mul_f32 v[32:33], v[12:13], s[36:37] op_sel_hi:[1,0]
	v_pk_mul_f32 v[36:37], v[10:11], s[36:37] op_sel_hi:[1,0]
	v_pk_mul_f32 v[14:15], v[28:29], s[36:37] op_sel_hi:[1,0]
	v_pk_mul_f32 v[16:17], v[26:27], s[36:37] op_sel_hi:[1,0]
	v_pk_mul_f32 v[10:11], v[20:21], s[36:37] op_sel_hi:[1,0]
	v_pk_mul_f32 v[12:13], v[18:19], s[36:37] op_sel_hi:[1,0]
	v_pk_mul_f32 v[8:9], v[8:9], s[36:37] op_sel_hi:[1,0]
	v_pk_mul_f32 v[6:7], v[6:7], s[36:37] op_sel_hi:[1,0]
	v_pk_mul_f32 v[4:5], v[4:5], s[36:37] op_sel_hi:[1,0]
	v_pk_mul_f32 v[2:3], v[2:3], s[36:37] op_sel_hi:[1,0]
	s_mov_b32 s56, s61
	s_and_b64 vcc, exec, s[6:7]
	s_cbranch_vccz .LBB7_1222

.LBB7_1274:
	s_add_i32 s72, s50, 2
	s_add_u32 s29, s48, 0xfffc0080
	s_addc_u32 s37, s49, -1
	s_add_i32 s73, 0, 0x10000
	s_cmp_eq_u32 s33, s50
	s_cselect_b32 s53, s13, s37
	s_cselect_b32 s52, s15, s29
	s_cselect_b32 s51, s54, s57
	s_cselect_b32 s50, s55, s56
	s_add_i32 s29, 0, 0x14000
	v_add_u32_e32 v156, s73, v141
	v_add_u32_e32 v160, s29, v141
	ds_read_b128 v[144:147], v156
	ds_read_b128 v[148:151], v156 offset:1024
	ds_read_b128 v[152:155], v156 offset:2048
	ds_read_b128 v[156:159], v156 offset:3072
	ds_read_b128 v[174:177], v160
	ds_read_b128 v[178:181], v160 offset:1024
	ds_read_b128 v[182:185], v160 offset:2048
	ds_read_b128 v[186:189], v160 offset:3072
	s_add_i32 m0, s5, 0xc000
	ds_read_b128 v[190:193], v143
	ds_read_b128 v[194:197], v143 offset:1024
	ds_read_b128 v[204:207], v143 offset:2048
	ds_read_b128 v[208:211], v143 offset:3072
	ds_read_b128 v[212:215], v143 offset:4096
	ds_read_b128 v[216:219], v143 offset:5120
	ds_read_b128 v[220:223], v143 offset:6144
	ds_read_b128 v[224:227], v143 offset:7168
	global_load_lds_dwordx4 v136, s[48:49]
	s_add_i32 m0, s5, 0xe000
	s_nop 0
	global_load_lds_dwordx4 v138, s[48:49]
	s_waitcnt vmcnt(8)
	s_waitcnt lgkmcnt(0)
	s_setprio 1
	s_barrier
	v_mfma_f32_16x16x32_bf16 v[126:129], v[144:147], v[190:193], v[126:129]
	v_mfma_f32_16x16x32_bf16 v[122:125], v[152:155], v[190:193], v[122:125]
	v_mfma_f32_16x16x32_bf16 v[110:113], v[144:147], v[204:207], v[110:113]
	v_mfma_f32_16x16x32_bf16 v[106:109], v[152:155], v[204:207], v[106:109]
	v_mfma_f32_16x16x32_bf16 v[94:97], v[144:147], v[212:215], v[94:97]
	v_mfma_f32_16x16x32_bf16 v[90:93], v[152:155], v[212:215], v[90:93]
	v_mfma_f32_16x16x32_bf16 v[78:81], v[144:147], v[220:223], v[78:81]
	v_mfma_f32_16x16x32_bf16 v[74:77], v[152:155], v[220:223], v[74:77]
	v_mfma_f32_16x16x32_bf16 v[126:129], v[148:151], v[194:197], v[126:129]
	v_mfma_f32_16x16x32_bf16 v[122:125], v[156:159], v[194:197], v[122:125]
	v_mfma_f32_16x16x32_bf16 v[110:113], v[148:151], v[208:211], v[110:113]
	v_mfma_f32_16x16x32_bf16 v[106:109], v[156:159], v[208:211], v[106:109]
	v_mfma_f32_16x16x32_bf16 v[94:97], v[148:151], v[216:219], v[94:97]
	v_mfma_f32_16x16x32_bf16 v[90:93], v[156:159], v[216:219], v[90:93]
	v_mfma_f32_16x16x32_bf16 v[78:81], v[148:151], v[224:227], v[78:81]
	v_mfma_f32_16x16x32_bf16 v[74:77], v[156:159], v[224:227], v[74:77]
	v_mfma_f32_16x16x32_bf16 v[118:121], v[174:177], v[190:193], v[118:121]
	v_mfma_f32_16x16x32_bf16 v[114:117], v[182:185], v[190:193], v[114:117]
	v_mfma_f32_16x16x32_bf16 v[102:105], v[174:177], v[204:207], v[102:105]
	v_mfma_f32_16x16x32_bf16 v[98:101], v[182:185], v[204:207], v[98:101]
	v_mfma_f32_16x16x32_bf16 v[86:89], v[174:177], v[212:215], v[86:89]
	v_mfma_f32_16x16x32_bf16 v[82:85], v[182:185], v[212:215], v[82:85]
	v_mfma_f32_16x16x32_bf16 v[70:73], v[174:177], v[220:223], v[70:73]
	v_mfma_f32_16x16x32_bf16 v[66:69], v[182:185], v[220:223], v[66:69]
	v_mfma_f32_16x16x32_bf16 v[118:121], v[178:181], v[194:197], v[118:121]
	v_mfma_f32_16x16x32_bf16 v[114:117], v[186:189], v[194:197], v[114:117]
	v_mfma_f32_16x16x32_bf16 v[102:105], v[178:181], v[208:211], v[102:105]
	v_mfma_f32_16x16x32_bf16 v[98:101], v[186:189], v[208:211], v[98:101]
	v_mfma_f32_16x16x32_bf16 v[86:89], v[178:181], v[216:219], v[86:89]
	v_mfma_f32_16x16x32_bf16 v[82:85], v[186:189], v[216:219], v[82:85]
	v_mfma_f32_16x16x32_bf16 v[70:73], v[178:181], v[224:227], v[70:73]
	v_mfma_f32_16x16x32_bf16 v[66:69], v[186:189], v[224:227], v[66:69]
	s_barrier
	s_setprio 0
	s_add_i32 s37, s73, s4
	v_lshl_add_u64 v[160:161], s[50:51], 0, v[0:1]
	s_mov_b32 m0, s37
	ds_read_b128 v[190:193], v143 offset:16384
	ds_read_b128 v[194:197], v143 offset:17408
	ds_read_b128 v[204:207], v143 offset:18432
	ds_read_b128 v[208:211], v143 offset:19456
	ds_read_b128 v[212:215], v143 offset:20480
	ds_read_b128 v[216:219], v143 offset:21504
	ds_read_b128 v[220:223], v143 offset:22528
	ds_read_b128 v[224:227], v143 offset:23552
	global_load_lds_dwordx4 v[160:161], off
	s_add_i32 m0, s37, 0x2000
	s_add_u32 s74, s50, 0x100000
	v_lshl_add_u64 v[170:171], s[50:51], 0, v[130:131]
	s_addc_u32 s75, s51, 0
	s_add_i32 s29, s29, s4
	global_load_lds_dwordx4 v[170:171], off
	s_mov_b32 m0, s29
	v_lshl_add_u64 v[198:199], s[52:53], 0, v[132:133]
	global_load_lds_dwordx4 v0, s[74:75]
	s_add_i32 m0, s29, 0x2000
	s_nop 0
	global_load_lds_dwordx4 v130, s[74:75]
	v_lshl_add_u64 v[172:173], s[52:53], 0, v[134:135]
	s_mov_b32 m0, s5
	s_nop 0
	global_load_lds_dwordx4 v[172:173], off
	s_mov_b32 m0, s10
	s_nop 0
	global_load_lds_dwordx4 v[198:199], off
	s_waitcnt vmcnt(8)
	s_waitcnt lgkmcnt(0)
	s_setprio 1
	s_barrier
	v_mfma_f32_16x16x32_bf16 v[62:65], v[144:147], v[190:193], v[62:65]
	v_mfma_f32_16x16x32_bf16 v[58:61], v[152:155], v[190:193], v[58:61]
	v_mfma_f32_16x16x32_bf16 v[46:49], v[144:147], v[204:207], v[46:49]
	v_mfma_f32_16x16x32_bf16 v[42:45], v[152:155], v[204:207], v[42:45]
	v_mfma_f32_16x16x32_bf16 v[30:33], v[144:147], v[212:215], v[30:33]
	v_mfma_f32_16x16x32_bf16 v[26:29], v[152:155], v[212:215], v[26:29]
	v_mfma_f32_16x16x32_bf16 v[14:17], v[144:147], v[220:223], v[14:17]
	v_mfma_f32_16x16x32_bf16 v[10:13], v[152:155], v[220:223], v[10:13]
	v_mfma_f32_16x16x32_bf16 v[62:65], v[148:151], v[194:197], v[62:65]
	v_mfma_f32_16x16x32_bf16 v[58:61], v[156:159], v[194:197], v[58:61]
	v_mfma_f32_16x16x32_bf16 v[46:49], v[148:151], v[208:211], v[46:49]
	v_mfma_f32_16x16x32_bf16 v[42:45], v[156:159], v[208:211], v[42:45]
	v_mfma_f32_16x16x32_bf16 v[30:33], v[148:151], v[216:219], v[30:33]
	v_mfma_f32_16x16x32_bf16 v[26:29], v[156:159], v[216:219], v[26:29]
	v_mfma_f32_16x16x32_bf16 v[14:17], v[148:151], v[224:227], v[14:17]
	v_mfma_f32_16x16x32_bf16 v[10:13], v[156:159], v[224:227], v[10:13]
	v_mfma_f32_16x16x32_bf16 v[54:57], v[174:177], v[190:193], v[54:57]
	v_mfma_f32_16x16x32_bf16 v[50:53], v[182:185], v[190:193], v[50:53]
	v_mfma_f32_16x16x32_bf16 v[38:41], v[174:177], v[204:207], v[38:41]
	v_mfma_f32_16x16x32_bf16 v[34:37], v[182:185], v[204:207], v[34:37]
	v_mfma_f32_16x16x32_bf16 v[22:25], v[174:177], v[212:215], v[22:25]
	v_mfma_f32_16x16x32_bf16 v[18:21], v[182:185], v[212:215], v[18:21]
	v_mfma_f32_16x16x32_bf16 v[6:9], v[174:177], v[220:223], v[6:9]
	v_mfma_f32_16x16x32_bf16 v[2:5], v[182:185], v[220:223], v[2:5]
	v_mfma_f32_16x16x32_bf16 v[54:57], v[178:181], v[194:197], v[54:57]
	v_mfma_f32_16x16x32_bf16 v[50:53], v[186:189], v[194:197], v[50:53]
	v_mfma_f32_16x16x32_bf16 v[38:41], v[178:181], v[208:211], v[38:41]
	v_mfma_f32_16x16x32_bf16 v[34:37], v[186:189], v[208:211], v[34:37]
	v_mfma_f32_16x16x32_bf16 v[22:25], v[178:181], v[216:219], v[22:25]
	v_mfma_f32_16x16x32_bf16 v[18:21], v[186:189], v[216:219], v[18:21]
	v_mfma_f32_16x16x32_bf16 v[6:9], v[178:181], v[224:227], v[6:9]
	v_mfma_f32_16x16x32_bf16 v[2:5], v[186:189], v[224:227], v[2:5]
	s_barrier
	s_setprio 0
	s_add_i32 s29, 0, 0x18000
	s_add_i32 s37, 0, 0x1c000
	v_add_u32_e32 v156, s29, v141
	v_add_u32_e32 v186, s37, v141
	ds_read_b128 v[144:147], v156
	ds_read_b128 v[148:151], v156 offset:1024
	ds_read_b128 v[152:155], v156 offset:2048
	ds_read_b128 v[156:159], v156 offset:3072
	ds_read_b128 v[174:177], v186
	ds_read_b128 v[178:181], v186 offset:1024
	ds_read_b128 v[182:185], v186 offset:2048
	ds_read_b128 v[186:189], v186 offset:3072
	s_add_u32 s52, s52, 0x40000
	s_addc_u32 s53, s53, 0
	s_mov_b32 m0, s20
	ds_read_b128 v[190:193], v143 offset:32768
	ds_read_b128 v[194:197], v143 offset:33792
	ds_read_b128 v[204:207], v143 offset:34816
	ds_read_b128 v[208:211], v143 offset:35840
	ds_read_b128 v[212:215], v143 offset:36864
	ds_read_b128 v[216:219], v143 offset:37888
	ds_read_b128 v[220:223], v143 offset:38912
	ds_read_b128 v[224:227], v143 offset:39936
	global_load_lds_dwordx4 v134, s[52:53]
	s_mov_b32 m0, s22
	s_nop 0
	global_load_lds_dwordx4 v132, s[52:53]
	s_waitcnt vmcnt(8)
	s_waitcnt lgkmcnt(0)
	s_setprio 1
	s_barrier
	v_mfma_f32_16x16x32_bf16 v[126:129], v[144:147], v[190:193], v[126:129]
	v_mfma_f32_16x16x32_bf16 v[122:125], v[152:155], v[190:193], v[122:125]
	v_mfma_f32_16x16x32_bf16 v[110:113], v[144:147], v[204:207], v[110:113]
	v_mfma_f32_16x16x32_bf16 v[106:109], v[152:155], v[204:207], v[106:109]
	v_mfma_f32_16x16x32_bf16 v[94:97], v[144:147], v[212:215], v[94:97]
	v_mfma_f32_16x16x32_bf16 v[90:93], v[152:155], v[212:215], v[90:93]
	v_mfma_f32_16x16x32_bf16 v[78:81], v[144:147], v[220:223], v[78:81]
	v_mfma_f32_16x16x32_bf16 v[74:77], v[152:155], v[220:223], v[74:77]
	v_mfma_f32_16x16x32_bf16 v[126:129], v[148:151], v[194:197], v[126:129]
	v_mfma_f32_16x16x32_bf16 v[122:125], v[156:159], v[194:197], v[122:125]
	v_mfma_f32_16x16x32_bf16 v[110:113], v[148:151], v[208:211], v[110:113]
	v_mfma_f32_16x16x32_bf16 v[106:109], v[156:159], v[208:211], v[106:109]
	v_mfma_f32_16x16x32_bf16 v[94:97], v[148:151], v[216:219], v[94:97]
	v_mfma_f32_16x16x32_bf16 v[90:93], v[156:159], v[216:219], v[90:93]
	v_mfma_f32_16x16x32_bf16 v[78:81], v[148:151], v[224:227], v[78:81]
	v_mfma_f32_16x16x32_bf16 v[74:77], v[156:159], v[224:227], v[74:77]
	v_mfma_f32_16x16x32_bf16 v[118:121], v[174:177], v[190:193], v[118:121]
	v_mfma_f32_16x16x32_bf16 v[114:117], v[182:185], v[190:193], v[114:117]
	v_mfma_f32_16x16x32_bf16 v[102:105], v[174:177], v[204:207], v[102:105]
	v_mfma_f32_16x16x32_bf16 v[98:101], v[182:185], v[204:207], v[98:101]
	v_mfma_f32_16x16x32_bf16 v[86:89], v[174:177], v[212:215], v[86:89]
	v_mfma_f32_16x16x32_bf16 v[82:85], v[182:185], v[212:215], v[82:85]
	v_mfma_f32_16x16x32_bf16 v[70:73], v[174:177], v[220:223], v[70:73]
	v_mfma_f32_16x16x32_bf16 v[66:69], v[182:185], v[220:223], v[66:69]
	v_mfma_f32_16x16x32_bf16 v[118:121], v[178:181], v[194:197], v[118:121]
	v_mfma_f32_16x16x32_bf16 v[114:117], v[186:189], v[194:197], v[114:117]
	v_mfma_f32_16x16x32_bf16 v[102:105], v[178:181], v[208:211], v[102:105]
	v_mfma_f32_16x16x32_bf16 v[98:101], v[186:189], v[208:211], v[98:101]
	v_mfma_f32_16x16x32_bf16 v[86:89], v[178:181], v[216:219], v[86:89]
	v_mfma_f32_16x16x32_bf16 v[82:85], v[186:189], v[216:219], v[82:85]
	v_mfma_f32_16x16x32_bf16 v[70:73], v[178:181], v[224:227], v[70:73]
	v_mfma_f32_16x16x32_bf16 v[66:69], v[186:189], v[224:227], v[66:69]
	s_barrier
	s_setprio 0
	s_add_i32 s29, s29, s4
	v_lshl_add_u64 v[160:161], v[160:161], 0, s[24:25]
	s_mov_b32 m0, s29
	ds_read_b128 v[190:193], v143 offset:49152
	ds_read_b128 v[194:197], v143 offset:50176
	ds_read_b128 v[204:207], v143 offset:51200
	ds_read_b128 v[208:211], v143 offset:52224
	ds_read_b128 v[212:215], v143 offset:53248
	ds_read_b128 v[216:219], v143 offset:54272
	ds_read_b128 v[220:223], v143 offset:55296
	ds_read_b128 v[224:227], v143 offset:56320
	global_load_lds_dwordx4 v[160:161], off
	s_add_i32 m0, s29, 0x2000
	s_add_u32 s50, s50, 0x100080
	v_lshl_add_u64 v[160:161], v[170:171], 0, s[24:25]
	s_addc_u32 s51, s51, 0
	s_add_i32 s29, s37, s4
	global_load_lds_dwordx4 v[160:161], off
	s_mov_b32 m0, s29
	s_nop 0
	global_load_lds_dwordx4 v0, s[50:51]
	s_add_i32 m0, s29, 0x2000
	s_nop 0
	global_load_lds_dwordx4 v130, s[50:51]
	v_lshl_add_u64 v[160:161], v[172:173], 0, s[24:25]
	s_mov_b32 m0, s23
	s_nop 0
	global_load_lds_dwordx4 v[160:161], off
	v_lshl_add_u64 v[160:161], v[198:199], 0, s[24:25]
	s_mov_b32 m0, s28
	s_nop 0
	global_load_lds_dwordx4 v[160:161], off
	s_waitcnt vmcnt(8)
	s_waitcnt lgkmcnt(0)
	s_setprio 1
	s_barrier
	v_mfma_f32_16x16x32_bf16 v[62:65], v[144:147], v[190:193], v[62:65]
	v_mfma_f32_16x16x32_bf16 v[58:61], v[152:155], v[190:193], v[58:61]
	v_mfma_f32_16x16x32_bf16 v[46:49], v[144:147], v[204:207], v[46:49]
	v_mfma_f32_16x16x32_bf16 v[42:45], v[152:155], v[204:207], v[42:45]
	v_mfma_f32_16x16x32_bf16 v[30:33], v[144:147], v[212:215], v[30:33]
	v_mfma_f32_16x16x32_bf16 v[26:29], v[152:155], v[212:215], v[26:29]
	v_mfma_f32_16x16x32_bf16 v[14:17], v[144:147], v[220:223], v[14:17]
	v_mfma_f32_16x16x32_bf16 v[10:13], v[152:155], v[220:223], v[10:13]
	v_mfma_f32_16x16x32_bf16 v[62:65], v[148:151], v[194:197], v[62:65]
	v_mfma_f32_16x16x32_bf16 v[58:61], v[156:159], v[194:197], v[58:61]
	v_mfma_f32_16x16x32_bf16 v[46:49], v[148:151], v[208:211], v[46:49]
	v_mfma_f32_16x16x32_bf16 v[42:45], v[156:159], v[208:211], v[42:45]
	v_mfma_f32_16x16x32_bf16 v[30:33], v[148:151], v[216:219], v[30:33]
	v_mfma_f32_16x16x32_bf16 v[26:29], v[156:159], v[216:219], v[26:29]
	v_mfma_f32_16x16x32_bf16 v[14:17], v[148:151], v[224:227], v[14:17]
	v_mfma_f32_16x16x32_bf16 v[10:13], v[156:159], v[224:227], v[10:13]
	v_mfma_f32_16x16x32_bf16 v[54:57], v[174:177], v[190:193], v[54:57]
	v_mfma_f32_16x16x32_bf16 v[50:53], v[182:185], v[190:193], v[50:53]
	v_mfma_f32_16x16x32_bf16 v[38:41], v[174:177], v[204:207], v[38:41]
	v_mfma_f32_16x16x32_bf16 v[34:37], v[182:185], v[204:207], v[34:37]
	v_mfma_f32_16x16x32_bf16 v[22:25], v[174:177], v[212:215], v[22:25]
	v_mfma_f32_16x16x32_bf16 v[18:21], v[182:185], v[212:215], v[18:21]
	v_mfma_f32_16x16x32_bf16 v[6:9], v[174:177], v[220:223], v[6:9]
	v_mfma_f32_16x16x32_bf16 v[2:5], v[182:185], v[220:223], v[2:5]
	v_mfma_f32_16x16x32_bf16 v[54:57], v[178:181], v[194:197], v[54:57]
	v_mfma_f32_16x16x32_bf16 v[50:53], v[186:189], v[194:197], v[50:53]
	v_mfma_f32_16x16x32_bf16 v[38:41], v[178:181], v[208:211], v[38:41]
	v_mfma_f32_16x16x32_bf16 v[34:37], v[186:189], v[208:211], v[34:37]
	v_mfma_f32_16x16x32_bf16 v[22:25], v[178:181], v[216:219], v[22:25]
	v_mfma_f32_16x16x32_bf16 v[18:21], v[186:189], v[216:219], v[18:21]
	v_mfma_f32_16x16x32_bf16 v[6:9], v[178:181], v[224:227], v[6:9]
	v_mfma_f32_16x16x32_bf16 v[2:5], v[186:189], v[224:227], v[2:5]
	s_barrier
	s_setprio 0
	s_add_u32 s48, s48, 0x100
	s_addc_u32 s49, s49, 0
	s_add_u32 s56, s56, 0x100
	s_addc_u32 s57, s57, 0
	s_cmp_ge_i32 s72, s3
	s_mov_b32 s50, s72
	s_cbranch_scc0 .LBB7_1274
	s_mov_b32 s56, s61
	s_and_b64 vcc, exec, s[6:7]
	s_cbranch_vccz .LBB7_1277
